# GEMM unit transition: first two K-loop waits after an epilogue count past its stores (vmcnt 24) instead of draining them
# speedup vs baseline: 1.0101x; 1.0021x over previous
; #define PG8_STAGE(bufoff, gbase, voff) do { _Pragma("unroll") for (int _i = 0; _i < 2; ++_i) \
;         __builtin_amdgcn_global_load_lds((const unsigned*)((const char*)(gbase) + (voff)[_i]), (LAS unsigned*)(lds + (bufoff) + ldsw + _i * 8192), 16, 0, 0); } while (0)
; #define PG8_BAR __builtin_amdgcn_s_barrier()
; template <class Epi, class Sched, bool ALIGN_EPI = false, bool SP2 = false>
; __device__ __forceinline__ void gemm_phase(LAS unsigned char* lds, const Gemm g, const Sched& S, const Epi& E) {
;     ...
;     const int wid = __builtin_amdgcn_readfirstlane(tid >> 6), lane = tid & 63, wr = wid >> 2, wc = wid & 3, fr = lane & 15, fq = lane >> 4;
;     const int K = g.K, nt = K / BK;
;     unsigned voffA[2], voffB[2];
; #pragma unroll
;     for (int i = 0; i < 2; ++i) { int R, C; stage_rc(tid * 16 + i * 8192, R, C); const int Rb = Epi::PERM ? ((R & ~31) + perm32(R & 31)) : R;
;         voffA[i] = (unsigned)(R * K + C) * 2u; voffB[i] = (unsigned)(Rb * K + C) * 2u; }
;     const size_t kstep = (size_t)(BK * 2);
;     const size_t hstep = (size_t)HALF * K * 2;
;     const size_t tstep = 2 * hstep;
;     const unsigned ldsw = (unsigned)wid * 1024u;
;     const int aoff = lds_byte(wr * 64 + fr, fq * 8), boff = lds_byte(wc * 32 + fr, fq * 8);
;     ...
;     Unit cur, nxt; int ui = 0;
;     if (!S.next(0, cur)) return;
;     f32x4 acc[2][2][4][2];
; #pragma unroll
;     for (int a = 0; a < 2; ++a)
; #pragma unroll
;         for (int b = 0; b < 2; ++b)
; #pragma unroll
;             for (int m = 0; m < 4; ++m)
; #pragma unroll
;                 for (int n = 0; n < 2; ++n) acc[a][b][m][n] = (f32x4){0.f, 0.f, 0.f, 0.f};
;     bf16x8 At[4][2], B0[2][2], B1[2][2];
;     const char* cA = (const char*)g.A + (size_t)cur.pm * tstep; const char* cB = (const char*)g.Bt + (size_t)cur.pn * tstep;
;     S.a_ready(cur);
;     if constexpr (SP2) {
;         PG8_STAGE(PG8_SB(0, 0), cB, voffB); PG8_STAGE(PG8_SB(0, 1), cB + hstep, voffB); PG8_STAGE(PG8_SA(0, 0), cA, voffA); PG8_STAGE(PG8_SA(0, 1), cA + hstep, voffA);
;         if (wr == 1) PG8_BAR;
.LBB0_405:
	s_or_b64 exec, exec, s[24:25]
	v_readlane_b32 s4, v246, 56
	v_readlane_b32 s5, v246, 57
	s_mov_b32 s5, s77
	v_writelane_b32 v246, s4, 56
	v_mov_b32_e32 v10, v206
	s_waitcnt lgkmcnt(0)
	v_writelane_b32 v246, s5, 57
	v_readlane_b32 s4, v247, 62
	v_readlane_b32 s5, v247, 63
	s_barrier
	s_mov_b32 s101, 0
	s_nop 0
	v_cndmask_b32_e64 v0, 0, 1, s[4:5]
	v_cmp_ne_u32_e64 s[98:99], 1, v0
	s_andn2_b64 vcc, exec, s[4:5]
	v_readfirstlane_b32 s4, v10
	s_cbranch_vccnz .LBB0_469
	v_lshlrev_b32_e32 v0, 4, v10
	v_add_u32_e32 v1, 0x2000, v0
	v_ashrrev_i32_e32 v2, 31, v1
	v_lshrrev_b32_e32 v2, 22, v2
	v_add_u32_e32 v2, v1, v2
	v_ashrrev_i32_e32 v4, 10, v2
	v_mul_i32_i24_e32 v2, 0x400, v4
	v_sub_u32_e32 v1, v1, v2
	v_lshrrev_b32_e32 v2, 4, v1
	v_bitop3_b32 v1, v2, v1, 32 bitop3:0x6c
	v_ashrrev_i32_e32 v2, 31, v1
	v_readlane_b32 s10, v246, 56
	v_lshrrev_b32_e32 v2, 26, v2
	v_readlane_b32 s11, v246, 57
	v_add_u32_e32 v2, v1, v2
	v_lshlrev_b32_e32 v3, 3, v4
	s_lshl_b64 s[6:7], s[10:11], 21
	v_readlane_b32 s5, v247, 60
	v_ashrrev_i32_e32 v5, 6, v2
	v_and_b32_e32 v3, -16, v3
	s_add_u32 s64, s5, s6
	v_readlane_b32 s5, v247, 61
	v_add_u32_e32 v3, v5, v3
	s_addc_u32 s65, s5, s7
	v_and_b32_e32 v6, 3, v5
	s_mov_b32 s7, 0x1fffe0
	v_lshrrev_b32_e32 v7, 2, v3
	v_lshlrev_b32_e32 v8, 1, v3
	v_and_b32_e32 v2, 0xc0, v2
	v_and_or_b32 v6, v3, s7, v6
	v_and_b32_e32 v7, 4, v7
	v_and_b32_e32 v8, 24, v8
	v_sub_u32_e32 v1, v1, v2
	v_or3_b32 v7, v6, v7, v8
	v_lshlrev_b32_e32 v6, 5, v4
	v_ashrrev_i16_sdwa v1, v207, sext(v1) dst_sel:DWORD dst_unused:UNUSED_PAD src0_sel:DWORD src1_sel:BYTE_0
	v_and_b32_e32 v8, 32, v6
	v_bfe_i32 v6, v1, 0, 16
	v_add_lshl_u32 v1, v8, v6, 1
	v_lshl_add_u32 v144, v7, 11, v1
	v_lshl_add_u32 v146, v3, 11, v1
	v_bfe_i32 v1, v10, 27, 1
	v_lshrrev_b32_e32 v1, 22, v1
	v_add_u32_e32 v1, v0, v1
	v_and_b32_e32 v1, 0xfffffc00, v1
	v_sub_u32_e32 v0, v0, v1
	v_lshrrev_b32_e32 v1, 4, v0
	v_ashrrev_i32_e32 v2, 31, v10
	v_bitop3_b32 v0, v1, v0, 32 bitop3:0x6c
	v_lshrrev_b32_e32 v2, 26, v2
	v_ashrrev_i32_e32 v1, 31, v0
	v_add_u32_e32 v2, v10, v2
	v_lshrrev_b32_e32 v1, 26, v1
	v_ashrrev_i32_e32 v8, 6, v2
	v_add_u32_e32 v1, v0, v1
	v_lshlrev_b32_e32 v2, 3, v8
	v_ashrrev_i32_e32 v7, 6, v1
	v_and_b32_e32 v2, -16, v2
	v_add_u32_e32 v2, v7, v2
	v_and_b32_e32 v3, 3, v7
	v_lshrrev_b32_e32 v9, 2, v2
	v_lshlrev_b32_e32 v11, 1, v2
	v_and_b32_e32 v1, 0xc0, v1
	s_ashr_i32 s6, s4, 6
	v_and_or_b32 v3, v2, s7, v3
	v_and_b32_e32 v9, 4, v9
	v_and_b32_e32 v11, 24, v11
	v_sub_u32_e32 v0, v0, v1
	s_ashr_i32 s5, s4, 8
	s_lshl_b32 s70, s6, 10
	v_or3_b32 v3, v3, v9, v11
	v_lshlrev_b32_e32 v9, 5, v8
	v_ashrrev_i16_sdwa v0, v207, sext(v0) dst_sel:DWORD dst_unused:UNUSED_PAD src0_sel:DWORD src1_sel:BYTE_0
	v_readlane_b32 s8, v246, 22
	v_and_b32_e32 v11, 32, v9
	v_bfe_i32 v9, v0, 0, 16
	v_readlane_b32 s9, v246, 23
	s_add_u32 s36, s64, s8
	v_add_lshl_u32 v0, v11, v9, 1
	s_addc_u32 s37, s65, s9
	s_add_i32 s71, s70, 0
	v_lshl_add_u32 v148, v3, 11, v0
	s_add_i32 m0, s71, 0x10000
	v_lshl_add_u32 v150, v2, 11, v0
	global_load_lds_dwordx4 v148, s[36:37]
	s_add_i32 m0, s71, 0x12000
	s_add_u32 s8, s36, 0x40000
	global_load_lds_dwordx4 v144, s[36:37]
	s_addc_u32 s9, s37, 0
	s_add_i32 m0, s71, 0x14000
	s_add_i32 s76, s71, 0x2000
	global_load_lds_dwordx4 v148, s[8:9]
	s_add_i32 m0, s71, 0x16000
	s_add_i32 s92, s71, 0x4000
	global_load_lds_dwordx4 v144, s[8:9]
	v_readlane_b32 s8, v246, 28
	s_mov_b32 m0, s71
	v_readlane_b32 s9, v246, 29
	s_add_i32 s93, s71, 0x6000
	v_mov_b32_e32 v149, v153
	v_mov_b32_e32 v145, v153
	s_cmp_eq_u32 s5, 1
	v_lshl_add_u64 v[0:1], s[36:37], 0, v[148:149]
	global_load_lds_dwordx4 v150, s[8:9]
	s_mov_b32 m0, s76
	s_cselect_b64 s[46:47], -1, 0
	global_load_lds_dwordx4 v146, s[8:9]
	v_readlane_b32 s8, v246, 30
	s_mov_b32 m0, s92
	v_readlane_b32 s9, v246, 31
	s_cmp_lg_u32 s5, 1
	v_lshl_add_u64 v[2:3], s[36:37], 0, v[144:145]
	s_nop 2
	global_load_lds_dwordx4 v150, s[8:9]
	s_mov_b32 m0, s93
	s_nop 0
	global_load_lds_dwordx4 v146, s[8:9]
	s_cbranch_scc1 .LBB0_408
	s_barrier

; #define PG8_STAGE(bufoff, gbase, voff) do { _Pragma("unroll") for (int _i = 0; _i < 2; ++_i) \
;         __builtin_amdgcn_global_load_lds((const unsigned*)((const char*)(gbase) + (voff)[_i]), (LAS unsigned*)(lds + (bufoff) + ldsw + _i * 8192), 16, 0, 0); } while (0)
; #define PG8_LDA(dst, b, h) do { _Pragma("unroll") for (int m = 0; m < 4; ++m) _Pragma("unroll") for (int k = 0; k < 2; ++k) dst[m][k] = *(const LAS bf16x8*)(lds + PG8_SA(b, h) + aoff + m * 2048 + k * 1024); } while (0)
; #define PG8_LDB(dst, b, h) do { _Pragma("unroll") for (int n = 0; n < 2; ++n) _Pragma("unroll") for (int k = 0; k < 2; ++k) dst[n][k] = *(const LAS bf16x8*)(lds + PG8_SB(b, h) + boff + n * 2048 + k * 1024); } while (0)
; #define PG8_MMA(ai, bj, At, Bt) do { __builtin_amdgcn_s_setprio(1); _Pragma("unroll") for (int m = 0; m < 4; ++m) _Pragma("unroll") for (int n = 0; n < 2; ++n) _Pragma("unroll") for (int k = 0; k < 2; ++k) \
;         acc[ai][bj][m][n] = __builtin_amdgcn_mfma_f32_16x16x32_bf16(Bt[n][k], At[m][k], acc[ai][bj][m][n], 0, 0, 0); __builtin_amdgcn_s_setprio(0); } while (0)
; #define PG8_WAIT_V(n) asm volatile("s_waitcnt vmcnt(" #n ")" ::: "memory")
; #define PG8_WAIT_L(n) asm volatile("s_waitcnt lgkmcnt(" #n ")" ::: "memory")
; template <class Epi, class Sched, bool ALIGN_EPI = false, bool SP2 = false>
; __device__ __forceinline__ void gemm_phase(LAS unsigned char* lds, const Gemm g, const Sched& S, const Epi& E) {
;     ...
;         for (int t = 0; t < nt; t += 2) {
;             const bool last = (t == nt - 2);
;             const char* a1 = cA + (size_t)(t + 1) * kstep;
;             const char* a2 = last ? nA : cA + (size_t)(t + 2) * kstep; const char* b2 = last ? nB : cB + (size_t)(t + 2) * kstep;
;             const char* a3 = a2 + kstep; const char* b3 = b2 + kstep;
;             if (last && has_next) S.a_ready(nxt);
;             if constexpr (SP2) {
;             PG8_LDB(B0, 0, 0); PG8_LDB(B1, 0, 1); PG8_SCHED; PG8_LDA(At, 0, 0); PG8_STAGE(PG8_SA(1, 1), a1 + hstep, voffA);
;             PG8_WAIT_V(8); PG8_WAIT_L(0); PG8_BAR; PG8_MMA(0, 0, At, B0); PG8_MMA(0, 1, At, B1); PG8_BAR; PG8_SCHED;
;             PG8_LDA(At, 0, 1); PG8_STAGE(PG8_SB(0, 0), b2, voffB); PG8_STAGE(PG8_SB(0, 1), b2 + hstep, voffB); PG8_STAGE(PG8_SA(0, 0), a2, voffA);
;             PG8_WAIT_V(8); PG8_WAIT_L(0); PG8_BAR; PG8_MMA(1, 0, At, B0); PG8_MMA(1, 1, At, B1); PG8_BAR; PG8_SCHED;
.LBB0_418:
	s_add_u32 s13, s24, 0xfffc0080
	s_addc_u32 s14, s25, -1
	s_add_i32 s15, 0, 0x10000
	s_cmp_eq_u32 s12, 12
	s_cselect_b32 s39, s6, s14
	s_cselect_b32 s38, s7, s13
	s_cselect_b32 s37, s8, s11
	s_cselect_b32 s36, s9, s10
	s_add_i32 s13, 0, 0x14000
	v_add_u32_e32 v140, s15, v218
	v_add_u32_e32 v152, s13, v218
	ds_read_b128 v[128:131], v140
	ds_read_b128 v[132:135], v140 offset:1024
	ds_read_b128 v[136:139], v140 offset:2048
	ds_read_b128 v[140:143], v140 offset:3072
	ds_read_b128 v[166:169], v152
	ds_read_b128 v[170:173], v152 offset:1024
	ds_read_b128 v[174:177], v152 offset:2048
	ds_read_b128 v[178:181], v152 offset:3072
	v_lshl_add_u64 v[230:231], s[24:25], 0, v[162:163]
	s_add_i32 m0, s71, 0xc000
	ds_read_b128 v[182:185], v221
	ds_read_b128 v[186:189], v221 offset:1024
	ds_read_b128 v[190:193], v221 offset:2048
	ds_read_b128 v[194:197], v221 offset:3072
	ds_read_b128 v[198:201], v221 offset:4096
	ds_read_b128 v[202:205], v221 offset:5120
	ds_read_b128 v[222:225], v221 offset:6144
	ds_read_b128 v[226:229], v221 offset:7168
	global_load_lds_dwordx4 v[230:231], off
	v_lshl_add_u64 v[230:231], s[24:25], 0, v[164:165]
	s_add_i32 m0, s71, 0xe000
	s_nop 0
	global_load_lds_dwordx4 v[230:231], off
	s_waitcnt vmcnt(24)
	s_cmp_eq_u32 s101, 1
	s_cbranch_scc1 .Lrlx_1
	s_waitcnt vmcnt(8)
.Lrlx_1:
	s_waitcnt lgkmcnt(0)
	s_barrier
	s_setprio 1
	s_waitcnt lgkmcnt(0)
	v_mfma_f32_16x16x32_bf16 v[124:127], v[128:131], v[182:185], v[124:127]
	v_mfma_f32_16x16x32_bf16 v[120:123], v[136:139], v[182:185], v[120:123]
	v_mfma_f32_16x16x32_bf16 v[108:111], v[128:131], v[190:193], v[108:111]
	v_mfma_f32_16x16x32_bf16 v[104:107], v[136:139], v[190:193], v[104:107]
	v_mfma_f32_16x16x32_bf16 v[92:95], v[128:131], v[198:201], v[92:95]
	v_mfma_f32_16x16x32_bf16 v[88:91], v[136:139], v[198:201], v[88:91]
	v_mfma_f32_16x16x32_bf16 v[76:79], v[128:131], v[222:225], v[76:79]
	v_mfma_f32_16x16x32_bf16 v[72:75], v[136:139], v[222:225], v[72:75]
	v_mfma_f32_16x16x32_bf16 v[124:127], v[132:135], v[186:189], v[124:127]
	v_mfma_f32_16x16x32_bf16 v[120:123], v[140:143], v[186:189], v[120:123]
	v_mfma_f32_16x16x32_bf16 v[108:111], v[132:135], v[194:197], v[108:111]
	v_mfma_f32_16x16x32_bf16 v[104:107], v[140:143], v[194:197], v[104:107]
	v_mfma_f32_16x16x32_bf16 v[92:95], v[132:135], v[202:205], v[92:95]
	v_mfma_f32_16x16x32_bf16 v[88:91], v[140:143], v[202:205], v[88:91]
	v_mfma_f32_16x16x32_bf16 v[76:79], v[132:135], v[226:229], v[76:79]
	v_mfma_f32_16x16x32_bf16 v[72:75], v[140:143], v[226:229], v[72:75]
	s_setprio 0
	s_setprio 1
	v_mfma_f32_16x16x32_bf16 v[116:119], v[166:169], v[182:185], v[116:119]
	v_mfma_f32_16x16x32_bf16 v[112:115], v[174:177], v[182:185], v[112:115]
	v_mfma_f32_16x16x32_bf16 v[100:103], v[166:169], v[190:193], v[100:103]
	v_mfma_f32_16x16x32_bf16 v[96:99], v[174:177], v[190:193], v[96:99]
	v_mfma_f32_16x16x32_bf16 v[84:87], v[166:169], v[198:201], v[84:87]
	v_mfma_f32_16x16x32_bf16 v[80:83], v[174:177], v[198:201], v[80:83]
	v_mfma_f32_16x16x32_bf16 v[68:71], v[166:169], v[222:225], v[68:71]
	v_mfma_f32_16x16x32_bf16 v[64:67], v[174:177], v[222:225], v[64:67]
	v_mfma_f32_16x16x32_bf16 v[116:119], v[170:173], v[186:189], v[116:119]
	v_mfma_f32_16x16x32_bf16 v[112:115], v[178:181], v[186:189], v[112:115]
	v_mfma_f32_16x16x32_bf16 v[100:103], v[170:173], v[194:197], v[100:103]
	v_mfma_f32_16x16x32_bf16 v[96:99], v[178:181], v[194:197], v[96:99]
	v_mfma_f32_16x16x32_bf16 v[84:87], v[170:173], v[202:205], v[84:87]
	v_mfma_f32_16x16x32_bf16 v[80:83], v[178:181], v[202:205], v[80:83]
	v_mfma_f32_16x16x32_bf16 v[68:71], v[170:173], v[226:229], v[68:71]
	v_mfma_f32_16x16x32_bf16 v[64:67], v[178:181], v[226:229], v[64:67]
	s_setprio 0
	s_barrier
	s_add_i32 s14, s15, s70
	v_lshl_add_u64 v[230:231], s[36:37], 0, v[148:149]
	s_mov_b32 m0, s14
	ds_read_b128 v[182:185], v221 offset:16384
	ds_read_b128 v[186:189], v221 offset:17408
	ds_read_b128 v[190:193], v221 offset:18432
	ds_read_b128 v[194:197], v221 offset:19456
	ds_read_b128 v[198:201], v221 offset:20480
	ds_read_b128 v[202:205], v221 offset:21504
	ds_read_b128 v[222:225], v221 offset:22528
	ds_read_b128 v[226:229], v221 offset:23552
	global_load_lds_dwordx4 v[230:231], off
	s_add_i32 m0, s14, 0x2000
	s_add_u32 s14, s36, 0x40000
	v_lshl_add_u64 v[232:233], s[36:37], 0, v[144:145]
	s_addc_u32 s15, s37, 0
	s_add_i32 s13, s13, s70
	global_load_lds_dwordx4 v[232:233], off
	v_lshl_add_u64 v[234:235], s[14:15], 0, v[148:149]
	s_mov_b32 m0, s13
	v_lshl_add_u64 v[236:237], s[38:39], 0, v[146:147]
	global_load_lds_dwordx4 v[234:235], off
	v_lshl_add_u64 v[234:235], s[14:15], 0, v[144:145]
	s_add_i32 m0, s13, 0x2000
	s_nop 0
	global_load_lds_dwordx4 v[234:235], off
	v_lshl_add_u64 v[234:235], s[38:39], 0, v[150:151]
	s_mov_b32 m0, s71
	s_nop 0
	global_load_lds_dwordx4 v[234:235], off
	s_mov_b32 m0, s76
	s_nop 0
	global_load_lds_dwordx4 v[236:237], off
	s_waitcnt vmcnt(24)
	s_cmp_eq_u32 s101, 1
	s_cbranch_scc1 .Lrlx_2
	s_waitcnt vmcnt(8)
; #define PG8_STAGE(bufoff, gbase, voff) do { _Pragma("unroll") for (int _i = 0; _i < 2; ++_i) \
;         __builtin_amdgcn_global_load_lds((const unsigned*)((const char*)(gbase) + (voff)[_i]), (LAS unsigned*)(lds + (bufoff) + ldsw + _i * 8192), 16, 0, 0); } while (0)
; #define PG8_LDA(dst, b, h) do { _Pragma("unroll") for (int m = 0; m < 4; ++m) _Pragma("unroll") for (int k = 0; k < 2; ++k) dst[m][k] = *(const LAS bf16x8*)(lds + PG8_SA(b, h) + aoff + m * 2048 + k * 1024); } while (0)
; #define PG8_LDB(dst, b, h) do { _Pragma("unroll") for (int n = 0; n < 2; ++n) _Pragma("unroll") for (int k = 0; k < 2; ++k) dst[n][k] = *(const LAS bf16x8*)(lds + PG8_SB(b, h) + boff + n * 2048 + k * 1024); } while (0)
; #define PG8_MMA(ai, bj, At, Bt) do { __builtin_amdgcn_s_setprio(1); _Pragma("unroll") for (int m = 0; m < 4; ++m) _Pragma("unroll") for (int n = 0; n < 2; ++n) _Pragma("unroll") for (int k = 0; k < 2; ++k) \
;         acc[ai][bj][m][n] = __builtin_amdgcn_mfma_f32_16x16x32_bf16(Bt[n][k], At[m][k], acc[ai][bj][m][n], 0, 0, 0); __builtin_amdgcn_s_setprio(0); } while (0)
; #define PG8_WAIT_V(n) asm volatile("s_waitcnt vmcnt(" #n ")" ::: "memory")
; #define PG8_WAIT_L(n) asm volatile("s_waitcnt lgkmcnt(" #n ")" ::: "memory")
; #define PG8_BAR __builtin_amdgcn_s_barrier()
; #define PG8_SCHED __builtin_amdgcn_sched_barrier(0)
; template <class Epi, class Sched, bool ALIGN_EPI = false, bool SP2 = false>
; __device__ __forceinline__ void gemm_phase(LAS unsigned char* lds, const Gemm g, const Sched& S, const Epi& E) {
;     ...
;             PG8_WAIT_V(8); PG8_WAIT_L(0); PG8_BAR; PG8_MMA(1, 0, At, B0); PG8_MMA(1, 1, At, B1); PG8_BAR; PG8_SCHED;
;             PG8_LDB(B0, 1, 0); PG8_LDB(B1, 1, 1); PG8_SCHED; PG8_LDA(At, 1, 0); PG8_STAGE(PG8_SA(0, 1), a2 + hstep, voffA);
;             PG8_WAIT_V(8); PG8_WAIT_L(0); PG8_BAR; PG8_MMA(0, 0, At, B0); PG8_MMA(0, 1, At, B1); PG8_BAR; PG8_SCHED;
.Lrlx_2:
	s_mov_b32 s101, 0
	s_waitcnt lgkmcnt(0)
	s_barrier
	s_setprio 1
	s_waitcnt lgkmcnt(0)
	v_mfma_f32_16x16x32_bf16 v[60:63], v[128:131], v[182:185], v[60:63]
	v_mfma_f32_16x16x32_bf16 v[56:59], v[136:139], v[182:185], v[56:59]
	v_mfma_f32_16x16x32_bf16 v[44:47], v[128:131], v[190:193], v[44:47]
	v_mfma_f32_16x16x32_bf16 v[40:43], v[136:139], v[190:193], v[40:43]
	v_mfma_f32_16x16x32_bf16 v[28:31], v[128:131], v[198:201], v[28:31]
	v_mfma_f32_16x16x32_bf16 v[24:27], v[136:139], v[198:201], v[24:27]
	v_mfma_f32_16x16x32_bf16 v[12:15], v[128:131], v[222:225], v[12:15]
	v_mfma_f32_16x16x32_bf16 v[8:11], v[136:139], v[222:225], v[8:11]
	v_mfma_f32_16x16x32_bf16 v[60:63], v[132:135], v[186:189], v[60:63]
	v_mfma_f32_16x16x32_bf16 v[56:59], v[140:143], v[186:189], v[56:59]
	v_mfma_f32_16x16x32_bf16 v[44:47], v[132:135], v[194:197], v[44:47]
	v_mfma_f32_16x16x32_bf16 v[40:43], v[140:143], v[194:197], v[40:43]
	v_mfma_f32_16x16x32_bf16 v[28:31], v[132:135], v[202:205], v[28:31]
	v_mfma_f32_16x16x32_bf16 v[24:27], v[140:143], v[202:205], v[24:27]
	v_mfma_f32_16x16x32_bf16 v[12:15], v[132:135], v[226:229], v[12:15]
	v_mfma_f32_16x16x32_bf16 v[8:11], v[140:143], v[226:229], v[8:11]
	s_setprio 0
	s_setprio 1
	v_mfma_f32_16x16x32_bf16 v[52:55], v[166:169], v[182:185], v[52:55]
	v_mfma_f32_16x16x32_bf16 v[48:51], v[174:177], v[182:185], v[48:51]
	v_mfma_f32_16x16x32_bf16 v[36:39], v[166:169], v[190:193], v[36:39]
	v_mfma_f32_16x16x32_bf16 v[32:35], v[174:177], v[190:193], v[32:35]
	v_mfma_f32_16x16x32_bf16 v[20:23], v[166:169], v[198:201], v[20:23]
	v_mfma_f32_16x16x32_bf16 v[16:19], v[174:177], v[198:201], v[16:19]
	v_mfma_f32_16x16x32_bf16 v[4:7], v[166:169], v[222:225], v[4:7]
	v_mfma_f32_16x16x32_bf16 v[0:3], v[174:177], v[222:225], v[0:3]
	v_mfma_f32_16x16x32_bf16 v[52:55], v[170:173], v[186:189], v[52:55]
	v_mfma_f32_16x16x32_bf16 v[48:51], v[178:181], v[186:189], v[48:51]
	v_mfma_f32_16x16x32_bf16 v[36:39], v[170:173], v[194:197], v[36:39]
	v_mfma_f32_16x16x32_bf16 v[32:35], v[178:181], v[194:197], v[32:35]
	v_mfma_f32_16x16x32_bf16 v[20:23], v[170:173], v[202:205], v[20:23]
	v_mfma_f32_16x16x32_bf16 v[16:19], v[178:181], v[202:205], v[16:19]
	v_mfma_f32_16x16x32_bf16 v[4:7], v[170:173], v[226:229], v[4:7]
	v_mfma_f32_16x16x32_bf16 v[0:3], v[178:181], v[226:229], v[0:3]
	s_setprio 0
	s_barrier
	s_add_i32 s13, 0, 0x18000
	s_add_i32 s16, 0, 0x1c000
	v_add_u32_e32 v140, s13, v218
	v_add_u32_e32 v152, s16, v218
	ds_read_b128 v[128:131], v140
	ds_read_b128 v[132:135], v140 offset:1024
	ds_read_b128 v[136:139], v140 offset:2048
	ds_read_b128 v[140:143], v140 offset:3072
	ds_read_b128 v[166:169], v152
	ds_read_b128 v[170:173], v152 offset:1024
	ds_read_b128 v[174:177], v152 offset:2048
	ds_read_b128 v[178:181], v152 offset:3072
	s_add_u32 s14, s38, 0x40000
	s_addc_u32 s15, s39, 0
	s_mov_b32 m0, s92
	v_lshl_add_u64 v[238:239], s[14:15], 0, v[150:151]
	ds_read_b128 v[182:185], v221 offset:32768
	ds_read_b128 v[186:189], v221 offset:33792
	ds_read_b128 v[190:193], v221 offset:34816
	ds_read_b128 v[194:197], v221 offset:35840
	ds_read_b128 v[198:201], v221 offset:36864
	ds_read_b128 v[202:205], v221 offset:37888
	ds_read_b128 v[222:225], v221 offset:38912
	ds_read_b128 v[226:229], v221 offset:39936
	global_load_lds_dwordx4 v[238:239], off
	v_lshl_add_u64 v[238:239], s[14:15], 0, v[146:147]
	s_mov_b32 m0, s93
	s_nop 0
	global_load_lds_dwordx4 v[238:239], off
	s_waitcnt vmcnt(8)
	s_waitcnt lgkmcnt(0)
	s_barrier
	s_setprio 1
	s_waitcnt lgkmcnt(0)
	v_mfma_f32_16x16x32_bf16 v[124:127], v[128:131], v[182:185], v[124:127]
	v_mfma_f32_16x16x32_bf16 v[120:123], v[136:139], v[182:185], v[120:123]
	v_mfma_f32_16x16x32_bf16 v[108:111], v[128:131], v[190:193], v[108:111]
	v_mfma_f32_16x16x32_bf16 v[104:107], v[136:139], v[190:193], v[104:107]
	v_mfma_f32_16x16x32_bf16 v[92:95], v[128:131], v[198:201], v[92:95]
	v_mfma_f32_16x16x32_bf16 v[88:91], v[136:139], v[198:201], v[88:91]
	v_mfma_f32_16x16x32_bf16 v[76:79], v[128:131], v[222:225], v[76:79]
	v_mfma_f32_16x16x32_bf16 v[72:75], v[136:139], v[222:225], v[72:75]
	v_mfma_f32_16x16x32_bf16 v[124:127], v[132:135], v[186:189], v[124:127]
	v_mfma_f32_16x16x32_bf16 v[120:123], v[140:143], v[186:189], v[120:123]
	v_mfma_f32_16x16x32_bf16 v[108:111], v[132:135], v[194:197], v[108:111]
	v_mfma_f32_16x16x32_bf16 v[104:107], v[140:143], v[194:197], v[104:107]
	v_mfma_f32_16x16x32_bf16 v[92:95], v[132:135], v[202:205], v[92:95]
	v_mfma_f32_16x16x32_bf16 v[88:91], v[140:143], v[202:205], v[88:91]
	v_mfma_f32_16x16x32_bf16 v[76:79], v[132:135], v[226:229], v[76:79]
	v_mfma_f32_16x16x32_bf16 v[72:75], v[140:143], v[226:229], v[72:75]
	s_setprio 0
	s_setprio 1
	v_mfma_f32_16x16x32_bf16 v[116:119], v[166:169], v[182:185], v[116:119]
	v_mfma_f32_16x16x32_bf16 v[112:115], v[174:177], v[182:185], v[112:115]
	v_mfma_f32_16x16x32_bf16 v[100:103], v[166:169], v[190:193], v[100:103]
	v_mfma_f32_16x16x32_bf16 v[96:99], v[174:177], v[190:193], v[96:99]
	v_mfma_f32_16x16x32_bf16 v[84:87], v[166:169], v[198:201], v[84:87]
	v_mfma_f32_16x16x32_bf16 v[80:83], v[174:177], v[198:201], v[80:83]
	v_mfma_f32_16x16x32_bf16 v[68:71], v[166:169], v[222:225], v[68:71]
	v_mfma_f32_16x16x32_bf16 v[64:67], v[174:177], v[222:225], v[64:67]
	v_mfma_f32_16x16x32_bf16 v[116:119], v[170:173], v[186:189], v[116:119]
	v_mfma_f32_16x16x32_bf16 v[112:115], v[178:181], v[186:189], v[112:115]
	v_mfma_f32_16x16x32_bf16 v[100:103], v[170:173], v[194:197], v[100:103]
	v_mfma_f32_16x16x32_bf16 v[96:99], v[178:181], v[194:197], v[96:99]
	v_mfma_f32_16x16x32_bf16 v[84:87], v[170:173], v[202:205], v[84:87]
	v_mfma_f32_16x16x32_bf16 v[80:83], v[178:181], v[202:205], v[80:83]
	v_mfma_f32_16x16x32_bf16 v[68:71], v[170:173], v[226:229], v[68:71]
	v_mfma_f32_16x16x32_bf16 v[64:67], v[178:181], v[226:229], v[64:67]
	s_setprio 0
	s_barrier
; template <class Epi, class Sched, bool ALIGN_EPI = false, bool SP2 = false>
; __device__ __forceinline__ void gemm_phase(LAS unsigned char* lds, const Gemm g, const Sched& S, const Epi& E) {
;     ...
;             PG8_LDA(At, 1, 1); PG8_STAGE(PG8_SB(1, 0), b3, voffB); PG8_STAGE(PG8_SB(1, 1), b3 + hstep, voffB); PG8_STAGE(PG8_SA(1, 0), a3, voffA);
;             PG8_WAIT_V(8); PG8_WAIT_L(0); PG8_BAR; PG8_MMA(1, 0, At, B0); PG8_MMA(1, 1, At, B1); PG8_BAR; PG8_SCHED;
;             } else {
;             PG8_LDB(B0, 0, 0); PG8_SCHED; PG8_LDA(At, 0, 0); PG8_STAGE(PG8_SA(1, 1), a1 + hstep, voffA);
;             PG8_WAIT_L(8); PG8_BAR; PG8_WAIT_L(0); PG8_MMA(0, 0, At, B0); PG8_BAR; PG8_SCHED;
;             PG8_LDB(B1, 0, 1); PG8_STAGE(PG8_SB(0, 0), b2, voffB);
;             PG8_BAR; PG8_WAIT_L(0); PG8_MMA(0, 1, At, B1); PG8_BAR;
;             PG8_LDA(At, 0, 1); PG8_STAGE(PG8_SA(0, 0), a2, voffA);
;             PG8_BAR; PG8_WAIT_L(0); PG8_MMA(1, 0, At, B0); PG8_BAR; PG8_SCHED;
;             PG8_STAGE(PG8_SB(0, 1), b2 + hstep, voffB);
;             PG8_WAIT_V(6); PG8_BAR; PG8_MMA(1, 1, At, B1); PG8_BAR;
;             PG8_LDB(B0, 1, 0); PG8_SCHED; PG8_LDA(At, 1, 0); PG8_STAGE(PG8_SA(0, 1), a2 + hstep, voffA);
;             PG8_WAIT_L(8); PG8_BAR; PG8_WAIT_L(0); PG8_MMA(0, 0, At, B0); PG8_BAR; PG8_SCHED;
;             PG8_LDB(B1, 1, 1); PG8_STAGE(PG8_SB(1, 0), b3, voffB);
;             PG8_BAR; PG8_WAIT_L(0); PG8_MMA(0, 1, At, B1); PG8_BAR;
;             PG8_LDA(At, 1, 1); PG8_STAGE(PG8_SA(1, 0), a3, voffA);
;             PG8_BAR; PG8_WAIT_L(0); PG8_MMA(1, 0, At, B0); PG8_BAR; PG8_SCHED;
;             PG8_STAGE(PG8_SB(1, 1), b3 + hstep, voffB);
;             PG8_WAIT_V(6); PG8_BAR; PG8_MMA(1, 1, At, B1); PG8_BAR;
;             }
;         }
;         if constexpr (ALIGN_EPI) { if (wr == 0) PG8_BAR; }
; template <bool RD32>
; __device__ __forceinline__ void res_rows(const float* __restrict__ xold32, const bf16_t* __restrict__ xoldb, bf16_t* __restrict__ xb, float* __restrict__ ssq, const f32x4 (&acc)[2][2][4][2], int row0, int col0, int slot) {
;     ...
;     for (int bj = 0; bj < 2; ++bj) ld((size_t)row0 * D + col0 + bj * HALF, xo[0][bj][0], xo[0][bj][1]);
; #pragma unroll
;     for (int idx = 0; idx < 8; ++idx) {
;         const int ai = idx >> 2, m = idx & 3; const int r = row0 + ai * HALF + m * 16; const size_t off = (size_t)r * D + col0;
	s_add_i32 s13, s13, s70
	v_lshl_add_u64 v[230:231], v[230:231], 0, s[30:31]
	s_mov_b32 m0, s13
	ds_read_b128 v[182:185], v221 offset:49152
	ds_read_b128 v[186:189], v221 offset:50176
	ds_read_b128 v[190:193], v221 offset:51200
	ds_read_b128 v[194:197], v221 offset:52224
	ds_read_b128 v[198:201], v221 offset:53248
	ds_read_b128 v[202:205], v221 offset:54272
	ds_read_b128 v[222:225], v221 offset:55296
	ds_read_b128 v[226:229], v221 offset:56320
	global_load_lds_dwordx4 v[230:231], off
	s_add_i32 m0, s13, 0x2000
	s_add_u32 s14, s36, 0x40080
	v_lshl_add_u64 v[230:231], v[232:233], 0, s[30:31]
	s_addc_u32 s15, s37, 0
	s_add_i32 s13, s16, s70
	global_load_lds_dwordx4 v[230:231], off
	v_lshl_add_u64 v[230:231], s[14:15], 0, v[148:149]
	s_mov_b32 m0, s13
	s_nop 0
	global_load_lds_dwordx4 v[230:231], off
	v_lshl_add_u64 v[230:231], s[14:15], 0, v[144:145]
	s_add_i32 m0, s13, 0x2000
	s_nop 0
	global_load_lds_dwordx4 v[230:231], off
	v_lshl_add_u64 v[230:231], v[234:235], 0, s[30:31]
	s_mov_b32 m0, s96
	s_nop 0
	global_load_lds_dwordx4 v[230:231], off
	v_lshl_add_u64 v[230:231], v[236:237], 0, s[30:31]
	s_mov_b32 m0, s97
	s_nop 0
	global_load_lds_dwordx4 v[230:231], off
	s_waitcnt vmcnt(8)
	s_waitcnt lgkmcnt(0)
	s_barrier
	s_setprio 1
	s_waitcnt lgkmcnt(0)
	v_mfma_f32_16x16x32_bf16 v[60:63], v[128:131], v[182:185], v[60:63]
	v_mfma_f32_16x16x32_bf16 v[56:59], v[136:139], v[182:185], v[56:59]
	v_mfma_f32_16x16x32_bf16 v[44:47], v[128:131], v[190:193], v[44:47]
	v_mfma_f32_16x16x32_bf16 v[40:43], v[136:139], v[190:193], v[40:43]
	v_mfma_f32_16x16x32_bf16 v[28:31], v[128:131], v[198:201], v[28:31]
	v_mfma_f32_16x16x32_bf16 v[24:27], v[136:139], v[198:201], v[24:27]
	v_mfma_f32_16x16x32_bf16 v[12:15], v[128:131], v[222:225], v[12:15]
	v_mfma_f32_16x16x32_bf16 v[8:11], v[136:139], v[222:225], v[8:11]
	v_mfma_f32_16x16x32_bf16 v[60:63], v[132:135], v[186:189], v[60:63]
	v_mfma_f32_16x16x32_bf16 v[56:59], v[140:143], v[186:189], v[56:59]
	v_mfma_f32_16x16x32_bf16 v[44:47], v[132:135], v[194:197], v[44:47]
	v_mfma_f32_16x16x32_bf16 v[40:43], v[140:143], v[194:197], v[40:43]
	v_mfma_f32_16x16x32_bf16 v[28:31], v[132:135], v[202:205], v[28:31]
	v_mfma_f32_16x16x32_bf16 v[24:27], v[140:143], v[202:205], v[24:27]
	v_mfma_f32_16x16x32_bf16 v[12:15], v[132:135], v[226:229], v[12:15]
	v_mfma_f32_16x16x32_bf16 v[8:11], v[140:143], v[226:229], v[8:11]
	s_setprio 0
	s_setprio 1
	v_mfma_f32_16x16x32_bf16 v[52:55], v[166:169], v[182:185], v[52:55]
	v_mfma_f32_16x16x32_bf16 v[48:51], v[174:177], v[182:185], v[48:51]
	v_mfma_f32_16x16x32_bf16 v[36:39], v[166:169], v[190:193], v[36:39]
	v_mfma_f32_16x16x32_bf16 v[32:35], v[174:177], v[190:193], v[32:35]
	v_mfma_f32_16x16x32_bf16 v[20:23], v[166:169], v[198:201], v[20:23]
	v_mfma_f32_16x16x32_bf16 v[16:19], v[174:177], v[198:201], v[16:19]
	v_mfma_f32_16x16x32_bf16 v[4:7], v[166:169], v[222:225], v[4:7]
	v_mfma_f32_16x16x32_bf16 v[0:3], v[174:177], v[222:225], v[0:3]
	v_mfma_f32_16x16x32_bf16 v[52:55], v[170:173], v[186:189], v[52:55]
	v_mfma_f32_16x16x32_bf16 v[48:51], v[178:181], v[186:189], v[48:51]
	v_mfma_f32_16x16x32_bf16 v[36:39], v[170:173], v[194:197], v[36:39]
	v_mfma_f32_16x16x32_bf16 v[32:35], v[178:181], v[194:197], v[32:35]
	v_mfma_f32_16x16x32_bf16 v[20:23], v[170:173], v[202:205], v[20:23]
	v_mfma_f32_16x16x32_bf16 v[16:19], v[178:181], v[202:205], v[16:19]
	v_mfma_f32_16x16x32_bf16 v[4:7], v[170:173], v[226:229], v[4:7]
	v_mfma_f32_16x16x32_bf16 v[0:3], v[178:181], v[226:229], v[0:3]
	s_setprio 0
	s_barrier
	s_add_i32 s12, s12, 2
	s_add_u32 s24, s24, 0x100
	s_addc_u32 s25, s25, 0
	s_add_u32 s10, s10, 0x100
	s_addc_u32 s11, s11, 0
	s_cmp_gt_u32 s12, 13
	s_cbranch_scc0 .LBB0_418
	s_and_b64 vcc, exec, s[50:51]
	s_cbranch_vccz .LBB0_421
	s_barrier
.LBB0_421:
	s_mov_b32 s101, 1
	v_lshl_add_u32 v166, s5, 8, v217
	v_lshl_or_b32 v132, s4, 8, v219
	v_lshl_or_b32 v222, s4, 2, v220
	v_ashrrev_i32_e32 v167, 31, v166
	v_or_b32_e32 v223, s95, v222
	v_ashrrev_i32_e32 v133, 31, v132
	s_andn2_b64 vcc, exec, s[48:49]
	v_lshlrev_b64 v[174:175], 11, v[166:167]
	v_or_b32_e32 v172, 16, v166
	v_or_b32_e32 v170, 32, v166
	v_or_b32_e32 v168, 48, v166
	s_cbranch_vccnz .LBB0_436
	v_lshl_add_u64 v[128:129], s[58:59], 0, v[174:175]
	v_lshlrev_b64 v[134:135], 1, v[132:133]
	v_lshl_add_u64 v[136:137], v[128:129], 0, v[134:135]
	global_load_dwordx4 v[128:131], v[136:137], off
	v_ashrrev_i32_e32 v173, 31, v172
	v_ashrrev_i32_e32 v171, 31, v170
	s_mov_b64 s[4:5], 0x40000
	s_waitcnt vmcnt(0)
	v_lshlrev_b32_e32 v138, 16, v128
	v_and_b32_e32 v139, 0xffff0000, v128
	v_lshlrev_b32_e32 v140, 16, v129
	v_and_b32_e32 v141, 0xffff0000, v129
	v_lshlrev_b32_e32 v142, 16, v130
	v_and_b32_e32 v143, 0xffff0000, v130
	v_lshlrev_b32_e32 v176, 16, v131
	v_and_b32_e32 v177, 0xffff0000, v131
	global_load_dwordx4 v[128:131], v[136:137], off offset:256
	v_pk_add_f32 v[140:141], v[126:127], v[140:141]
	v_pk_add_f32 v[138:139], v[124:125], v[138:139]
	v_pk_add_f32 v[176:177], v[122:123], v[176:177]
	v_pk_add_f32 v[142:143], v[120:121], v[142:143]
	s_waitcnt vmcnt(0)
	v_lshlrev_b32_e32 v178, 16, v128
	v_and_b32_e32 v179, 0xffff0000, v128
	v_lshlrev_b32_e32 v180, 16, v129
	v_and_b32_e32 v181, 0xffff0000, v129
	v_lshlrev_b32_e32 v182, 16, v130
	v_and_b32_e32 v183, 0xffff0000, v130
	v_lshlrev_b32_e32 v202, 16, v131
	v_and_b32_e32 v203, 0xffff0000, v131
	v_lshl_add_u64 v[130:131], s[58:59], 0, v[134:135]
	v_lshlrev_b64 v[128:129], 11, v[172:173]
	v_lshl_add_u64 v[184:185], v[130:131], 0, v[128:129]
	global_load_dwordx4 v[134:137], v[184:185], off
	v_lshl_add_u64 v[128:129], v[130:131], 0, v[174:175]
	s_waitcnt vmcnt(0)
; __device__ __forceinline__ unsigned cvt_pk_bf16(float lo, float hi) { unsigned r; asm volatile("v_cvt_pk_bf16_f32 %0, %1, %2" : "=v"(r) : "v"(lo), "v"(hi)); return r; }
; template <bool RD32>
; __device__ __forceinline__ void res_rows(const float* __restrict__ xold32, const bf16_t* __restrict__ xoldb, bf16_t* __restrict__ xb, float* __restrict__ ssq, const f32x4 (&acc)[2][2][4][2], int row0, int col0, int slot) {
;     ...
;     for (int bj = 0; bj < 2; ++bj) ld((size_t)row0 * D + col0 + bj * HALF, xo[0][bj][0], xo[0][bj][1]);
; #pragma unroll
;     for (int idx = 0; idx < 8; ++idx) {
;         const int ai = idx >> 2, m = idx & 3; const int r = row0 + ai * HALF + m * 16; const size_t off = (size_t)r * D + col0;
;         if (idx < 7) { const int ai2 = (idx + 1) >> 2, m2 = (idx + 1) & 3; const size_t off2 = (size_t)(row0 + ai2 * HALF + m2 * 16) * D + col0;
; #pragma unroll
;             for (int bj = 0; bj < 2; ++bj) ld(off2 + bj * HALF, xo[(idx + 1) & 1][bj][0], xo[(idx + 1) & 1][bj][1]); }
;         float ss = 0.f;
; #pragma unroll
;         for (int bj = 0; bj < 2; ++bj) { const f32x4 x0 = xo[idx & 1][bj][0] + acc[ai][bj][m][0], x1 = xo[idx & 1][bj][1] + acc[ai][bj][m][1];
;             u32x4 w; w.x = cvt_pk_bf16(x0[0], x0[1]); w.y = cvt_pk_bf16(x0[2], x0[3]); w.z = cvt_pk_bf16(x1[0], x1[1]); w.w = cvt_pk_bf16(x1[2], x1[3]);
;             *(u32x4*)(xb + off + bj * HALF) = w;
;             ss += ((x0[0] * x0[0] + x0[1] * x0[1]) + (x0[2] * x0[2] + x0[3] * x0[3])) + ((x1[0] * x1[0] + x1[1] * x1[1]) + (x1[2] * x1[2] + x1[3] * x1[3])); }
;         ss += __shfl_xor(ss, 16); ss += __shfl_xor(ss, 32);
;         ssv[idx] = ss;
;     }
	v_lshlrev_b32_e32 v186, 16, v134
	v_and_b32_e32 v187, 0xffff0000, v134
	v_lshlrev_b32_e32 v190, 16, v135
	v_and_b32_e32 v191, 0xffff0000, v135
	v_lshlrev_b32_e32 v188, 16, v136
	v_and_b32_e32 v189, 0xffff0000, v136
	v_lshlrev_b32_e32 v192, 16, v137
	v_and_b32_e32 v193, 0xffff0000, v137
	global_load_dwordx4 v[134:137], v[184:185], off offset:256
	v_pk_add_f32 v[190:191], v[110:111], v[190:191]
	v_pk_add_f32 v[192:193], v[106:107], v[192:193]
	s_waitcnt vmcnt(0)
	v_lshlrev_b32_e32 v194, 16, v134
	v_and_b32_e32 v195, 0xffff0000, v134
	v_lshlrev_b32_e32 v198, 16, v135
	v_and_b32_e32 v199, 0xffff0000, v135
	v_cvt_pk_bf16_f32 v134, v138, v139
	v_cvt_pk_bf16_f32 v135, v140, v141
	v_lshlrev_b32_e32 v196, 16, v136
	v_and_b32_e32 v197, 0xffff0000, v136
	v_lshlrev_b32_e32 v200, 16, v137
	v_and_b32_e32 v201, 0xffff0000, v137
	v_cvt_pk_bf16_f32 v136, v142, v143
	v_cvt_pk_bf16_f32 v137, v176, v177
	global_store_dwordx4 v[128:129], v[134:137], off
	v_pk_add_f32 v[196:197], v[96:97], v[196:197]
	s_nop 0
	v_mul_f32_e32 v134, v139, v139
	v_mul_f32_e32 v135, v141, v141
	v_fmac_f32_e32 v134, v138, v138
	v_fmac_f32_e32 v135, v140, v140
	v_add_f32_e32 v134, v134, v135
	v_mul_f32_e32 v135, v143, v143
	v_mul_f32_e32 v136, v177, v177
	v_fmac_f32_e32 v135, v142, v142
	v_fmac_f32_e32 v136, v176, v176
	v_add_f32_e32 v135, v135, v136
	v_add_f32_e32 v152, v134, v135
	v_pk_add_f32 v[138:139], v[118:119], v[180:181]
	v_pk_add_f32 v[140:141], v[116:117], v[178:179]
	v_pk_add_f32 v[142:143], v[114:115], v[202:203]
	v_cvt_pk_bf16_f32 v134, v140, v141
	v_cvt_pk_bf16_f32 v135, v138, v139
	v_pk_add_f32 v[176:177], v[112:113], v[182:183]
	s_nop 0
	v_cvt_pk_bf16_f32 v136, v176, v177
	v_cvt_pk_bf16_f32 v137, v142, v143
	global_store_dwordx4 v[128:129], v[134:137], off offset:256
	s_nop 1
	v_mul_f32_e32 v134, v141, v141
	v_mul_f32_e32 v135, v139, v139
	v_fmac_f32_e32 v134, v140, v140
	v_fmac_f32_e32 v135, v138, v138
	v_add_f32_e32 v134, v134, v135
	v_mul_f32_e32 v135, v177, v177
	v_mul_f32_e32 v136, v143, v143
	v_fmac_f32_e32 v135, v176, v176
	v_fmac_f32_e32 v136, v142, v142
	v_add_f32_e32 v135, v135, v136
	v_and_b32_e32 v136, 64, v209
	v_add_f32_e32 v134, v134, v135
	v_xor_b32_e32 v135, 16, v209
	v_add_u32_e32 v136, 64, v136
	v_cmp_lt_i32_e32 vcc, v135, v136
	v_add_f32_e32 v134, v152, v134
	s_nop 0
	v_cndmask_b32_e32 v135, v209, v135, vcc
	v_lshlrev_b32_e32 v152, 2, v135
	ds_bpermute_b32 v135, v152, v134
	s_waitcnt lgkmcnt(0)
	v_add_f32_e32 v173, v134, v135
	v_xor_b32_e32 v134, 32, v209
	v_cmp_lt_i32_e32 vcc, v134, v136
	s_nop 1
	v_cndmask_b32_e32 v134, v209, v134, vcc
	v_lshlrev_b32_e32 v225, 2, v134
	v_lshlrev_b64 v[134:135], 11, v[170:171]
	v_lshl_add_u64 v[134:135], v[130:131], 0, v[134:135]
	global_load_dwordx4 v[136:139], v[134:135], off
	global_load_dwordx4 v[202:205], v[134:135], off offset:256
	v_mul_f32_e32 v171, v191, v191
	v_fmac_f32_e32 v171, v190, v190
	ds_bpermute_b32 v224, v225, v173
	s_waitcnt vmcnt(1)
	v_lshlrev_b32_e32 v176, 16, v138
	v_and_b32_e32 v177, 0xffff0000, v138
	v_lshlrev_b32_e32 v180, 16, v139
	v_and_b32_e32 v181, 0xffff0000, v139
	s_waitcnt vmcnt(0)
	v_lshlrev_b32_e32 v138, 16, v202
	v_and_b32_e32 v139, 0xffff0000, v202
	v_lshlrev_b32_e32 v142, 16, v203
	v_and_b32_e32 v143, 0xffff0000, v203
	v_pk_add_f32 v[202:203], v[108:109], v[186:187]
	v_lshlrev_b32_e32 v178, 16, v136
	v_mul_f32_e32 v169, v203, v203
	v_and_b32_e32 v179, 0xffff0000, v136
	v_lshlrev_b32_e32 v182, 16, v137
	v_and_b32_e32 v183, 0xffff0000, v137
	v_lshlrev_b32_e32 v136, 16, v204
	v_and_b32_e32 v137, 0xffff0000, v204
	v_lshlrev_b32_e32 v140, 16, v205
	v_and_b32_e32 v141, 0xffff0000, v205
	v_pk_add_f32 v[204:205], v[104:105], v[188:189]
	v_cvt_pk_bf16_f32 v186, v202, v203
	v_fmac_f32_e32 v169, v202, v202
	v_cvt_pk_bf16_f32 v187, v190, v191
	v_cvt_pk_bf16_f32 v188, v204, v205
	v_cvt_pk_bf16_f32 v189, v192, v193
	global_store_dwordx4 v[184:185], v[186:189], off
	v_add_f32_e32 v169, v169, v171
	v_mul_f32_e32 v171, v205, v205
	v_mul_f32_e32 v186, v193, v193
	v_fmac_f32_e32 v171, v204, v204
	v_fmac_f32_e32 v186, v192, v192
	v_add_f32_e32 v171, v171, v186
	v_pk_add_f32 v[190:191], v[102:103], v[198:199]
	v_pk_add_f32 v[192:193], v[100:101], v[194:195]
	v_add_f32_e32 v169, v169, v171
	v_pk_add_f32 v[194:195], v[98:99], v[200:201]
	v_cvt_pk_bf16_f32 v186, v192, v193
	v_cvt_pk_bf16_f32 v187, v190, v191
	v_cvt_pk_bf16_f32 v188, v196, v197
	v_mul_f32_e32 v171, v193, v193
	v_cvt_pk_bf16_f32 v189, v194, v195
	global_store_dwordx4 v[184:185], v[186:189], off offset:256
	v_mul_f32_e32 v184, v191, v191
	v_fmac_f32_e32 v171, v192, v192
	v_fmac_f32_e32 v184, v190, v190
	v_add_f32_e32 v171, v171, v184
	v_mul_f32_e32 v184, v197, v197
	v_mul_f32_e32 v185, v195, v195
	v_fmac_f32_e32 v184, v196, v196
	v_fmac_f32_e32 v185, v194, v194
	v_add_f32_e32 v184, v184, v185
	v_add_f32_e32 v171, v171, v184
	v_add_f32_e32 v169, v169, v171
	ds_bpermute_b32 v171, v152, v169
	v_pk_add_f32 v[182:183], v[94:95], v[182:183]
	v_pk_add_f32 v[194:195], v[92:93], v[178:179]
	v_pk_add_f32 v[180:181], v[90:91], v[180:181]
	v_pk_add_f32 v[142:143], v[86:87], v[142:143]
	s_waitcnt lgkmcnt(0)
	v_add_f32_e32 v171, v169, v171
	v_ashrrev_i32_e32 v169, 31, v168
	v_lshlrev_b64 v[184:185], 11, v[168:169]
	v_lshl_add_u64 v[130:131], v[130:131], 0, v[184:185]
	global_load_dwordx4 v[184:187], v[130:131], off
	global_load_dwordx4 v[202:205], v[130:131], off offset:256
	v_mul_f32_e32 v169, v195, v195
	v_fmac_f32_e32 v169, v194, v194
	v_pk_add_f32 v[140:141], v[82:83], v[140:141]
	ds_bpermute_b32 v226, v225, v171
	s_waitcnt vmcnt(1)
	v_lshlrev_b32_e32 v192, 16, v186
	v_and_b32_e32 v193, 0xffff0000, v186
	v_lshlrev_b32_e32 v198, 16, v187
	v_and_b32_e32 v199, 0xffff0000, v187
	s_waitcnt vmcnt(0)
; __device__ __forceinline__ unsigned cvt_pk_bf16(float lo, float hi) { unsigned r; asm volatile("v_cvt_pk_bf16_f32 %0, %1, %2" : "=v"(r) : "v"(lo), "v"(hi)); return r; }
; template <bool RD32>
; __device__ __forceinline__ void res_rows(const float* __restrict__ xold32, const bf16_t* __restrict__ xoldb, bf16_t* __restrict__ xb, float* __restrict__ ssq, const f32x4 (&acc)[2][2][4][2], int row0, int col0, int slot) {
;     ...
;     for (int bj = 0; bj < 2; ++bj) ld((size_t)row0 * D + col0 + bj * HALF, xo[0][bj][0], xo[0][bj][1]);
; #pragma unroll
;     for (int idx = 0; idx < 8; ++idx) {
;         const int ai = idx >> 2, m = idx & 3; const int r = row0 + ai * HALF + m * 16; const size_t off = (size_t)r * D + col0;
;         if (idx < 7) { const int ai2 = (idx + 1) >> 2, m2 = (idx + 1) & 3; const size_t off2 = (size_t)(row0 + ai2 * HALF + m2 * 16) * D + col0;
; #pragma unroll
;             for (int bj = 0; bj < 2; ++bj) ld(off2 + bj * HALF, xo[(idx + 1) & 1][bj][0], xo[(idx + 1) & 1][bj][1]); }
;         float ss = 0.f;
; #pragma unroll
;         for (int bj = 0; bj < 2; ++bj) { const f32x4 x0 = xo[idx & 1][bj][0] + acc[ai][bj][m][0], x1 = xo[idx & 1][bj][1] + acc[ai][bj][m][1];
;             u32x4 w; w.x = cvt_pk_bf16(x0[0], x0[1]); w.y = cvt_pk_bf16(x0[2], x0[3]); w.z = cvt_pk_bf16(x1[0], x1[1]); w.w = cvt_pk_bf16(x1[2], x1[3]);
;             *(u32x4*)(xb + off + bj * HALF) = w;
;             ss += ((x0[0] * x0[0] + x0[1] * x0[1]) + (x0[2] * x0[2] + x0[3] * x0[3])) + ((x1[0] * x1[0] + x1[1] * x1[1]) + (x1[2] * x1[2] + x1[3] * x1[3])); }
;         ss += __shfl_xor(ss, 16); ss += __shfl_xor(ss, 32);
;         ssv[idx] = ss;
;     }
	v_lshlrev_b32_e32 v186, 16, v202
	v_and_b32_e32 v187, 0xffff0000, v202
	v_lshlrev_b32_e32 v190, 16, v203
	v_and_b32_e32 v191, 0xffff0000, v203
	v_pk_add_f32 v[202:203], v[88:89], v[176:177]
	v_cvt_pk_bf16_f32 v176, v194, v195
	v_cvt_pk_bf16_f32 v177, v182, v183
	v_lshlrev_b32_e32 v196, 16, v184
	v_cvt_pk_bf16_f32 v178, v202, v203
	v_cvt_pk_bf16_f32 v179, v180, v181
	global_store_dwordx4 v[134:135], v[176:179], off
	v_and_b32_e32 v197, 0xffff0000, v184
	v_lshlrev_b32_e32 v200, 16, v185
	v_mul_f32_e32 v176, v183, v183
	v_fmac_f32_e32 v176, v182, v182
	v_add_f32_e32 v169, v169, v176
	v_mul_f32_e32 v176, v203, v203
	v_mul_f32_e32 v177, v181, v181
	v_fmac_f32_e32 v176, v202, v202
	v_fmac_f32_e32 v177, v180, v180
	v_add_f32_e32 v176, v176, v177
	v_add_f32_e32 v169, v169, v176
	v_pk_add_f32 v[176:177], v[84:85], v[138:139]
	v_pk_add_f32 v[178:179], v[80:81], v[136:137]
	v_cvt_pk_bf16_f32 v136, v176, v177
	v_cvt_pk_bf16_f32 v137, v142, v143
	v_and_b32_e32 v201, 0xffff0000, v185
	v_cvt_pk_bf16_f32 v138, v178, v179
	v_cvt_pk_bf16_f32 v139, v140, v141
	global_store_dwordx4 v[134:135], v[136:139], off offset:256
	v_mul_f32_e32 v134, v177, v177
	v_mul_f32_e32 v135, v143, v143
	v_fmac_f32_e32 v134, v176, v176
	v_fmac_f32_e32 v135, v142, v142
	v_add_f32_e32 v134, v134, v135
	v_mul_f32_e32 v135, v179, v179
	v_mul_f32_e32 v136, v141, v141
	v_fmac_f32_e32 v135, v178, v178
	v_fmac_f32_e32 v136, v140, v140
	v_add_f32_e32 v135, v135, v136
	v_add_f32_e32 v134, v134, v135
	v_add_f32_e32 v134, v169, v134
	ds_bpermute_b32 v135, v152, v134
	v_lshlrev_b32_e32 v184, 16, v204
	v_and_b32_e32 v185, 0xffff0000, v204
	v_lshlrev_b32_e32 v188, 16, v205
	v_and_b32_e32 v189, 0xffff0000, v205
	s_waitcnt lgkmcnt(0)
	v_add_f32_e32 v169, v134, v135
	v_lshl_add_u64 v[134:135], v[128:129], 0, s[4:5]
	s_mov_b32 s4, 0x40000
	v_add_co_u32_e32 v136, vcc, s4, v128
	global_load_dwordx4 v[202:205], v[134:135], off offset:256
	s_nop 0
	v_addc_co_u32_e32 v137, vcc, 0, v129, vcc
	global_load_dwordx4 v[138:141], v[136:137], off
	v_pk_add_f32 v[192:193], v[72:73], v[192:193]
	v_pk_add_f32 v[200:201], v[78:79], v[200:201]
	v_pk_add_f32 v[190:191], v[70:71], v[190:191]
	v_pk_add_f32 v[188:189], v[66:67], v[188:189]
	s_mov_b64 s[4:5], 0x48000
	ds_bpermute_b32 v227, v225, v169
	s_waitcnt vmcnt(1)
	v_lshlrev_b32_e32 v176, 16, v203
	v_and_b32_e32 v177, 0xffff0000, v203
	v_lshlrev_b32_e32 v142, 16, v205
	s_waitcnt vmcnt(0)
	v_lshlrev_b32_e32 v180, 16, v138
	v_and_b32_e32 v181, 0xffff0000, v138
	v_lshlrev_b32_e32 v194, 16, v139
	v_and_b32_e32 v195, 0xffff0000, v139
	v_lshlrev_b32_e32 v178, 16, v140
	v_and_b32_e32 v179, 0xffff0000, v140
	v_lshlrev_b32_e32 v182, 16, v141
	v_and_b32_e32 v183, 0xffff0000, v141
	v_lshlrev_b32_e32 v140, 16, v202
	v_and_b32_e32 v141, 0xffff0000, v202
	v_lshlrev_b32_e32 v138, 16, v204
	v_and_b32_e32 v139, 0xffff0000, v204
	v_and_b32_e32 v143, 0xffff0000, v205
	v_pk_add_f32 v[202:203], v[76:77], v[196:197]
	v_pk_add_f32 v[204:205], v[74:75], v[198:199]
	v_cvt_pk_bf16_f32 v196, v202, v203
	v_cvt_pk_bf16_f32 v197, v200, v201
	v_cvt_pk_bf16_f32 v198, v192, v193
	v_mul_f32_e32 v193, v193, v193
	v_cvt_pk_bf16_f32 v199, v204, v205
	global_store_dwordx4 v[130:131], v[196:199], off
	v_fmac_f32_e32 v193, v192, v192
	v_mul_f32_e32 v192, v205, v205
	v_mul_f32_e32 v196, v203, v203
	v_mul_f32_e32 v197, v201, v201
	v_fmac_f32_e32 v196, v202, v202
	v_fmac_f32_e32 v197, v200, v200
	v_fmac_f32_e32 v192, v204, v204
	v_add_f32_e32 v196, v196, v197
	v_add_f32_e32 v192, v193, v192
	v_add_f32_e32 v198, v196, v192
	v_pk_add_f32 v[192:193], v[68:69], v[186:187]
	v_pk_add_f32 v[196:197], v[64:65], v[184:185]
	v_cvt_pk_bf16_f32 v184, v192, v193
	v_cvt_pk_bf16_f32 v185, v190, v191
	v_pk_add_f32 v[182:183], v[58:59], v[182:183]
	v_cvt_pk_bf16_f32 v186, v196, v197
	v_cvt_pk_bf16_f32 v187, v188, v189
	global_store_dwordx4 v[130:131], v[184:187], off offset:256
	v_mul_f32_e32 v130, v193, v193
	v_mul_f32_e32 v131, v191, v191
	v_fmac_f32_e32 v130, v192, v192
	v_fmac_f32_e32 v131, v190, v190
	v_add_f32_e32 v130, v130, v131
	v_mul_f32_e32 v131, v197, v197
	v_mul_f32_e32 v184, v189, v189
	v_fmac_f32_e32 v131, v196, v196
	v_fmac_f32_e32 v184, v188, v188
	v_add_f32_e32 v131, v131, v184
	v_add_f32_e32 v130, v130, v131
	v_add_f32_e32 v130, v198, v130
	ds_bpermute_b32 v131, v152, v130
	v_pk_add_f32 v[184:185], v[62:63], v[194:195]
	v_pk_add_f32 v[194:195], v[60:61], v[180:181]
	v_pk_add_f32 v[176:177], v[54:55], v[176:177]
	v_pk_add_f32 v[140:141], v[52:53], v[140:141]
	s_waitcnt lgkmcnt(0)
	v_add_f32_e32 v228, v130, v131
	v_lshl_add_u64 v[130:131], v[128:129], 0, s[4:5]
	s_mov_b32 s4, 0x48000
	v_add_co_u32_e32 v186, vcc, s4, v128
	global_load_dwordx4 v[230:233], v[130:131], off offset:256
	s_nop 0
	v_addc_co_u32_e32 v187, vcc, 0, v129, vcc
	global_load_dwordx4 v[188:191], v[186:187], off
	v_pk_add_f32 v[142:143], v[50:51], v[142:143]
	s_mov_b64 s[4:5], 0x50000
	ds_bpermute_b32 v229, v225, v228
	s_waitcnt vmcnt(1)
	v_lshlrev_b32_e32 v196, 16, v231
	v_and_b32_e32 v197, 0xffff0000, v231
	v_lshlrev_b32_e32 v192, 16, v233
	s_waitcnt vmcnt(0)
; __device__ __forceinline__ unsigned cvt_pk_bf16(float lo, float hi) { unsigned r; asm volatile("v_cvt_pk_bf16_f32 %0, %1, %2" : "=v"(r) : "v"(lo), "v"(hi)); return r; }
; template <bool RD32>
; __device__ __forceinline__ void res_rows(const float* __restrict__ xold32, const bf16_t* __restrict__ xoldb, bf16_t* __restrict__ xb, float* __restrict__ ssq, const f32x4 (&acc)[2][2][4][2], int row0, int col0, int slot) {
;     ...
;     for (int idx = 0; idx < 8; ++idx) {
;         const int ai = idx >> 2, m = idx & 3; const int r = row0 + ai * HALF + m * 16; const size_t off = (size_t)r * D + col0;
;         if (idx < 7) { const int ai2 = (idx + 1) >> 2, m2 = (idx + 1) & 3; const size_t off2 = (size_t)(row0 + ai2 * HALF + m2 * 16) * D + col0;
; #pragma unroll
;             for (int bj = 0; bj < 2; ++bj) ld(off2 + bj * HALF, xo[(idx + 1) & 1][bj][0], xo[(idx + 1) & 1][bj][1]); }
;         float ss = 0.f;
; #pragma unroll
;         for (int bj = 0; bj < 2; ++bj) { const f32x4 x0 = xo[idx & 1][bj][0] + acc[ai][bj][m][0], x1 = xo[idx & 1][bj][1] + acc[ai][bj][m][1];
;             u32x4 w; w.x = cvt_pk_bf16(x0[0], x0[1]); w.y = cvt_pk_bf16(x0[2], x0[3]); w.z = cvt_pk_bf16(x1[0], x1[1]); w.w = cvt_pk_bf16(x1[2], x1[3]);
;             *(u32x4*)(xb + off + bj * HALF) = w;
;             ss += ((x0[0] * x0[0] + x0[1] * x0[1]) + (x0[2] * x0[2] + x0[3] * x0[3])) + ((x1[0] * x1[0] + x1[1] * x1[1]) + (x1[2] * x1[2] + x1[3] * x1[3])); }
;         ss += __shfl_xor(ss, 16); ss += __shfl_xor(ss, 32);
;         ssv[idx] = ss;
;     }
	v_lshlrev_b32_e32 v198, 16, v190
	v_and_b32_e32 v199, 0xffff0000, v190
	v_lshlrev_b32_e32 v202, 16, v191
	v_and_b32_e32 v203, 0xffff0000, v191
	v_lshlrev_b32_e32 v190, 16, v230
	v_and_b32_e32 v191, 0xffff0000, v230
	v_pk_add_f32 v[230:231], v[56:57], v[178:179]
	v_cvt_pk_bf16_f32 v178, v194, v195
	v_cvt_pk_bf16_f32 v179, v184, v185
	v_lshlrev_b32_e32 v200, 16, v188
	v_cvt_pk_bf16_f32 v180, v230, v231
	v_cvt_pk_bf16_f32 v181, v182, v183
	global_store_dwordx4 v[136:137], v[178:181], off
	v_mul_f32_e32 v136, v195, v195
	v_mul_f32_e32 v137, v185, v185
	v_fmac_f32_e32 v136, v194, v194
	v_fmac_f32_e32 v137, v184, v184
	v_add_f32_e32 v136, v136, v137
	v_mul_f32_e32 v137, v231, v231
	v_mul_f32_e32 v178, v183, v183
	v_fmac_f32_e32 v137, v230, v230
	v_fmac_f32_e32 v178, v182, v182
	v_add_f32_e32 v137, v137, v178
	v_add_f32_e32 v180, v136, v137
	v_pk_add_f32 v[178:179], v[48:49], v[138:139]
	v_cvt_pk_bf16_f32 v136, v140, v141
	v_cvt_pk_bf16_f32 v137, v176, v177
	v_and_b32_e32 v201, 0xffff0000, v188
	v_cvt_pk_bf16_f32 v138, v178, v179
	v_cvt_pk_bf16_f32 v139, v142, v143
	global_store_dwordx4 v[134:135], v[136:139], off offset:256
	v_mul_f32_e32 v134, v141, v141
	v_mul_f32_e32 v135, v177, v177
	v_fmac_f32_e32 v134, v140, v140
	v_fmac_f32_e32 v135, v176, v176
	v_add_f32_e32 v134, v134, v135
	v_mul_f32_e32 v135, v179, v179
	v_mul_f32_e32 v136, v143, v143
	v_fmac_f32_e32 v135, v178, v178
	v_fmac_f32_e32 v136, v142, v142
	v_add_f32_e32 v135, v135, v136
	v_add_f32_e32 v134, v134, v135
	v_add_f32_e32 v134, v180, v134
	ds_bpermute_b32 v135, v152, v134
	v_lshlrev_b32_e32 v204, 16, v189
	v_and_b32_e32 v205, 0xffff0000, v189
	v_lshlrev_b32_e32 v188, 16, v232
	v_and_b32_e32 v189, 0xffff0000, v232
	s_waitcnt lgkmcnt(0)
	v_add_f32_e32 v230, v134, v135
	v_lshl_add_u64 v[134:135], v[128:129], 0, s[4:5]
	s_mov_b32 s4, 0x50000
	v_add_co_u32_e32 v136, vcc, s4, v128
	v_and_b32_e32 v193, 0xffff0000, v233
	s_nop 0
	v_addc_co_u32_e32 v137, vcc, 0, v129, vcc
	global_load_dwordx4 v[176:179], v[136:137], off
	global_load_dwordx4 v[232:235], v[134:135], off offset:256
	v_pk_add_f32 v[194:195], v[46:47], v[204:205]
	v_pk_add_f32 v[204:205], v[44:45], v[200:201]
	v_pk_add_f32 v[202:203], v[42:43], v[202:203]
	v_pk_add_f32 v[190:191], v[36:37], v[190:191]
	v_pk_add_f32 v[192:193], v[34:35], v[192:193]
	s_mov_b64 s[4:5], 0x58000
	ds_bpermute_b32 v231, v225, v230
	s_waitcnt vmcnt(1)
	v_lshlrev_b32_e32 v140, 16, v176
	s_waitcnt vmcnt(0)
	v_lshlrev_b32_e32 v180, 16, v232
	v_and_b32_e32 v181, 0xffff0000, v232
	v_lshlrev_b32_e32 v184, 16, v233
	v_and_b32_e32 v185, 0xffff0000, v233
	v_pk_add_f32 v[232:233], v[40:41], v[198:199]
	v_cvt_pk_bf16_f32 v198, v204, v205
	v_cvt_pk_bf16_f32 v199, v194, v195
	v_and_b32_e32 v141, 0xffff0000, v176
	v_cvt_pk_bf16_f32 v200, v232, v233
	v_cvt_pk_bf16_f32 v201, v202, v203
	global_store_dwordx4 v[186:187], v[198:201], off
	v_mul_f32_e32 v186, v205, v205
	v_mul_f32_e32 v187, v195, v195
	v_fmac_f32_e32 v186, v204, v204
	v_fmac_f32_e32 v187, v194, v194
	v_add_f32_e32 v186, v186, v187
	v_mul_f32_e32 v187, v233, v233
	v_mul_f32_e32 v194, v203, v203
	v_fmac_f32_e32 v187, v232, v232
	v_fmac_f32_e32 v194, v202, v202
	v_add_f32_e32 v187, v187, v194
	v_pk_add_f32 v[194:195], v[38:39], v[196:197]
	v_add_f32_e32 v198, v186, v187
	v_pk_add_f32 v[196:197], v[32:33], v[188:189]
	v_cvt_pk_bf16_f32 v186, v190, v191
	v_cvt_pk_bf16_f32 v187, v194, v195
	v_lshlrev_b32_e32 v176, 16, v177
	v_cvt_pk_bf16_f32 v188, v196, v197
	v_cvt_pk_bf16_f32 v189, v192, v193
	global_store_dwordx4 v[130:131], v[186:189], off offset:256
	v_mul_f32_e32 v130, v191, v191
	v_mul_f32_e32 v131, v195, v195
	v_fmac_f32_e32 v130, v190, v190
	v_fmac_f32_e32 v131, v194, v194
	v_add_f32_e32 v130, v130, v131
	v_mul_f32_e32 v131, v197, v197
	v_mul_f32_e32 v186, v193, v193
	v_fmac_f32_e32 v131, v196, v196
	v_fmac_f32_e32 v186, v192, v192
	v_add_f32_e32 v131, v131, v186
	v_add_f32_e32 v130, v130, v131
	v_add_f32_e32 v130, v198, v130
	ds_bpermute_b32 v131, v152, v130
	v_lshl_add_u64 v[186:187], v[128:129], 0, s[4:5]
	s_mov_b32 s4, 0x58000
	v_add_co_u32_e32 v188, vcc, s4, v128
	s_waitcnt lgkmcnt(0)
	v_add_f32_e32 v198, v130, v131
	v_addc_co_u32_e32 v189, vcc, 0, v129, vcc
	global_load_dwordx4 v[128:131], v[188:189], off
	v_and_b32_e32 v177, 0xffff0000, v177
	v_lshlrev_b32_e32 v138, 16, v178
	v_and_b32_e32 v139, 0xffff0000, v178
	v_lshlrev_b32_e32 v142, 16, v179
	v_and_b32_e32 v143, 0xffff0000, v179
	v_pk_add_f32 v[176:177], v[30:31], v[176:177]
	v_pk_add_f32 v[140:141], v[28:29], v[140:141]
	v_pk_add_f32 v[142:143], v[26:27], v[142:143]
	v_pk_add_f32 v[138:139], v[24:25], v[138:139]
	v_lshlrev_b32_e32 v178, 16, v234
	v_and_b32_e32 v179, 0xffff0000, v234
	v_lshlrev_b32_e32 v182, 16, v235
	v_and_b32_e32 v183, 0xffff0000, v235
	ds_bpermute_b32 v199, v225, v198
	v_cmp_lt_u32_e32 vcc, 63, v222
	s_waitcnt vmcnt(0)
; __device__ __forceinline__ unsigned cvt_pk_bf16(float lo, float hi) { unsigned r; asm volatile("v_cvt_pk_bf16_f32 %0, %1, %2" : "=v"(r) : "v"(lo), "v"(hi)); return r; }
; template <bool RD32>
; __device__ __forceinline__ void res_rows(const float* __restrict__ xold32, const bf16_t* __restrict__ xoldb, bf16_t* __restrict__ xb, float* __restrict__ ssq, const f32x4 (&acc)[2][2][4][2], int row0, int col0, int slot) {
;     ...
;     for (int idx = 0; idx < 8; ++idx) {
;         const int ai = idx >> 2, m = idx & 3; const int r = row0 + ai * HALF + m * 16; const size_t off = (size_t)r * D + col0;
;         if (idx < 7) { const int ai2 = (idx + 1) >> 2, m2 = (idx + 1) & 3; const size_t off2 = (size_t)(row0 + ai2 * HALF + m2 * 16) * D + col0;
; #pragma unroll
;             for (int bj = 0; bj < 2; ++bj) ld(off2 + bj * HALF, xo[(idx + 1) & 1][bj][0], xo[(idx + 1) & 1][bj][1]); }
;         float ss = 0.f;
; #pragma unroll
;         for (int bj = 0; bj < 2; ++bj) { const f32x4 x0 = xo[idx & 1][bj][0] + acc[ai][bj][m][0], x1 = xo[idx & 1][bj][1] + acc[ai][bj][m][1];
;             u32x4 w; w.x = cvt_pk_bf16(x0[0], x0[1]); w.y = cvt_pk_bf16(x0[2], x0[3]); w.z = cvt_pk_bf16(x1[0], x1[1]); w.w = cvt_pk_bf16(x1[2], x1[3]);
;             *(u32x4*)(xb + off + bj * HALF) = w;
;             ss += ((x0[0] * x0[0] + x0[1] * x0[1]) + (x0[2] * x0[2] + x0[3] * x0[3])) + ((x1[0] * x1[0] + x1[1] * x1[1]) + (x1[2] * x1[2] + x1[3] * x1[3])); }
;         ss += __shfl_xor(ss, 16); ss += __shfl_xor(ss, 32);
;         ssv[idx] = ss;
;     }
;     const int fq = slot >> 6;
; #pragma unroll
;     for (int j = 0; j < 2; ++j) { const float v = fq == 0 ? ssv[j] : fq == 1 ? ssv[2 + j] : fq == 2 ? ssv[4 + j] : ssv[6 + j]; const int idx = 2 * fq + j;
;         ssq[(size_t)(row0 + (idx >> 2) * HALF + (idx & 3) * 16) * 16 + (slot & 15)] = v; }
	v_lshlrev_b32_e32 v192, 16, v128
	v_and_b32_e32 v193, 0xffff0000, v128
	v_lshlrev_b32_e32 v196, 16, v129
	v_and_b32_e32 v197, 0xffff0000, v129
	v_lshlrev_b32_e32 v190, 16, v130
	v_and_b32_e32 v191, 0xffff0000, v130
	v_lshlrev_b32_e32 v194, 16, v131
	v_and_b32_e32 v195, 0xffff0000, v131
	global_load_dwordx4 v[128:131], v[186:187], off offset:256
	s_waitcnt vmcnt(0)
	v_lshlrev_b32_e32 v200, 16, v128
	v_and_b32_e32 v201, 0xffff0000, v128
	v_lshlrev_b32_e32 v202, 16, v129
	v_and_b32_e32 v203, 0xffff0000, v129
	v_cvt_pk_bf16_f32 v128, v140, v141
	v_cvt_pk_bf16_f32 v129, v176, v177
	v_lshlrev_b32_e32 v204, 16, v130
	v_and_b32_e32 v205, 0xffff0000, v130
	v_lshlrev_b32_e32 v232, 16, v131
	v_and_b32_e32 v233, 0xffff0000, v131
	v_cvt_pk_bf16_f32 v130, v138, v139
	v_cvt_pk_bf16_f32 v131, v142, v143
	global_store_dwordx4 v[136:137], v[128:131], off
	v_pk_add_f32 v[136:137], v[22:23], v[184:185]
	s_nop 0
	v_mul_f32_e32 v128, v141, v141
	v_mul_f32_e32 v129, v177, v177
	v_fmac_f32_e32 v128, v140, v140
	v_fmac_f32_e32 v129, v176, v176
	v_add_f32_e32 v128, v128, v129
	v_mul_f32_e32 v129, v139, v139
	v_mul_f32_e32 v130, v143, v143
	v_fmac_f32_e32 v129, v138, v138
	v_fmac_f32_e32 v130, v142, v142
	v_add_f32_e32 v129, v129, v130
	v_add_f32_e32 v176, v128, v129
	v_pk_add_f32 v[138:139], v[20:21], v[180:181]
	v_pk_add_f32 v[140:141], v[18:19], v[182:183]
	v_cvt_pk_bf16_f32 v128, v138, v139
	v_cvt_pk_bf16_f32 v129, v136, v137
	v_pk_add_f32 v[142:143], v[16:17], v[178:179]
	s_nop 0
	v_cvt_pk_bf16_f32 v130, v142, v143
	v_cvt_pk_bf16_f32 v131, v140, v141
	global_store_dwordx4 v[134:135], v[128:131], off offset:256
	s_nop 1
	v_mul_f32_e32 v128, v139, v139
	v_mul_f32_e32 v129, v137, v137
	v_fmac_f32_e32 v128, v138, v138
	v_fmac_f32_e32 v129, v136, v136
	v_add_f32_e32 v128, v128, v129
	v_mul_f32_e32 v129, v143, v143
	v_mul_f32_e32 v130, v141, v141
	v_fmac_f32_e32 v129, v142, v142
	v_fmac_f32_e32 v130, v140, v140
	v_add_f32_e32 v129, v129, v130
	v_add_f32_e32 v128, v128, v129
	v_add_f32_e32 v128, v176, v128
	ds_bpermute_b32 v129, v152, v128
	v_pk_add_f32 v[130:131], v[14:15], v[196:197]
	v_pk_add_f32 v[140:141], v[12:13], v[192:193]
	v_pk_add_f32 v[142:143], v[10:11], v[194:195]
	v_cvt_pk_bf16_f32 v136, v140, v141
	s_waitcnt lgkmcnt(0)
	v_add_f32_e32 v129, v128, v129
	v_cvt_pk_bf16_f32 v137, v130, v131
	v_mul_f32_e32 v128, v141, v141
	v_mul_f32_e32 v131, v131, v131
	v_pk_add_f32 v[176:177], v[8:9], v[190:191]
	v_fmac_f32_e32 v128, v140, v140
	v_fmac_f32_e32 v131, v130, v130
	v_add_f32_e32 v128, v128, v131
	v_mul_f32_e32 v130, v177, v177
	v_mul_f32_e32 v131, v143, v143
	v_fmac_f32_e32 v130, v176, v176
	v_fmac_f32_e32 v131, v142, v142
	v_add_f32_e32 v130, v130, v131
	v_add_f32_e32 v128, v128, v130
	v_pk_add_f32 v[130:131], v[6:7], v[202:203]
	v_pk_add_f32 v[140:141], v[4:5], v[200:201]
	v_cvt_pk_bf16_f32 v138, v176, v177
	v_cvt_pk_bf16_f32 v139, v142, v143
	global_store_dwordx4 v[188:189], v[136:139], off
	v_mul_f32_e32 v134, v141, v141
	v_pk_add_f32 v[142:143], v[2:3], v[232:233]
	v_cvt_pk_bf16_f32 v136, v140, v141
	v_cvt_pk_bf16_f32 v137, v130, v131
	v_mul_f32_e32 v131, v131, v131
	v_pk_add_f32 v[176:177], v[0:1], v[204:205]
	v_fmac_f32_e32 v134, v140, v140
	v_fmac_f32_e32 v131, v130, v130
	v_add_f32_e32 v130, v134, v131
	v_mul_f32_e32 v131, v177, v177
	v_mul_f32_e32 v134, v143, v143
	v_fmac_f32_e32 v131, v176, v176
	v_fmac_f32_e32 v134, v142, v142
	v_add_f32_e32 v131, v131, v134
	v_add_f32_e32 v130, v130, v131
	v_add_f32_e32 v128, v128, v130
	ds_bpermute_b32 v130, v152, v128
	v_cvt_pk_bf16_f32 v138, v176, v177
	v_cvt_pk_bf16_f32 v139, v142, v143
	global_store_dwordx4 v[186:187], v[136:139], off offset:256
	ds_bpermute_b32 v135, v225, v129
	s_waitcnt lgkmcnt(1)
	v_add_f32_e32 v136, v128, v130
	ds_bpermute_b32 v137, v225, v136
	v_and_b32_e32 v130, 15, v223
	v_and_b32_e32 v128, 0xffffff80, v222
	v_lshlrev_b32_e32 v152, 2, v130
	v_add_u32_e32 v128, v166, v128
	v_lshl_add_u64 v[130:131], s[18:19], 0, v[152:153]
	s_and_saveexec_b64 s[4:5], vcc
	s_xor_b64 s[24:25], exec, s[4:5]
	s_cbranch_execz .LBB0_433
	v_ashrrev_i32_e32 v138, 6, v222
	v_cmp_lt_i32_e32 vcc, 1, v138
	s_mov_b64 s[36:37], 0
	s_and_saveexec_b64 s[4:5], vcc
	s_xor_b64 s[38:39], exec, s[4:5]
	s_cbranch_execnz .LBB0_454
	s_or_saveexec_b64 s[38:39], s[38:39]
	v_cmp_ne_u32_e32 vcc, 1, v138
	s_xor_b64 exec, exec, s[38:39]
	s_cbranch_execnz .LBB0_457

; #define PG8_STAGE(bufoff, gbase, voff) do { _Pragma("unroll") for (int _i = 0; _i < 2; ++_i) \
;         __builtin_amdgcn_global_load_lds((const unsigned*)((const char*)(gbase) + (voff)[_i]), (LAS unsigned*)(lds + (bufoff) + ldsw + _i * 8192), 16, 0, 0); } while (0)
; #define PG8_WAIT_V(n) asm volatile("s_waitcnt vmcnt(" #n ")" ::: "memory")
; #define PG8_BAR __builtin_amdgcn_s_barrier()
; template <class Epi, class Sched, bool ALIGN_EPI = false, bool SP2 = false>
; __device__ __forceinline__ void gemm_phase(LAS unsigned char* lds, const Gemm g, const Sched& S, const Epi& E) {
;     ...
;     for (int i = 0; i < 2; ++i) { int R, C; stage_rc(tid * 16 + i * 8192, R, C); const int Rb = Epi::PERM ? ((R & ~31) + perm32(R & 31)) : R;
;         voffA[i] = (unsigned)(R * K + C) * 2u; voffB[i] = (unsigned)(Rb * K + C) * 2u; }
;     const size_t kstep = (size_t)(BK * 2);
;     const size_t hstep = (size_t)HALF * K * 2;
;     const size_t tstep = 2 * hstep;
;     const unsigned ldsw = (unsigned)wid * 1024u;
;     const int aoff = lds_byte(wr * 64 + fr, fq * 8), boff = lds_byte(wc * 32 + fr, fq * 8);
;     ...
;     const char* cA = (const char*)g.A + (size_t)cur.pm * tstep; const char* cB = (const char*)g.Bt + (size_t)cur.pn * tstep;
;     S.a_ready(cur);
;     if constexpr (SP2) {
;         PG8_STAGE(PG8_SB(0, 0), cB, voffB); PG8_STAGE(PG8_SB(0, 1), cB + hstep, voffB); PG8_STAGE(PG8_SA(0, 0), cA, voffA); PG8_STAGE(PG8_SA(0, 1), cA + hstep, voffA);
;         if (wr == 1) PG8_BAR;
;         PG8_WAIT_V(2); PG8_BAR;
;         PG8_STAGE(PG8_SB(1, 0), cB + kstep, voffB); PG8_STAGE(PG8_SA(1, 0), cA + kstep, voffA); PG8_STAGE(PG8_SB(1, 1), cB + hstep + kstep, voffB);
.LBB0_521:
	s_or_b64 exec, exec, s[24:25]
	v_readlane_b32 s4, v246, 56
	v_readlane_b32 s5, v246, 57
	s_lshl_b64 s[24:25], s[4:5], 23
	v_readlane_b32 s4, v246, 2
	v_mov_b32_e32 v5, v206
	v_readlane_b32 s5, v246, 3
	s_waitcnt lgkmcnt(0)
	s_barrier
	s_mov_b32 s101, 0
	s_andn2_b64 vcc, exec, s[4:5]
	v_readfirstlane_b32 s13, v5
	s_cbranch_vccnz .LBB0_547
	v_lshlrev_b32_e32 v0, 4, v5
	v_add_u32_e32 v1, 0x2000, v0
	v_ashrrev_i32_e32 v2, 31, v1
	v_lshrrev_b32_e32 v2, 22, v2
	v_add_u32_e32 v2, v1, v2
	v_ashrrev_i32_e32 v4, 10, v2
	v_mul_i32_i24_e32 v2, 0x400, v4
	v_sub_u32_e32 v1, v1, v2
	v_lshrrev_b32_e32 v2, 4, v1
	v_bitop3_b32 v1, v2, v1, 32 bitop3:0x6c
	v_ashrrev_i32_e32 v2, 31, v1
	v_lshrrev_b32_e32 v2, 26, v2
	v_add_u32_e32 v2, v1, v2
	v_lshlrev_b32_e32 v3, 3, v4
	v_ashrrev_i32_e32 v6, 6, v2
	v_and_b32_e32 v3, -16, v3
	v_add_u32_e32 v3, v6, v3
	v_and_b32_e32 v7, 3, v6
	s_mov_b32 s7, 0x1fffe0
	v_lshrrev_b32_e32 v8, 2, v3
	v_lshlrev_b32_e32 v9, 1, v3
	v_and_b32_e32 v2, 0xc0, v2
	v_and_or_b32 v7, v3, s7, v7
	v_and_b32_e32 v8, 4, v8
	v_and_b32_e32 v9, 24, v9
	v_sub_u32_e32 v1, v1, v2
	v_or3_b32 v8, v7, v8, v9
	v_lshlrev_b32_e32 v7, 5, v4
	v_ashrrev_i16_sdwa v1, v207, sext(v1) dst_sel:DWORD dst_unused:UNUSED_PAD src0_sel:DWORD src1_sel:BYTE_0
	v_and_b32_e32 v9, 32, v7
	v_bfe_i32 v7, v1, 0, 16
	v_add_lshl_u32 v1, v9, v7, 1
	v_lshl_add_u32 v162, v8, 11, v1
	v_lshl_add_u32 v164, v3, 11, v1
	v_bfe_i32 v1, v5, 27, 1
	v_lshrrev_b32_e32 v1, 22, v1
	v_add_u32_e32 v1, v0, v1
	v_and_b32_e32 v1, 0xfffffc00, v1
	v_sub_u32_e32 v0, v0, v1
	v_lshrrev_b32_e32 v1, 4, v0
	v_ashrrev_i32_e32 v2, 31, v5
	v_bitop3_b32 v0, v1, v0, 32 bitop3:0x6c
	v_lshrrev_b32_e32 v2, 26, v2
	v_ashrrev_i32_e32 v1, 31, v0
	v_add_u32_e32 v2, v5, v2
	v_lshrrev_b32_e32 v1, 26, v1
	v_ashrrev_i32_e32 v9, 6, v2
	v_add_u32_e32 v1, v0, v1
	v_lshlrev_b32_e32 v2, 3, v9
	v_ashrrev_i32_e32 v8, 6, v1
	v_and_b32_e32 v2, -16, v2
	v_readlane_b32 s4, v246, 0
	v_add_u32_e32 v2, v8, v2
	s_add_u32 s4, s4, s24
	v_readlane_b32 s5, v246, 1
	v_and_b32_e32 v3, 3, v8
	v_lshrrev_b32_e32 v10, 2, v2
	v_lshlrev_b32_e32 v11, 1, v2
	v_and_b32_e32 v1, 0xc0, v1
	s_addc_u32 s5, s5, s25
	s_ashr_i32 s36, s13, 6
	v_and_or_b32 v3, v2, s7, v3
	v_and_b32_e32 v10, 4, v10
	v_and_b32_e32 v11, 24, v11
	v_sub_u32_e32 v0, v0, v1
	s_ashr_i32 s28, s13, 8
	s_lshl_b32 s6, s36, 10
	v_or3_b32 v3, v3, v10, v11
	v_lshlrev_b32_e32 v10, 5, v9
	v_ashrrev_i16_sdwa v0, v207, sext(v0) dst_sel:DWORD dst_unused:UNUSED_PAD src0_sel:DWORD src1_sel:BYTE_0
	v_readlane_b32 s8, v246, 7
	v_and_b32_e32 v11, 32, v10
	v_bfe_i32 v10, v0, 0, 16
	v_readlane_b32 s9, v246, 8
	s_add_u32 s50, s4, s8
	v_add_lshl_u32 v0, v11, v10, 1
	s_addc_u32 s51, s5, s9
	s_add_i32 s7, s6, 0
	v_lshl_add_u32 v166, v3, 11, v0
	s_add_i32 m0, s7, 0x10000
	v_readlane_b32 s10, v246, 12
	global_load_lds_dwordx4 v166, s[50:51]
	s_add_i32 m0, s7, 0x12000
	s_add_u32 s8, s50, 0x40000
	global_load_lds_dwordx4 v162, s[50:51]
	s_addc_u32 s9, s51, 0
	s_add_i32 m0, s7, 0x14000
	v_lshl_add_u32 v168, v2, 11, v0
	global_load_lds_dwordx4 v166, s[8:9]
	s_add_i32 m0, s7, 0x16000
	v_readlane_b32 s11, v246, 13
	global_load_lds_dwordx4 v162, s[8:9]
	s_mov_b32 m0, s7
	s_add_i32 s8, s7, 0x2000
	s_add_i32 s9, s7, 0x4000
	s_nop 0
	global_load_lds_dwordx4 v168, s[10:11]
	s_mov_b32 m0, s8
	v_readlane_b32 s14, v246, 14
	global_load_lds_dwordx4 v164, s[10:11]
	s_mov_b32 m0, s9
	v_readlane_b32 s15, v246, 15
	s_add_i32 s10, s7, 0x6000
	v_mov_b32_e32 v167, v153
	v_mov_b32_e32 v163, v153
	s_cmp_eq_u32 s28, 1
	v_lshl_add_u64 v[0:1], s[50:51], 0, v[166:167]
	global_load_lds_dwordx4 v168, s[14:15]
	s_mov_b32 m0, s10
	s_cselect_b64 s[26:27], -1, 0
	global_load_lds_dwordx4 v164, s[14:15]
	s_cmp_lg_u32 s28, 1
	v_lshl_add_u64 v[2:3], s[50:51], 0, v[162:163]
	s_cbranch_scc1 .LBB0_524
	s_barrier

; #define PG8_STAGE(bufoff, gbase, voff) do { _Pragma("unroll") for (int _i = 0; _i < 2; ++_i) \
;         __builtin_amdgcn_global_load_lds((const unsigned*)((const char*)(gbase) + (voff)[_i]), (LAS unsigned*)(lds + (bufoff) + ldsw + _i * 8192), 16, 0, 0); } while (0)
; #define PG8_LDA(dst, b, h) do { _Pragma("unroll") for (int m = 0; m < 4; ++m) _Pragma("unroll") for (int k = 0; k < 2; ++k) dst[m][k] = *(const LAS bf16x8*)(lds + PG8_SA(b, h) + aoff + m * 2048 + k * 1024); } while (0)
; #define PG8_LDB(dst, b, h) do { _Pragma("unroll") for (int n = 0; n < 2; ++n) _Pragma("unroll") for (int k = 0; k < 2; ++k) dst[n][k] = *(const LAS bf16x8*)(lds + PG8_SB(b, h) + boff + n * 2048 + k * 1024); } while (0)
; #define PG8_MMA(ai, bj, At, Bt) do { __builtin_amdgcn_s_setprio(1); _Pragma("unroll") for (int m = 0; m < 4; ++m) _Pragma("unroll") for (int n = 0; n < 2; ++n) _Pragma("unroll") for (int k = 0; k < 2; ++k) \
;         acc[ai][bj][m][n] = __builtin_amdgcn_mfma_f32_16x16x32_bf16(Bt[n][k], At[m][k], acc[ai][bj][m][n], 0, 0, 0); __builtin_amdgcn_s_setprio(0); } while (0)
; #define PG8_WAIT_V(n) asm volatile("s_waitcnt vmcnt(" #n ")" ::: "memory")
; #define PG8_WAIT_L(n) asm volatile("s_waitcnt lgkmcnt(" #n ")" ::: "memory")
; template <class Epi, class Sched, bool ALIGN_EPI = false, bool SP2 = false>
; __device__ __forceinline__ void gemm_phase(LAS unsigned char* lds, const Gemm g, const Sched& S, const Epi& E) {
;     ...
;         for (int t = 0; t < nt; t += 2) {
;             const bool last = (t == nt - 2);
;             const char* a1 = cA + (size_t)(t + 1) * kstep;
;             const char* a2 = last ? nA : cA + (size_t)(t + 2) * kstep; const char* b2 = last ? nB : cB + (size_t)(t + 2) * kstep;
;             const char* a3 = a2 + kstep; const char* b3 = b2 + kstep;
;             if (last && has_next) S.a_ready(nxt);
;             if constexpr (SP2) {
;             PG8_LDB(B0, 0, 0); PG8_LDB(B1, 0, 1); PG8_SCHED; PG8_LDA(At, 0, 0); PG8_STAGE(PG8_SA(1, 1), a1 + hstep, voffA);
;             PG8_WAIT_V(8); PG8_WAIT_L(0); PG8_BAR; PG8_MMA(0, 0, At, B0); PG8_MMA(0, 1, At, B1); PG8_BAR; PG8_SCHED;
;             PG8_LDA(At, 0, 1); PG8_STAGE(PG8_SB(0, 0), b2, voffB); PG8_STAGE(PG8_SB(0, 1), b2 + hstep, voffB); PG8_STAGE(PG8_SA(0, 0), a2, voffA);
;             PG8_WAIT_V(8); PG8_WAIT_L(0); PG8_BAR; PG8_MMA(1, 0, At, B0); PG8_MMA(1, 1, At, B1); PG8_BAR; PG8_SCHED;
.LBB0_534:
	s_add_u32 s14, s46, 0xfffc0080
	s_addc_u32 s15, s47, -1
	s_add_i32 s16, 0, 0x10000
	s_cmp_eq_u32 s82, 12
	s_cselect_b32 s55, s39, s15
	s_cselect_b32 s54, s71, s14
	s_cselect_b32 s51, s37, s79
	s_cselect_b32 s50, s72, s73
	s_add_i32 s17, 0, 0x14000
	v_add_u32_e32 v140, s16, v194
	v_add_u32_e32 v180, s17, v194
	ds_read_b128 v[128:131], v140
	ds_read_b128 v[132:135], v140 offset:1024
	ds_read_b128 v[136:139], v140 offset:2048
	ds_read_b128 v[140:143], v140 offset:3072
	ds_read_b128 v[144:147], v180
	ds_read_b128 v[148:151], v180 offset:1024
	ds_read_b128 v[176:179], v180 offset:2048
	ds_read_b128 v[180:183], v180 offset:3072
	v_lshl_add_u64 v[234:235], s[46:47], 0, v[172:173]
	s_add_i32 m0, s7, 0xc000
	ds_read_b128 v[184:187], v196
	ds_read_b128 v[190:193], v196 offset:1024
	ds_read_b128 v[198:201], v196 offset:2048
	ds_read_b128 v[202:205], v196 offset:3072
	ds_read_b128 v[218:221], v196 offset:4096
	ds_read_b128 v[222:225], v196 offset:5120
	ds_read_b128 v[226:229], v196 offset:6144
	ds_read_b128 v[230:233], v196 offset:7168
	global_load_lds_dwordx4 v[234:235], off
	v_lshl_add_u64 v[234:235], s[46:47], 0, v[174:175]
	s_add_i32 m0, s7, 0xe000
	s_nop 0
	global_load_lds_dwordx4 v[234:235], off
	s_waitcnt vmcnt(24)
	s_cmp_eq_u32 s101, 1
	s_cbranch_scc1 .Lrlx_3
	s_waitcnt vmcnt(8)
.Lrlx_3:
	s_waitcnt lgkmcnt(0)
	s_barrier
	s_setprio 1
	s_waitcnt lgkmcnt(0)
	v_mfma_f32_16x16x32_bf16 v[124:127], v[128:131], v[184:187], v[124:127]
	v_mfma_f32_16x16x32_bf16 v[120:123], v[136:139], v[184:187], v[120:123]
	v_mfma_f32_16x16x32_bf16 v[108:111], v[128:131], v[198:201], v[108:111]
	v_mfma_f32_16x16x32_bf16 v[104:107], v[136:139], v[198:201], v[104:107]
	v_mfma_f32_16x16x32_bf16 v[92:95], v[128:131], v[218:221], v[92:95]
	v_mfma_f32_16x16x32_bf16 v[88:91], v[136:139], v[218:221], v[88:91]
	v_mfma_f32_16x16x32_bf16 v[76:79], v[128:131], v[226:229], v[76:79]
	v_mfma_f32_16x16x32_bf16 v[72:75], v[136:139], v[226:229], v[72:75]
	v_mfma_f32_16x16x32_bf16 v[124:127], v[132:135], v[190:193], v[124:127]
	v_mfma_f32_16x16x32_bf16 v[120:123], v[140:143], v[190:193], v[120:123]
	v_mfma_f32_16x16x32_bf16 v[108:111], v[132:135], v[202:205], v[108:111]
	v_mfma_f32_16x16x32_bf16 v[104:107], v[140:143], v[202:205], v[104:107]
	v_mfma_f32_16x16x32_bf16 v[92:95], v[132:135], v[222:225], v[92:95]
	v_mfma_f32_16x16x32_bf16 v[88:91], v[140:143], v[222:225], v[88:91]
	v_mfma_f32_16x16x32_bf16 v[76:79], v[132:135], v[230:233], v[76:79]
	v_mfma_f32_16x16x32_bf16 v[72:75], v[140:143], v[230:233], v[72:75]
	s_setprio 0
	s_setprio 1
	v_mfma_f32_16x16x32_bf16 v[116:119], v[144:147], v[184:187], v[116:119]
	v_mfma_f32_16x16x32_bf16 v[112:115], v[176:179], v[184:187], v[112:115]
	v_mfma_f32_16x16x32_bf16 v[100:103], v[144:147], v[198:201], v[100:103]
	v_mfma_f32_16x16x32_bf16 v[96:99], v[176:179], v[198:201], v[96:99]
	v_mfma_f32_16x16x32_bf16 v[84:87], v[144:147], v[218:221], v[84:87]
	v_mfma_f32_16x16x32_bf16 v[80:83], v[176:179], v[218:221], v[80:83]
	v_mfma_f32_16x16x32_bf16 v[68:71], v[144:147], v[226:229], v[68:71]
	v_mfma_f32_16x16x32_bf16 v[64:67], v[176:179], v[226:229], v[64:67]
	v_mfma_f32_16x16x32_bf16 v[116:119], v[148:151], v[190:193], v[116:119]
	v_mfma_f32_16x16x32_bf16 v[112:115], v[180:183], v[190:193], v[112:115]
	v_mfma_f32_16x16x32_bf16 v[100:103], v[148:151], v[202:205], v[100:103]
	v_mfma_f32_16x16x32_bf16 v[96:99], v[180:183], v[202:205], v[96:99]
	v_mfma_f32_16x16x32_bf16 v[84:87], v[148:151], v[222:225], v[84:87]
	v_mfma_f32_16x16x32_bf16 v[80:83], v[180:183], v[222:225], v[80:83]
	v_mfma_f32_16x16x32_bf16 v[68:71], v[148:151], v[230:233], v[68:71]
	v_mfma_f32_16x16x32_bf16 v[64:67], v[180:183], v[230:233], v[64:67]
	s_setprio 0
	s_barrier
	s_add_i32 s14, s16, s6
	v_lshl_add_u64 v[234:235], s[50:51], 0, v[166:167]
	s_mov_b32 m0, s14
	ds_read_b128 v[184:187], v196 offset:16384
	ds_read_b128 v[190:193], v196 offset:17408
	ds_read_b128 v[198:201], v196 offset:18432
	ds_read_b128 v[202:205], v196 offset:19456
	ds_read_b128 v[218:221], v196 offset:20480
	ds_read_b128 v[222:225], v196 offset:21504
	ds_read_b128 v[226:229], v196 offset:22528
	ds_read_b128 v[230:233], v196 offset:23552
	global_load_lds_dwordx4 v[234:235], off
	s_add_i32 m0, s14, 0x2000
	s_add_u32 s14, s50, 0x40000
	v_lshl_add_u64 v[236:237], s[50:51], 0, v[162:163]
	s_addc_u32 s15, s51, 0
	s_add_i32 s16, s17, s6
	global_load_lds_dwordx4 v[236:237], off
	v_lshl_add_u64 v[238:239], s[14:15], 0, v[166:167]
	s_mov_b32 m0, s16
	v_lshl_add_u64 v[240:241], s[54:55], 0, v[164:165]
	global_load_lds_dwordx4 v[238:239], off
	v_lshl_add_u64 v[238:239], s[14:15], 0, v[162:163]
	s_add_i32 m0, s16, 0x2000
	s_nop 0
	global_load_lds_dwordx4 v[238:239], off
	v_lshl_add_u64 v[238:239], s[54:55], 0, v[168:169]
	s_mov_b32 m0, s7
	s_nop 0
	global_load_lds_dwordx4 v[238:239], off
	s_mov_b32 m0, s8
	s_nop 0
	global_load_lds_dwordx4 v[240:241], off
	s_waitcnt vmcnt(24)
	s_cmp_eq_u32 s101, 1
	s_cbranch_scc1 .Lrlx_4
	s_waitcnt vmcnt(8)
; #define PG8_STAGE(bufoff, gbase, voff) do { _Pragma("unroll") for (int _i = 0; _i < 2; ++_i) \
;         __builtin_amdgcn_global_load_lds((const unsigned*)((const char*)(gbase) + (voff)[_i]), (LAS unsigned*)(lds + (bufoff) + ldsw + _i * 8192), 16, 0, 0); } while (0)
; #define PG8_LDA(dst, b, h) do { _Pragma("unroll") for (int m = 0; m < 4; ++m) _Pragma("unroll") for (int k = 0; k < 2; ++k) dst[m][k] = *(const LAS bf16x8*)(lds + PG8_SA(b, h) + aoff + m * 2048 + k * 1024); } while (0)
; #define PG8_LDB(dst, b, h) do { _Pragma("unroll") for (int n = 0; n < 2; ++n) _Pragma("unroll") for (int k = 0; k < 2; ++k) dst[n][k] = *(const LAS bf16x8*)(lds + PG8_SB(b, h) + boff + n * 2048 + k * 1024); } while (0)
; #define PG8_MMA(ai, bj, At, Bt) do { __builtin_amdgcn_s_setprio(1); _Pragma("unroll") for (int m = 0; m < 4; ++m) _Pragma("unroll") for (int n = 0; n < 2; ++n) _Pragma("unroll") for (int k = 0; k < 2; ++k) \
;         acc[ai][bj][m][n] = __builtin_amdgcn_mfma_f32_16x16x32_bf16(Bt[n][k], At[m][k], acc[ai][bj][m][n], 0, 0, 0); __builtin_amdgcn_s_setprio(0); } while (0)
; #define PG8_WAIT_V(n) asm volatile("s_waitcnt vmcnt(" #n ")" ::: "memory")
; #define PG8_WAIT_L(n) asm volatile("s_waitcnt lgkmcnt(" #n ")" ::: "memory")
; #define PG8_BAR __builtin_amdgcn_s_barrier()
; #define PG8_SCHED __builtin_amdgcn_sched_barrier(0)
; template <class Epi, class Sched, bool ALIGN_EPI = false, bool SP2 = false>
; __device__ __forceinline__ void gemm_phase(LAS unsigned char* lds, const Gemm g, const Sched& S, const Epi& E) {
;     ...
;             PG8_WAIT_V(8); PG8_WAIT_L(0); PG8_BAR; PG8_MMA(1, 0, At, B0); PG8_MMA(1, 1, At, B1); PG8_BAR; PG8_SCHED;
;             PG8_LDB(B0, 1, 0); PG8_LDB(B1, 1, 1); PG8_SCHED; PG8_LDA(At, 1, 0); PG8_STAGE(PG8_SA(0, 1), a2 + hstep, voffA);
;             PG8_WAIT_V(8); PG8_WAIT_L(0); PG8_BAR; PG8_MMA(0, 0, At, B0); PG8_MMA(0, 1, At, B1); PG8_BAR; PG8_SCHED;
.Lrlx_4:
	s_mov_b32 s101, 0
	s_waitcnt lgkmcnt(0)
	s_barrier
	s_setprio 1
	s_waitcnt lgkmcnt(0)
	v_mfma_f32_16x16x32_bf16 v[60:63], v[128:131], v[184:187], v[60:63]
	v_mfma_f32_16x16x32_bf16 v[56:59], v[136:139], v[184:187], v[56:59]
	v_mfma_f32_16x16x32_bf16 v[44:47], v[128:131], v[198:201], v[44:47]
	v_mfma_f32_16x16x32_bf16 v[40:43], v[136:139], v[198:201], v[40:43]
	v_mfma_f32_16x16x32_bf16 v[28:31], v[128:131], v[218:221], v[28:31]
	v_mfma_f32_16x16x32_bf16 v[24:27], v[136:139], v[218:221], v[24:27]
	v_mfma_f32_16x16x32_bf16 v[12:15], v[128:131], v[226:229], v[12:15]
	v_mfma_f32_16x16x32_bf16 v[8:11], v[136:139], v[226:229], v[8:11]
	v_mfma_f32_16x16x32_bf16 v[60:63], v[132:135], v[190:193], v[60:63]
	v_mfma_f32_16x16x32_bf16 v[56:59], v[140:143], v[190:193], v[56:59]
	v_mfma_f32_16x16x32_bf16 v[44:47], v[132:135], v[202:205], v[44:47]
	v_mfma_f32_16x16x32_bf16 v[40:43], v[140:143], v[202:205], v[40:43]
	v_mfma_f32_16x16x32_bf16 v[28:31], v[132:135], v[222:225], v[28:31]
	v_mfma_f32_16x16x32_bf16 v[24:27], v[140:143], v[222:225], v[24:27]
	v_mfma_f32_16x16x32_bf16 v[12:15], v[132:135], v[230:233], v[12:15]
	v_mfma_f32_16x16x32_bf16 v[8:11], v[140:143], v[230:233], v[8:11]
	s_setprio 0
	s_setprio 1
	v_mfma_f32_16x16x32_bf16 v[52:55], v[144:147], v[184:187], v[52:55]
	v_mfma_f32_16x16x32_bf16 v[48:51], v[176:179], v[184:187], v[48:51]
	v_mfma_f32_16x16x32_bf16 v[36:39], v[144:147], v[198:201], v[36:39]
	v_mfma_f32_16x16x32_bf16 v[32:35], v[176:179], v[198:201], v[32:35]
	v_mfma_f32_16x16x32_bf16 v[20:23], v[144:147], v[218:221], v[20:23]
	v_mfma_f32_16x16x32_bf16 v[16:19], v[176:179], v[218:221], v[16:19]
	v_mfma_f32_16x16x32_bf16 v[4:7], v[144:147], v[226:229], v[4:7]
	v_mfma_f32_16x16x32_bf16 v[0:3], v[176:179], v[226:229], v[0:3]
	v_mfma_f32_16x16x32_bf16 v[52:55], v[148:151], v[190:193], v[52:55]
	v_mfma_f32_16x16x32_bf16 v[48:51], v[180:183], v[190:193], v[48:51]
	v_mfma_f32_16x16x32_bf16 v[36:39], v[148:151], v[202:205], v[36:39]
	v_mfma_f32_16x16x32_bf16 v[32:35], v[180:183], v[202:205], v[32:35]
	v_mfma_f32_16x16x32_bf16 v[20:23], v[148:151], v[222:225], v[20:23]
	v_mfma_f32_16x16x32_bf16 v[16:19], v[180:183], v[222:225], v[16:19]
	v_mfma_f32_16x16x32_bf16 v[4:7], v[148:151], v[230:233], v[4:7]
	v_mfma_f32_16x16x32_bf16 v[0:3], v[180:183], v[230:233], v[0:3]
	s_setprio 0
	s_barrier
	s_add_i32 s16, 0, 0x18000
	s_add_i32 s17, 0, 0x1c000
	v_add_u32_e32 v140, s16, v194
	v_add_u32_e32 v180, s17, v194
	ds_read_b128 v[128:131], v140
	ds_read_b128 v[132:135], v140 offset:1024
	ds_read_b128 v[136:139], v140 offset:2048
	ds_read_b128 v[140:143], v140 offset:3072
	ds_read_b128 v[144:147], v180
	ds_read_b128 v[148:151], v180 offset:1024
	ds_read_b128 v[176:179], v180 offset:2048
	ds_read_b128 v[180:183], v180 offset:3072
	s_add_u32 s14, s54, 0x40000
	s_addc_u32 s15, s55, 0
	s_mov_b32 m0, s9
	v_lshl_add_u64 v[242:243], s[14:15], 0, v[168:169]
	ds_read_b128 v[184:187], v196 offset:32768
	ds_read_b128 v[190:193], v196 offset:33792
	ds_read_b128 v[198:201], v196 offset:34816
	ds_read_b128 v[202:205], v196 offset:35840
	ds_read_b128 v[218:221], v196 offset:36864
	ds_read_b128 v[222:225], v196 offset:37888
	ds_read_b128 v[226:229], v196 offset:38912
	ds_read_b128 v[230:233], v196 offset:39936
	global_load_lds_dwordx4 v[242:243], off
	v_lshl_add_u64 v[242:243], s[14:15], 0, v[164:165]
	s_mov_b32 m0, s10
	s_nop 0
	global_load_lds_dwordx4 v[242:243], off
	s_waitcnt vmcnt(8)
	s_waitcnt lgkmcnt(0)
	s_barrier
	s_setprio 1
	s_waitcnt lgkmcnt(0)
	v_mfma_f32_16x16x32_bf16 v[124:127], v[128:131], v[184:187], v[124:127]
	v_mfma_f32_16x16x32_bf16 v[120:123], v[136:139], v[184:187], v[120:123]
	v_mfma_f32_16x16x32_bf16 v[108:111], v[128:131], v[198:201], v[108:111]
	v_mfma_f32_16x16x32_bf16 v[104:107], v[136:139], v[198:201], v[104:107]
	v_mfma_f32_16x16x32_bf16 v[92:95], v[128:131], v[218:221], v[92:95]
	v_mfma_f32_16x16x32_bf16 v[88:91], v[136:139], v[218:221], v[88:91]
	v_mfma_f32_16x16x32_bf16 v[76:79], v[128:131], v[226:229], v[76:79]
	v_mfma_f32_16x16x32_bf16 v[72:75], v[136:139], v[226:229], v[72:75]
	v_mfma_f32_16x16x32_bf16 v[124:127], v[132:135], v[190:193], v[124:127]
	v_mfma_f32_16x16x32_bf16 v[120:123], v[140:143], v[190:193], v[120:123]
	v_mfma_f32_16x16x32_bf16 v[108:111], v[132:135], v[202:205], v[108:111]
	v_mfma_f32_16x16x32_bf16 v[104:107], v[140:143], v[202:205], v[104:107]
	v_mfma_f32_16x16x32_bf16 v[92:95], v[132:135], v[222:225], v[92:95]
	v_mfma_f32_16x16x32_bf16 v[88:91], v[140:143], v[222:225], v[88:91]
	v_mfma_f32_16x16x32_bf16 v[76:79], v[132:135], v[230:233], v[76:79]
	v_mfma_f32_16x16x32_bf16 v[72:75], v[140:143], v[230:233], v[72:75]
	s_setprio 0
	s_setprio 1
	v_mfma_f32_16x16x32_bf16 v[116:119], v[144:147], v[184:187], v[116:119]
	v_mfma_f32_16x16x32_bf16 v[112:115], v[176:179], v[184:187], v[112:115]
	v_mfma_f32_16x16x32_bf16 v[100:103], v[144:147], v[198:201], v[100:103]
	v_mfma_f32_16x16x32_bf16 v[96:99], v[176:179], v[198:201], v[96:99]
	v_mfma_f32_16x16x32_bf16 v[84:87], v[144:147], v[218:221], v[84:87]
	v_mfma_f32_16x16x32_bf16 v[80:83], v[176:179], v[218:221], v[80:83]
	v_mfma_f32_16x16x32_bf16 v[68:71], v[144:147], v[226:229], v[68:71]
	v_mfma_f32_16x16x32_bf16 v[64:67], v[176:179], v[226:229], v[64:67]
	v_mfma_f32_16x16x32_bf16 v[116:119], v[148:151], v[190:193], v[116:119]
	v_mfma_f32_16x16x32_bf16 v[112:115], v[180:183], v[190:193], v[112:115]
	v_mfma_f32_16x16x32_bf16 v[100:103], v[148:151], v[202:205], v[100:103]
	v_mfma_f32_16x16x32_bf16 v[96:99], v[180:183], v[202:205], v[96:99]
	v_mfma_f32_16x16x32_bf16 v[84:87], v[148:151], v[222:225], v[84:87]
	v_mfma_f32_16x16x32_bf16 v[80:83], v[180:183], v[222:225], v[80:83]
	v_mfma_f32_16x16x32_bf16 v[68:71], v[148:151], v[230:233], v[68:71]
	v_mfma_f32_16x16x32_bf16 v[64:67], v[180:183], v[230:233], v[64:67]
	s_setprio 0
	s_barrier
; #define PG8_STAGE(bufoff, gbase, voff) do { _Pragma("unroll") for (int _i = 0; _i < 2; ++_i) \
;         __builtin_amdgcn_global_load_lds((const unsigned*)((const char*)(gbase) + (voff)[_i]), (LAS unsigned*)(lds + (bufoff) + ldsw + _i * 8192), 16, 0, 0); } while (0)
; #define PG8_LDA(dst, b, h) do { _Pragma("unroll") for (int m = 0; m < 4; ++m) _Pragma("unroll") for (int k = 0; k < 2; ++k) dst[m][k] = *(const LAS bf16x8*)(lds + PG8_SA(b, h) + aoff + m * 2048 + k * 1024); } while (0)
; #define PG8_MMA(ai, bj, At, Bt) do { __builtin_amdgcn_s_setprio(1); _Pragma("unroll") for (int m = 0; m < 4; ++m) _Pragma("unroll") for (int n = 0; n < 2; ++n) _Pragma("unroll") for (int k = 0; k < 2; ++k) \
;         acc[ai][bj][m][n] = __builtin_amdgcn_mfma_f32_16x16x32_bf16(Bt[n][k], At[m][k], acc[ai][bj][m][n], 0, 0, 0); __builtin_amdgcn_s_setprio(0); } while (0)
; #define PG8_WAIT_V(n) asm volatile("s_waitcnt vmcnt(" #n ")" ::: "memory")
; #define PG8_WAIT_L(n) asm volatile("s_waitcnt lgkmcnt(" #n ")" ::: "memory")
; #define PG8_BAR __builtin_amdgcn_s_barrier()
; #define PG8_SCHED __builtin_amdgcn_sched_barrier(0)
; template <class Epi, class Sched, bool ALIGN_EPI = false, bool SP2 = false>
; __device__ __forceinline__ void gemm_phase(LAS unsigned char* lds, const Gemm g, const Sched& S, const Epi& E) {
;     ...
;             PG8_LDA(At, 1, 1); PG8_STAGE(PG8_SB(1, 0), b3, voffB); PG8_STAGE(PG8_SB(1, 1), b3 + hstep, voffB); PG8_STAGE(PG8_SA(1, 0), a3, voffA);
;             PG8_WAIT_V(8); PG8_WAIT_L(0); PG8_BAR; PG8_MMA(1, 0, At, B0); PG8_MMA(1, 1, At, B1); PG8_BAR; PG8_SCHED;
;     ...
;         if constexpr (ALIGN_EPI) { if (wr == 0) PG8_BAR; }
	s_add_i32 s14, s16, s6
	v_lshl_add_u64 v[234:235], v[234:235], 0, s[30:31]
	s_mov_b32 m0, s14
	ds_read_b128 v[184:187], v196 offset:49152
	ds_read_b128 v[190:193], v196 offset:50176
	ds_read_b128 v[198:201], v196 offset:51200
	ds_read_b128 v[202:205], v196 offset:52224
	ds_read_b128 v[218:221], v196 offset:53248
	ds_read_b128 v[222:225], v196 offset:54272
	ds_read_b128 v[226:229], v196 offset:55296
	ds_read_b128 v[230:233], v196 offset:56320
	global_load_lds_dwordx4 v[234:235], off
	s_add_i32 m0, s14, 0x2000
	s_add_u32 s14, s50, 0x40080
	v_lshl_add_u64 v[234:235], v[236:237], 0, s[30:31]
	s_addc_u32 s15, s51, 0
	s_add_i32 s16, s17, s6
	global_load_lds_dwordx4 v[234:235], off
	v_lshl_add_u64 v[234:235], s[14:15], 0, v[166:167]
	s_mov_b32 m0, s16
	s_nop 0
	global_load_lds_dwordx4 v[234:235], off
	v_lshl_add_u64 v[234:235], s[14:15], 0, v[162:163]
	s_add_i32 m0, s16, 0x2000
	s_nop 0
	global_load_lds_dwordx4 v[234:235], off
	v_lshl_add_u64 v[234:235], v[238:239], 0, s[30:31]
	s_mov_b32 m0, s11
	s_nop 0
	global_load_lds_dwordx4 v[234:235], off
	v_lshl_add_u64 v[234:235], v[240:241], 0, s[30:31]
	s_mov_b32 m0, s12
	s_nop 0
	global_load_lds_dwordx4 v[234:235], off
	s_waitcnt vmcnt(8)
	s_waitcnt lgkmcnt(0)
	s_barrier
	s_setprio 1
	s_waitcnt lgkmcnt(0)
	v_mfma_f32_16x16x32_bf16 v[60:63], v[128:131], v[184:187], v[60:63]
	v_mfma_f32_16x16x32_bf16 v[56:59], v[136:139], v[184:187], v[56:59]
	v_mfma_f32_16x16x32_bf16 v[44:47], v[128:131], v[198:201], v[44:47]
	v_mfma_f32_16x16x32_bf16 v[40:43], v[136:139], v[198:201], v[40:43]
	v_mfma_f32_16x16x32_bf16 v[28:31], v[128:131], v[218:221], v[28:31]
	v_mfma_f32_16x16x32_bf16 v[24:27], v[136:139], v[218:221], v[24:27]
	v_mfma_f32_16x16x32_bf16 v[12:15], v[128:131], v[226:229], v[12:15]
	v_mfma_f32_16x16x32_bf16 v[8:11], v[136:139], v[226:229], v[8:11]
	v_mfma_f32_16x16x32_bf16 v[60:63], v[132:135], v[190:193], v[60:63]
	v_mfma_f32_16x16x32_bf16 v[56:59], v[140:143], v[190:193], v[56:59]
	v_mfma_f32_16x16x32_bf16 v[44:47], v[132:135], v[202:205], v[44:47]
	v_mfma_f32_16x16x32_bf16 v[40:43], v[140:143], v[202:205], v[40:43]
	v_mfma_f32_16x16x32_bf16 v[28:31], v[132:135], v[222:225], v[28:31]
	v_mfma_f32_16x16x32_bf16 v[24:27], v[140:143], v[222:225], v[24:27]
	v_mfma_f32_16x16x32_bf16 v[12:15], v[132:135], v[230:233], v[12:15]
	v_mfma_f32_16x16x32_bf16 v[8:11], v[140:143], v[230:233], v[8:11]
	s_setprio 0
	s_setprio 1
	v_mfma_f32_16x16x32_bf16 v[52:55], v[144:147], v[184:187], v[52:55]
	v_mfma_f32_16x16x32_bf16 v[48:51], v[176:179], v[184:187], v[48:51]
	v_mfma_f32_16x16x32_bf16 v[36:39], v[144:147], v[198:201], v[36:39]
	v_mfma_f32_16x16x32_bf16 v[32:35], v[176:179], v[198:201], v[32:35]
	v_mfma_f32_16x16x32_bf16 v[20:23], v[144:147], v[218:221], v[20:23]
	v_mfma_f32_16x16x32_bf16 v[16:19], v[176:179], v[218:221], v[16:19]
	v_mfma_f32_16x16x32_bf16 v[4:7], v[144:147], v[226:229], v[4:7]
	v_mfma_f32_16x16x32_bf16 v[0:3], v[176:179], v[226:229], v[0:3]
	v_mfma_f32_16x16x32_bf16 v[52:55], v[148:151], v[190:193], v[52:55]
	v_mfma_f32_16x16x32_bf16 v[48:51], v[180:183], v[190:193], v[48:51]
	v_mfma_f32_16x16x32_bf16 v[36:39], v[148:151], v[202:205], v[36:39]
	v_mfma_f32_16x16x32_bf16 v[32:35], v[180:183], v[202:205], v[32:35]
	v_mfma_f32_16x16x32_bf16 v[20:23], v[148:151], v[222:225], v[20:23]
	v_mfma_f32_16x16x32_bf16 v[16:19], v[180:183], v[222:225], v[16:19]
	v_mfma_f32_16x16x32_bf16 v[4:7], v[148:151], v[230:233], v[4:7]
	v_mfma_f32_16x16x32_bf16 v[0:3], v[180:183], v[230:233], v[0:3]
	s_setprio 0
	s_barrier
	s_add_i32 s82, s82, 2
	s_add_u32 s46, s46, 0x100
	s_addc_u32 s47, s47, 0
	s_add_u32 s73, s73, 0x100
	s_addc_u32 s79, s79, 0
	s_cmp_gt_u32 s82, 13
	s_cbranch_scc0 .LBB0_534
	s_and_b64 vcc, exec, s[28:29]
	s_cbranch_vccz .LBB0_537
	s_barrier
; #define LAS __attribute__((address_space(3)))
; __device__ __forceinline__ void rows_rstd(const float* __restrict__ ssq, int row0, int fq, float (&rs)[2][4]) {
;     f32x4 pp[2][4];
; #pragma unroll
;     for (int ai = 0; ai < 2; ++ai)
; #pragma unroll
;         for (int m = 0; m < 4; ++m) pp[ai][m] = *(const f32x4*)(ssq + (size_t)(row0 + ai * HALF + m * 16) * 16 + 4 * fq);
; #pragma unroll
;     for (int ai = 0; ai < 2; ++ai)
; #pragma unroll
;         for (int m = 0; m < 4; ++m) { float s = (pp[ai][m][0] + pp[ai][m][1]) + (pp[ai][m][2] + pp[ai][m][3]); s += __shfl_xor(s, 16); s += __shfl_xor(s, 32); rs[ai][m] = rsqrtf(s * (1.0f / 1024.0f) + EPS); }
; }
; __device__ __forceinline__ void rows_rstd_cached(const float* __restrict__ ssq, int row0, int fq, float (&rs)[2][4], bool hit, LAS float* cache, int lrow0, bool writer) {
;     if (hit) {
; #pragma unroll
;         for (int ai = 0; ai < 2; ++ai)
; #pragma unroll
;             for (int m = 0; m < 4; ++m) rs[ai][m] = cache[lrow0 + ai * HALF + m * 16];
;     } else {
;         rows_rstd(ssq, row0, fq, rs);
;         if (writer) {
; #pragma unroll
;             for (int ai = 0; ai < 2; ++ai)
; #pragma unroll
;                 for (int m = 0; m < 4; ++m) cache[lrow0 + ai * HALF + m * 16] = rs[ai][m];
;         }
;     }
; }
;     __device__ __forceinline__ void operator()(const f32x4 (&acc)[2][2][4][2], const Unit& u, int wr, int wc, int fr, int fq) const {
;         const int row0 = u.pm * BM + wr * 64 + fr;
;         float rsv[2][4]; rows_rstd_cached(ssq, row0, fq, rsv, u.pm == cached_pm, rsc, wr * 64 + fr, wc == 0 && fq == 0); cached_pm = u.pm;
.LBB0_537:
	s_mov_b32 s101, 1
	v_lshl_add_u32 v184, s64, 8, v189
	v_or_b32_e32 v182, 16, v184
	v_or_b32_e32 v180, 32, v184
	v_or_b32_e32 v178, 48, v184
	v_readlane_b32 s72, v246, 51
	v_readlane_b32 s82, v246, 53
	s_cmp_lg_u32 s64, s70
	s_mov_b64 s[46:47], -1
	v_ashrrev_i32_e32 v185, 31, v184
	v_ashrrev_i32_e32 v183, 31, v182
	v_ashrrev_i32_e32 v181, 31, v180
	v_ashrrev_i32_e32 v179, 31, v178
	v_add_u32_e32 v186, 0x80, v184
	v_readlane_b32 s73, v246, 52
	v_readlane_b32 s83, v246, 54
	s_cbranch_scc0 .LBB0_541
	v_lshlrev_b64 v[128:129], 6, v[184:185]
	v_lshlrev_b64 v[130:131], 6, v[182:183]
	v_lshl_add_u64 v[128:129], v[170:171], 0, v[128:129]
	v_lshl_add_u64 v[130:131], v[170:171], 0, v[130:131]
	global_load_dwordx4 v[198:201], v[128:129], off
	global_load_dwordx4 v[202:205], v[130:131], off
	v_lshlrev_b64 v[130:131], 6, v[180:181]
	v_lshl_add_u64 v[130:131], v[170:171], 0, v[130:131]
	global_load_dwordx4 v[148:151], v[130:131], off
	v_lshlrev_b64 v[130:131], 6, v[178:179]
	v_lshl_add_u64 v[130:131], v[170:171], 0, v[130:131]
	global_load_dwordx4 v[144:147], v[130:131], off
	v_add_u32_e32 v176, 0x80, v184
	v_ashrrev_i32_e32 v177, 31, v176
	v_lshlrev_b64 v[130:131], 6, v[176:177]
	v_lshl_add_u64 v[130:131], v[170:171], 0, v[130:131]
	global_load_dwordx4 v[136:139], v[130:131], off
	v_add_co_u32_e32 v128, vcc, s35, v128
	v_and_b32_e32 v188, 64, v209
	s_nop 0
	v_addc_co_u32_e32 v129, vcc, 0, v129, vcc
	global_load_dwordx4 v[140:143], v[128:129], off offset:1024
	global_load_dwordx4 v[132:135], v[128:129], off offset:2048
	s_nop 0
	global_load_dwordx4 v[128:131], v[128:129], off offset:3072
	v_xor_b32_e32 v187, 16, v209
	v_add_u32_e32 v188, 64, v188
	v_cmp_lt_i32_e32 vcc, v187, v188
	s_mov_b32 s14, 0x358637bd
	s_waitcnt vmcnt(0)
	v_mov_b32_e32 v192, v198
	v_mov_b32_e32 v193, v202
	v_mov_b32_e32 v202, v199
	v_mov_b32_e32 v198, v200
	v_mov_b32_e32 v199, v204
	v_mov_b32_e32 v204, v201
	v_cndmask_b32_e32 v187, v209, v187, vcc
	v_pk_add_f32 v[192:193], v[192:193], v[202:203]
	v_pk_add_f32 v[198:199], v[198:199], v[204:205]
	v_lshlrev_b32_e32 v191, 2, v187
	v_pk_add_f32 v[192:193], v[192:193], v[198:199]
	ds_bpermute_b32 v198, v191, v192
	ds_bpermute_b32 v199, v191, v193
	v_xor_b32_e32 v187, 32, v209
	v_cmp_lt_i32_e32 vcc, v187, v188
	s_waitcnt lgkmcnt(0)
	v_pk_add_f32 v[192:193], v[192:193], v[198:199]
	v_cndmask_b32_e32 v187, v209, v187, vcc
	v_lshlrev_b32_e32 v187, 2, v187
	ds_bpermute_b32 v198, v187, v192
	ds_bpermute_b32 v199, v187, v193
	s_waitcnt lgkmcnt(0)
	v_pk_add_f32 v[198:199], v[192:193], v[198:199]
	v_mov_b64_e32 v[192:193], s[14:15]
	v_pk_fma_f32 v[198:199], v[198:199], s[34:35], v[192:193] op_sel_hi:[1,0,0]
	s_nop 0
	v_mul_f32_e32 v188, 0x4b800000, v198
	v_cmp_gt_f32_e64 s[46:47], s75, v198
	v_cmp_gt_f32_e32 vcc, s75, v199
	s_nop 0
	v_cndmask_b32_e64 v188, v198, v188, s[46:47]
	v_rsq_f32_e32 v198, v188
	v_mul_f32_e32 v188, 0x4b800000, v199
	v_cndmask_b32_e32 v188, v199, v188, vcc
	v_rsq_f32_e32 v199, v188
	s_nop 0
	v_pk_mul_f32 v[200:201], v[198:199], s[80:81] op_sel_hi:[1,0]
	s_nop 0
	v_cndmask_b32_e64 v190, v198, v200, s[46:47]
	v_cndmask_b32_e32 v188, v199, v201, vcc
	v_mov_b32_e32 v198, v148
	v_mov_b32_e32 v199, v144
	v_mov_b32_e32 v144, v149
	v_mov_b32_e32 v148, v150
	v_mov_b32_e32 v149, v146
	v_mov_b32_e32 v146, v151
	v_pk_add_f32 v[144:145], v[198:199], v[144:145]
	v_pk_add_f32 v[146:147], v[148:149], v[146:147]
	v_mov_b32_e32 v148, v136
	v_pk_add_f32 v[144:145], v[144:145], v[146:147]
	ds_bpermute_b32 v146, v191, v144
	ds_bpermute_b32 v147, v191, v145
	v_mov_b32_e32 v149, v140
	v_mov_b32_e32 v140, v137
	v_pk_add_f32 v[136:137], v[148:149], v[140:141]
	v_mov_b32_e32 v140, v138
	s_waitcnt lgkmcnt(0)
	v_pk_add_f32 v[144:145], v[144:145], v[146:147]
	v_mov_b32_e32 v141, v142
	v_mov_b32_e32 v142, v139
	ds_bpermute_b32 v146, v187, v144
	ds_bpermute_b32 v147, v187, v145
	v_pk_add_f32 v[138:139], v[140:141], v[142:143]
	v_mov_b32_e32 v140, v132
	v_pk_add_f32 v[136:137], v[136:137], v[138:139]
	ds_bpermute_b32 v138, v191, v136
	ds_bpermute_b32 v139, v191, v137
	s_waitcnt lgkmcnt(2)
	v_pk_add_f32 v[144:145], v[144:145], v[146:147]
	v_mov_b32_e32 v141, v128
	v_pk_fma_f32 v[144:145], v[144:145], s[34:35], v[192:193] op_sel_hi:[1,0,0]
	v_mov_b32_e32 v128, v133
	v_mul_f32_e32 v146, 0x4b800000, v144
	v_cmp_gt_f32_e64 s[46:47], s75, v144
	s_waitcnt lgkmcnt(0)
	v_pk_add_f32 v[136:137], v[136:137], v[138:139]
	v_mov_b32_e32 v132, v134
	v_mov_b32_e32 v133, v130
	v_mov_b32_e32 v130, v135
	v_cmp_gt_f32_e32 vcc, s75, v145
	v_cndmask_b32_e64 v144, v144, v146, s[46:47]
	v_mul_f32_e32 v146, 0x4b800000, v145
	ds_bpermute_b32 v138, v187, v136
	ds_bpermute_b32 v139, v187, v137
	v_pk_add_f32 v[128:129], v[140:141], v[128:129]
	v_pk_add_f32 v[130:131], v[132:133], v[130:131]
	v_cndmask_b32_e32 v145, v145, v146, vcc
	v_pk_add_f32 v[128:129], v[128:129], v[130:131]
	v_rsq_f32_e32 v144, v144
	v_rsq_f32_e32 v145, v145
	ds_bpermute_b32 v130, v191, v128
	ds_bpermute_b32 v131, v191, v129
	s_waitcnt lgkmcnt(2)
	v_pk_add_f32 v[136:137], v[136:137], v[138:139]
	v_pk_mul_f32 v[146:147], v[144:145], s[80:81] op_sel_hi:[1,0]
	v_pk_fma_f32 v[136:137], v[136:137], s[34:35], v[192:193] op_sel_hi:[1,0,0]
	v_cndmask_b32_e64 v146, v144, v146, s[46:47]
	v_mul_f32_e32 v138, 0x4b800000, v136
	v_cmp_gt_f32_e64 s[46:47], s75, v136
	s_waitcnt lgkmcnt(0)
	v_pk_add_f32 v[128:129], v[128:129], v[130:131]
	v_cndmask_b32_e32 v144, v145, v147, vcc
	v_cmp_gt_f32_e32 vcc, s75, v137
	v_cndmask_b32_e64 v136, v136, v138, s[46:47]
	v_mul_f32_e32 v138, 0x4b800000, v137
	ds_bpermute_b32 v130, v187, v128
	ds_bpermute_b32 v131, v187, v129
	v_cndmask_b32_e32 v137, v137, v138, vcc
	v_rsq_f32_e32 v136, v136
	v_rsq_f32_e32 v137, v137
	s_waitcnt lgkmcnt(0)
	v_pk_add_f32 v[128:129], v[128:129], v[130:131]
	s_nop 0
	v_pk_fma_f32 v[128:129], v[128:129], s[34:35], v[192:193] op_sel_hi:[1,0,0]
	v_pk_mul_f32 v[138:139], v[136:137], s[80:81] op_sel_hi:[1,0]
	v_mul_f32_e32 v130, 0x4b800000, v128
	v_cndmask_b32_e64 v138, v136, v138, s[46:47]
	v_cmp_gt_f32_e64 s[46:47], s75, v128
	v_cndmask_b32_e32 v136, v137, v139, vcc
	v_cmp_gt_f32_e32 vcc, s75, v129
	v_cndmask_b32_e64 v128, v128, v130, s[46:47]
	v_mul_f32_e32 v130, 0x4b800000, v129
	v_cndmask_b32_e32 v129, v129, v130, vcc
	v_rsq_f32_e32 v128, v128
	v_rsq_f32_e32 v129, v129
	s_nop 0
	v_pk_mul_f32 v[130:131], v[128:129], s[80:81] op_sel_hi:[1,0]
	s_nop 0
	v_cndmask_b32_e64 v130, v128, v130, s[46:47]
	v_cndmask_b32_e32 v128, v129, v131, vcc
	s_and_saveexec_b64 s[46:47], s[42:43]
	s_cbranch_execz .LBB0_540
	ds_write2_b32 v195, v190, v188 offset1:16
	ds_write2_b32 v195, v146, v144 offset0:32 offset1:48
	ds_write2_b32 v195, v138, v136 offset0:128 offset1:144
	ds_write2_b32 v195, v130, v128 offset0:160 offset1:176

; #define PG8_STAGE(bufoff, gbase, voff) do { _Pragma("unroll") for (int _i = 0; _i < 2; ++_i) \
;         __builtin_amdgcn_global_load_lds((const unsigned*)((const char*)(gbase) + (voff)[_i]), (LAS unsigned*)(lds + (bufoff) + ldsw + _i * 8192), 16, 0, 0); } while (0)
; #define PG8_WAIT_V(n) asm volatile("s_waitcnt vmcnt(" #n ")" ::: "memory")
; #define PG8_BAR __builtin_amdgcn_s_barrier()
; template <class Epi, class Sched, bool ALIGN_EPI = false, bool SP2 = false>
; __device__ __forceinline__ void gemm_phase(LAS unsigned char* lds, const Gemm g, const Sched& S, const Epi& E) {
;     ...
;     for (int i = 0; i < 2; ++i) { int R, C; stage_rc(tid * 16 + i * 8192, R, C); const int Rb = Epi::PERM ? ((R & ~31) + perm32(R & 31)) : R;
;         voffA[i] = (unsigned)(R * K + C) * 2u; voffB[i] = (unsigned)(Rb * K + C) * 2u; }
;     const size_t kstep = (size_t)(BK * 2);
;     const size_t hstep = (size_t)HALF * K * 2;
;     const size_t tstep = 2 * hstep;
;     const unsigned ldsw = (unsigned)wid * 1024u;
;     const int aoff = lds_byte(wr * 64 + fr, fq * 8), boff = lds_byte(wc * 32 + fr, fq * 8);
;     ...
;     const char* cA = (const char*)g.A + (size_t)cur.pm * tstep; const char* cB = (const char*)g.Bt + (size_t)cur.pn * tstep;
;     S.a_ready(cur);
;     if constexpr (SP2) {
;         PG8_STAGE(PG8_SB(0, 0), cB, voffB); PG8_STAGE(PG8_SB(0, 1), cB + hstep, voffB); PG8_STAGE(PG8_SA(0, 0), cA, voffA); PG8_STAGE(PG8_SA(0, 1), cA + hstep, voffA);
;         if (wr == 1) PG8_BAR;
;         PG8_WAIT_V(2); PG8_BAR;
;         PG8_STAGE(PG8_SB(1, 0), cB + kstep, voffB); PG8_STAGE(PG8_SA(1, 0), cA + kstep, voffA); PG8_STAGE(PG8_SB(1, 1), cB + hstep + kstep, voffB);
.LBB0_599:
	s_or_b64 exec, exec, s[26:27]
	v_mov_b32_e32 v6, v206
	s_waitcnt lgkmcnt(0)
	s_barrier
	s_mov_b32 s101, 0
	s_and_b64 vcc, exec, s[98:99]
	v_readfirstlane_b32 s26, v6
	s_cbranch_vccnz .LBB0_639
	v_lshlrev_b32_e32 v3, 4, v6
	v_add_u32_e32 v1, 0x2000, v3
	v_ashrrev_i32_e32 v0, 31, v1
	v_lshrrev_b32_e32 v0, 22, v0
	v_add_u32_e32 v0, v1, v0
	v_ashrrev_i32_e32 v0, 10, v0
	v_mul_i32_i24_e32 v2, 0x400, v0
	v_sub_u32_e32 v1, v1, v2
	v_lshrrev_b32_e32 v2, 4, v1
	v_bitop3_b32 v2, v2, v1, 32 bitop3:0x6c
	v_ashrrev_i32_e32 v1, 31, v2
	v_lshrrev_b32_e32 v1, 26, v1
	v_add_u32_e32 v4, v2, v1
	v_lshlrev_b32_e32 v5, 3, v0
	v_ashrrev_i32_e32 v1, 6, v4
	v_and_b32_e32 v5, -16, v5
	v_add_u32_e32 v5, v1, v5
	v_and_b32_e32 v7, 3, v1
	s_mov_b32 s7, 0x7ffe0
	v_lshrrev_b32_e32 v8, 2, v5
	v_lshlrev_b32_e32 v9, 1, v5
	v_and_b32_e32 v4, 0xc0, v4
	v_and_or_b32 v7, v5, s7, v7
	v_and_b32_e32 v8, 4, v8
	v_and_b32_e32 v9, 24, v9
	v_sub_u32_e32 v2, v2, v4
	v_or3_b32 v7, v7, v8, v9
	v_lshlrev_b32_e32 v8, 5, v0
	v_ashrrev_i16_sdwa v2, v207, sext(v2) dst_sel:DWORD dst_unused:UNUSED_PAD src0_sel:DWORD src1_sel:BYTE_0
	v_and_b32_e32 v8, 32, v8
	v_bfe_i32 v2, v2, 0, 16
	v_add_lshl_u32 v4, v8, v2, 1
	v_lshl_add_u32 v144, v7, 13, v4
	v_lshl_add_u32 v146, v5, 13, v4
	v_bfe_i32 v4, v6, 27, 1
	v_lshrrev_b32_e32 v4, 22, v4
	v_add_u32_e32 v4, v3, v4
	v_and_b32_e32 v4, 0xfffffc00, v4
	v_sub_u32_e32 v3, v3, v4
	v_lshrrev_b32_e32 v4, 4, v3
	v_bitop3_b32 v5, v4, v3, 32 bitop3:0x6c
	v_ashrrev_i32_e32 v4, 31, v6
	v_lshrrev_b32_e32 v4, 26, v4
	v_ashrrev_i32_e32 v3, 31, v5
	v_add_u32_e32 v4, v6, v4
	v_lshrrev_b32_e32 v3, 26, v3
	v_ashrrev_i32_e32 v4, 6, v4
	v_add_u32_e32 v7, v5, v3
	v_lshlrev_b32_e32 v8, 3, v4
	v_ashrrev_i32_e32 v3, 6, v7
	v_and_b32_e32 v8, -16, v8
	v_readlane_b32 s4, v246, 4
	v_add_u32_e32 v8, v3, v8
	s_add_u32 s4, s4, s24
	v_readlane_b32 s5, v246, 5
	v_and_b32_e32 v9, 3, v3
	v_lshrrev_b32_e32 v10, 2, v8
	v_lshlrev_b32_e32 v11, 1, v8
	v_and_b32_e32 v7, 0xc0, v7
	s_addc_u32 s5, s5, s25
	s_ashr_i32 s11, s26, 6
	v_and_or_b32 v9, v8, s7, v9
	v_and_b32_e32 v10, 4, v10
	v_and_b32_e32 v11, 24, v11
	v_sub_u32_e32 v5, v5, v7
	s_ashr_i32 s12, s26, 8
	s_lshl_b32 s6, s11, 10
	v_or3_b32 v9, v9, v10, v11
	v_lshlrev_b32_e32 v10, 5, v4
	v_ashrrev_i16_sdwa v5, v207, sext(v5) dst_sel:DWORD dst_unused:UNUSED_PAD src0_sel:DWORD src1_sel:BYTE_0
	v_readlane_b32 s8, v246, 16
	v_and_b32_e32 v10, 32, v10
	v_bfe_i32 v5, v5, 0, 16
	v_readlane_b32 s9, v246, 17
	s_add_u32 s46, s4, s8
	v_add_lshl_u32 v7, v10, v5, 1
	s_addc_u32 s47, s5, s9
	s_add_i32 s7, s6, 0
	v_lshl_add_u32 v152, v9, 13, v7
	s_add_i32 m0, s7, 0x10000
	v_readlane_b32 s14, v246, 18
	global_load_lds_dwordx4 v152, s[46:47]
	s_add_i32 m0, s7, 0x12000
	s_add_u32 s8, s46, 0x100000
	global_load_lds_dwordx4 v144, s[46:47]
	s_addc_u32 s9, s47, 0
	s_add_i32 m0, s7, 0x14000
	v_lshl_add_u32 v148, v8, 13, v7
	global_load_lds_dwordx4 v152, s[8:9]
	s_add_i32 m0, s7, 0x16000
	v_readlane_b32 s15, v246, 19
	global_load_lds_dwordx4 v144, s[8:9]
	s_mov_b32 m0, s7
	s_add_i32 s8, s7, 0x2000
	s_add_i32 s9, s7, 0x4000
	s_nop 0
	global_load_lds_dwordx4 v148, s[14:15]
	s_mov_b32 m0, s8
	s_add_i32 s10, s7, 0x6000
	global_load_lds_dwordx4 v146, s[14:15]
	v_readlane_b32 s14, v246, 20
	s_mov_b32 m0, s9
	v_readlane_b32 s15, v246, 21
	s_cmp_eq_u32 s12, 1
	s_cselect_b64 s[24:25], -1, 0
	s_cmp_lg_u32 s12, 1
	s_nop 1
	global_load_lds_dwordx4 v148, s[14:15]
	s_mov_b32 m0, s10
	s_nop 0
	global_load_lds_dwordx4 v146, s[14:15]
	s_cbranch_scc1 .LBB0_602
	s_barrier

; #define PG8_STAGE(bufoff, gbase, voff) do { _Pragma("unroll") for (int _i = 0; _i < 2; ++_i) \
;         __builtin_amdgcn_global_load_lds((const unsigned*)((const char*)(gbase) + (voff)[_i]), (LAS unsigned*)(lds + (bufoff) + ldsw + _i * 8192), 16, 0, 0); } while (0)
; #define PG8_LDA(dst, b, h) do { _Pragma("unroll") for (int m = 0; m < 4; ++m) _Pragma("unroll") for (int k = 0; k < 2; ++k) dst[m][k] = *(const LAS bf16x8*)(lds + PG8_SA(b, h) + aoff + m * 2048 + k * 1024); } while (0)
; #define PG8_LDB(dst, b, h) do { _Pragma("unroll") for (int n = 0; n < 2; ++n) _Pragma("unroll") for (int k = 0; k < 2; ++k) dst[n][k] = *(const LAS bf16x8*)(lds + PG8_SB(b, h) + boff + n * 2048 + k * 1024); } while (0)
; #define PG8_MMA(ai, bj, At, Bt) do { __builtin_amdgcn_s_setprio(1); _Pragma("unroll") for (int m = 0; m < 4; ++m) _Pragma("unroll") for (int n = 0; n < 2; ++n) _Pragma("unroll") for (int k = 0; k < 2; ++k) \
;         acc[ai][bj][m][n] = __builtin_amdgcn_mfma_f32_16x16x32_bf16(Bt[n][k], At[m][k], acc[ai][bj][m][n], 0, 0, 0); __builtin_amdgcn_s_setprio(0); } while (0)
; #define PG8_WAIT_V(n) asm volatile("s_waitcnt vmcnt(" #n ")" ::: "memory")
; #define PG8_WAIT_L(n) asm volatile("s_waitcnt lgkmcnt(" #n ")" ::: "memory")
; #define PG8_BAR __builtin_amdgcn_s_barrier()
; #define PG8_SCHED __builtin_amdgcn_sched_barrier(0)
; template <class Epi, class Sched, bool ALIGN_EPI = false, bool SP2 = false>
; __device__ __forceinline__ void gemm_phase(LAS unsigned char* lds, const Gemm g, const Sched& S, const Epi& E) {
;     ...
;             PG8_LDB(B0, 0, 0); PG8_LDB(B1, 0, 1); PG8_SCHED; PG8_LDA(At, 0, 0); PG8_STAGE(PG8_SA(1, 1), a1 + hstep, voffA);
;             PG8_WAIT_V(8); PG8_WAIT_L(0); PG8_BAR; PG8_MMA(0, 0, At, B0); PG8_MMA(0, 1, At, B1); PG8_BAR; PG8_SCHED;
;             PG8_LDA(At, 0, 1); PG8_STAGE(PG8_SB(0, 0), b2, voffB); PG8_STAGE(PG8_SB(0, 1), b2 + hstep, voffB); PG8_STAGE(PG8_SA(0, 0), a2, voffA);
;             PG8_WAIT_V(8); PG8_WAIT_L(0); PG8_BAR; PG8_MMA(1, 0, At, B0); PG8_MMA(1, 1, At, B1); PG8_BAR; PG8_SCHED;
.LBB0_612:
	s_add_u32 s14, s42, 0xfff00080
	s_addc_u32 s15, s43, -1
	s_add_i32 s16, 0, 0x10000
	s_cmp_eq_u32 s71, 60
	s_cselect_b32 s49, s37, s15
	s_cselect_b32 s48, s54, s14
	s_cselect_b32 s47, s29, s65
	s_cselect_b32 s46, s55, s64
	s_add_i32 s17, 0, 0x14000
	v_add_u32_e32 v140, s16, v175
	v_add_u32_e32 v172, s17, v175
	ds_read_b128 v[128:131], v140
	ds_read_b128 v[132:135], v140 offset:1024
	ds_read_b128 v[136:139], v140 offset:2048
	ds_read_b128 v[140:143], v140 offset:3072
	ds_read_b128 v[164:167], v172
	ds_read_b128 v[168:171], v172 offset:1024
	ds_read_b128 v[180:183], v172 offset:2048
	ds_read_b128 v[184:187], v172 offset:3072
	v_lshl_add_u64 v[172:173], s[42:43], 0, v[150:151]
	s_add_i32 m0, s7, 0xc000
	ds_read_b128 v[188:191], v178
	ds_read_b128 v[192:195], v178 offset:1024
	ds_read_b128 v[196:199], v178 offset:2048
	ds_read_b128 v[200:203], v178 offset:3072
	ds_read_b128 v[218:221], v178 offset:4096
	ds_read_b128 v[222:225], v178 offset:5120
	ds_read_b128 v[226:229], v178 offset:6144
	ds_read_b128 v[230:233], v178 offset:7168
	global_load_lds_dwordx4 v[172:173], off
	v_lshl_add_u64 v[172:173], s[42:43], 0, v[162:163]
	s_add_i32 m0, s7, 0xe000
	s_nop 0
	global_load_lds_dwordx4 v[172:173], off
	s_waitcnt vmcnt(24)
	s_cmp_eq_u32 s101, 1
	s_cbranch_scc1 .Lrlx_5
	s_waitcnt vmcnt(8)
.Lrlx_5:
	s_waitcnt lgkmcnt(0)
	s_barrier
	s_setprio 1
	s_waitcnt lgkmcnt(0)
	v_mfma_f32_16x16x32_bf16 v[124:127], v[128:131], v[188:191], v[124:127]
	v_mfma_f32_16x16x32_bf16 v[120:123], v[136:139], v[188:191], v[120:123]
	v_mfma_f32_16x16x32_bf16 v[112:115], v[128:131], v[196:199], v[112:115]
	v_mfma_f32_16x16x32_bf16 v[104:107], v[136:139], v[196:199], v[104:107]
	v_mfma_f32_16x16x32_bf16 v[92:95], v[128:131], v[218:221], v[92:95]
	v_mfma_f32_16x16x32_bf16 v[88:91], v[136:139], v[218:221], v[88:91]
	v_mfma_f32_16x16x32_bf16 v[76:79], v[128:131], v[226:229], v[76:79]
	v_mfma_f32_16x16x32_bf16 v[72:75], v[136:139], v[226:229], v[72:75]
	v_mfma_f32_16x16x32_bf16 v[124:127], v[132:135], v[192:195], v[124:127]
	v_mfma_f32_16x16x32_bf16 v[120:123], v[140:143], v[192:195], v[120:123]
	v_mfma_f32_16x16x32_bf16 v[112:115], v[132:135], v[200:203], v[112:115]
	v_mfma_f32_16x16x32_bf16 v[104:107], v[140:143], v[200:203], v[104:107]
	v_mfma_f32_16x16x32_bf16 v[92:95], v[132:135], v[222:225], v[92:95]
	v_mfma_f32_16x16x32_bf16 v[88:91], v[140:143], v[222:225], v[88:91]
	v_mfma_f32_16x16x32_bf16 v[76:79], v[132:135], v[230:233], v[76:79]
	v_mfma_f32_16x16x32_bf16 v[72:75], v[140:143], v[230:233], v[72:75]
	s_setprio 0
	s_setprio 1
	v_mfma_f32_16x16x32_bf16 v[116:119], v[164:167], v[188:191], v[116:119]
	v_mfma_f32_16x16x32_bf16 v[108:111], v[180:183], v[188:191], v[108:111]
	v_mfma_f32_16x16x32_bf16 v[100:103], v[164:167], v[196:199], v[100:103]
	v_mfma_f32_16x16x32_bf16 v[96:99], v[180:183], v[196:199], v[96:99]
	v_mfma_f32_16x16x32_bf16 v[84:87], v[164:167], v[218:221], v[84:87]
	v_mfma_f32_16x16x32_bf16 v[80:83], v[180:183], v[218:221], v[80:83]
	v_mfma_f32_16x16x32_bf16 v[68:71], v[164:167], v[226:229], v[68:71]
	v_mfma_f32_16x16x32_bf16 v[64:67], v[180:183], v[226:229], v[64:67]
	v_mfma_f32_16x16x32_bf16 v[116:119], v[168:171], v[192:195], v[116:119]
	v_mfma_f32_16x16x32_bf16 v[108:111], v[184:187], v[192:195], v[108:111]
	v_mfma_f32_16x16x32_bf16 v[100:103], v[168:171], v[200:203], v[100:103]
	v_mfma_f32_16x16x32_bf16 v[96:99], v[184:187], v[200:203], v[96:99]
	v_mfma_f32_16x16x32_bf16 v[84:87], v[168:171], v[222:225], v[84:87]
	v_mfma_f32_16x16x32_bf16 v[80:83], v[184:187], v[222:225], v[80:83]
	v_mfma_f32_16x16x32_bf16 v[68:71], v[168:171], v[230:233], v[68:71]
	v_mfma_f32_16x16x32_bf16 v[64:67], v[184:187], v[230:233], v[64:67]
	s_setprio 0
	s_barrier
	s_add_i32 s14, s16, s6
	v_lshl_add_u64 v[172:173], s[46:47], 0, v[152:153]
	s_mov_b32 m0, s14
	ds_read_b128 v[188:191], v178 offset:16384
	ds_read_b128 v[192:195], v178 offset:17408
	ds_read_b128 v[196:199], v178 offset:18432
	ds_read_b128 v[200:203], v178 offset:19456
	ds_read_b128 v[218:221], v178 offset:20480
	ds_read_b128 v[222:225], v178 offset:21504
	ds_read_b128 v[226:229], v178 offset:22528
	ds_read_b128 v[230:233], v178 offset:23552
	global_load_lds_dwordx4 v[172:173], off
	s_add_i32 m0, s14, 0x2000
	s_add_u32 s14, s46, 0x100000
	v_lshl_add_u64 v[204:205], s[46:47], 0, v[144:145]
	s_addc_u32 s15, s47, 0
	s_add_i32 s16, s17, s6
	global_load_lds_dwordx4 v[204:205], off
	v_lshl_add_u64 v[234:235], s[14:15], 0, v[152:153]
	s_mov_b32 m0, s16
	v_lshl_add_u64 v[236:237], s[48:49], 0, v[146:147]
	global_load_lds_dwordx4 v[234:235], off
	v_lshl_add_u64 v[234:235], s[14:15], 0, v[144:145]
	s_add_i32 m0, s16, 0x2000
	s_nop 0
	global_load_lds_dwordx4 v[234:235], off
	v_lshl_add_u64 v[234:235], s[48:49], 0, v[148:149]
	s_mov_b32 m0, s7
	s_nop 0
	global_load_lds_dwordx4 v[234:235], off
	s_mov_b32 m0, s8
	s_nop 0
	global_load_lds_dwordx4 v[236:237], off
	s_waitcnt vmcnt(24)
	s_cmp_eq_u32 s101, 1
	s_cbranch_scc1 .Lrlx_6
	s_waitcnt vmcnt(8)
; #define PG8_STAGE(bufoff, gbase, voff) do { _Pragma("unroll") for (int _i = 0; _i < 2; ++_i) \
;         __builtin_amdgcn_global_load_lds((const unsigned*)((const char*)(gbase) + (voff)[_i]), (LAS unsigned*)(lds + (bufoff) + ldsw + _i * 8192), 16, 0, 0); } while (0)
; #define PG8_LDA(dst, b, h) do { _Pragma("unroll") for (int m = 0; m < 4; ++m) _Pragma("unroll") for (int k = 0; k < 2; ++k) dst[m][k] = *(const LAS bf16x8*)(lds + PG8_SA(b, h) + aoff + m * 2048 + k * 1024); } while (0)
; #define PG8_LDB(dst, b, h) do { _Pragma("unroll") for (int n = 0; n < 2; ++n) _Pragma("unroll") for (int k = 0; k < 2; ++k) dst[n][k] = *(const LAS bf16x8*)(lds + PG8_SB(b, h) + boff + n * 2048 + k * 1024); } while (0)
; #define PG8_MMA(ai, bj, At, Bt) do { __builtin_amdgcn_s_setprio(1); _Pragma("unroll") for (int m = 0; m < 4; ++m) _Pragma("unroll") for (int n = 0; n < 2; ++n) _Pragma("unroll") for (int k = 0; k < 2; ++k) \
;         acc[ai][bj][m][n] = __builtin_amdgcn_mfma_f32_16x16x32_bf16(Bt[n][k], At[m][k], acc[ai][bj][m][n], 0, 0, 0); __builtin_amdgcn_s_setprio(0); } while (0)
; #define PG8_WAIT_V(n) asm volatile("s_waitcnt vmcnt(" #n ")" ::: "memory")
; #define PG8_WAIT_L(n) asm volatile("s_waitcnt lgkmcnt(" #n ")" ::: "memory")
; #define PG8_BAR __builtin_amdgcn_s_barrier()
; #define PG8_SCHED __builtin_amdgcn_sched_barrier(0)
; template <class Epi, class Sched, bool ALIGN_EPI = false, bool SP2 = false>
; __device__ __forceinline__ void gemm_phase(LAS unsigned char* lds, const Gemm g, const Sched& S, const Epi& E) {
;     ...
;             PG8_WAIT_V(8); PG8_WAIT_L(0); PG8_BAR; PG8_MMA(1, 0, At, B0); PG8_MMA(1, 1, At, B1); PG8_BAR; PG8_SCHED;
;             PG8_LDB(B0, 1, 0); PG8_LDB(B1, 1, 1); PG8_SCHED; PG8_LDA(At, 1, 0); PG8_STAGE(PG8_SA(0, 1), a2 + hstep, voffA);
;             PG8_WAIT_V(8); PG8_WAIT_L(0); PG8_BAR; PG8_MMA(0, 0, At, B0); PG8_MMA(0, 1, At, B1); PG8_BAR; PG8_SCHED;
.Lrlx_6:
	s_mov_b32 s101, 0
	s_waitcnt lgkmcnt(0)
	s_barrier
	s_setprio 1
	s_waitcnt lgkmcnt(0)
	v_mfma_f32_16x16x32_bf16 v[60:63], v[128:131], v[188:191], v[60:63]
	v_mfma_f32_16x16x32_bf16 v[56:59], v[136:139], v[188:191], v[56:59]
	v_mfma_f32_16x16x32_bf16 v[44:47], v[128:131], v[196:199], v[44:47]
	v_mfma_f32_16x16x32_bf16 v[40:43], v[136:139], v[196:199], v[40:43]
	v_mfma_f32_16x16x32_bf16 v[28:31], v[128:131], v[218:221], v[28:31]
	v_mfma_f32_16x16x32_bf16 v[24:27], v[136:139], v[218:221], v[24:27]
	v_mfma_f32_16x16x32_bf16 v[12:15], v[128:131], v[226:229], v[12:15]
	v_mfma_f32_16x16x32_bf16 v[8:11], v[136:139], v[226:229], v[8:11]
	v_mfma_f32_16x16x32_bf16 v[60:63], v[132:135], v[192:195], v[60:63]
	v_mfma_f32_16x16x32_bf16 v[56:59], v[140:143], v[192:195], v[56:59]
	v_mfma_f32_16x16x32_bf16 v[44:47], v[132:135], v[200:203], v[44:47]
	v_mfma_f32_16x16x32_bf16 v[40:43], v[140:143], v[200:203], v[40:43]
	v_mfma_f32_16x16x32_bf16 v[28:31], v[132:135], v[222:225], v[28:31]
	v_mfma_f32_16x16x32_bf16 v[24:27], v[140:143], v[222:225], v[24:27]
	v_mfma_f32_16x16x32_bf16 v[12:15], v[132:135], v[230:233], v[12:15]
	v_mfma_f32_16x16x32_bf16 v[8:11], v[140:143], v[230:233], v[8:11]
	s_setprio 0
	s_setprio 1
	v_mfma_f32_16x16x32_bf16 v[52:55], v[164:167], v[188:191], v[52:55]
	v_mfma_f32_16x16x32_bf16 v[48:51], v[180:183], v[188:191], v[48:51]
	v_mfma_f32_16x16x32_bf16 v[36:39], v[164:167], v[196:199], v[36:39]
	v_mfma_f32_16x16x32_bf16 v[32:35], v[180:183], v[196:199], v[32:35]
	v_mfma_f32_16x16x32_bf16 v[20:23], v[164:167], v[218:221], v[20:23]
	v_mfma_f32_16x16x32_bf16 v[16:19], v[180:183], v[218:221], v[16:19]
	v_mfma_f32_16x16x32_bf16 v[4:7], v[164:167], v[226:229], v[4:7]
	v_mfma_f32_16x16x32_bf16 v[0:3], v[180:183], v[226:229], v[0:3]
	v_mfma_f32_16x16x32_bf16 v[52:55], v[168:171], v[192:195], v[52:55]
	v_mfma_f32_16x16x32_bf16 v[48:51], v[184:187], v[192:195], v[48:51]
	v_mfma_f32_16x16x32_bf16 v[36:39], v[168:171], v[200:203], v[36:39]
	v_mfma_f32_16x16x32_bf16 v[32:35], v[184:187], v[200:203], v[32:35]
	v_mfma_f32_16x16x32_bf16 v[20:23], v[168:171], v[222:225], v[20:23]
	v_mfma_f32_16x16x32_bf16 v[16:19], v[184:187], v[222:225], v[16:19]
	v_mfma_f32_16x16x32_bf16 v[4:7], v[168:171], v[230:233], v[4:7]
	v_mfma_f32_16x16x32_bf16 v[0:3], v[184:187], v[230:233], v[0:3]
	s_setprio 0
	s_barrier
	s_add_i32 s16, 0, 0x18000
	s_add_i32 s17, 0, 0x1c000
	v_add_u32_e32 v140, s16, v175
	v_add_u32_e32 v179, s17, v175
	ds_read_b128 v[128:131], v140
	ds_read_b128 v[132:135], v140 offset:1024
	ds_read_b128 v[136:139], v140 offset:2048
	ds_read_b128 v[140:143], v140 offset:3072
	ds_read_b128 v[164:167], v179
	ds_read_b128 v[168:171], v179 offset:1024
	ds_read_b128 v[180:183], v179 offset:2048
	ds_read_b128 v[184:187], v179 offset:3072
	s_add_u32 s14, s48, 0x100000
	s_addc_u32 s15, s49, 0
	s_mov_b32 m0, s9
	v_lshl_add_u64 v[238:239], s[14:15], 0, v[148:149]
	ds_read_b128 v[188:191], v178 offset:32768
	ds_read_b128 v[192:195], v178 offset:33792
	ds_read_b128 v[196:199], v178 offset:34816
	ds_read_b128 v[200:203], v178 offset:35840
	ds_read_b128 v[218:221], v178 offset:36864
	ds_read_b128 v[222:225], v178 offset:37888
	ds_read_b128 v[226:229], v178 offset:38912
	ds_read_b128 v[230:233], v178 offset:39936
	global_load_lds_dwordx4 v[238:239], off
	v_lshl_add_u64 v[238:239], s[14:15], 0, v[146:147]
	s_mov_b32 m0, s10
	s_nop 0
	global_load_lds_dwordx4 v[238:239], off
	s_waitcnt vmcnt(8)
	s_waitcnt lgkmcnt(0)
	s_barrier
	s_setprio 1
	s_waitcnt lgkmcnt(0)
	v_mfma_f32_16x16x32_bf16 v[124:127], v[128:131], v[188:191], v[124:127]
	v_mfma_f32_16x16x32_bf16 v[120:123], v[136:139], v[188:191], v[120:123]
	v_mfma_f32_16x16x32_bf16 v[112:115], v[128:131], v[196:199], v[112:115]
	v_mfma_f32_16x16x32_bf16 v[104:107], v[136:139], v[196:199], v[104:107]
	v_mfma_f32_16x16x32_bf16 v[92:95], v[128:131], v[218:221], v[92:95]
	v_mfma_f32_16x16x32_bf16 v[88:91], v[136:139], v[218:221], v[88:91]
	v_mfma_f32_16x16x32_bf16 v[76:79], v[128:131], v[226:229], v[76:79]
	v_mfma_f32_16x16x32_bf16 v[72:75], v[136:139], v[226:229], v[72:75]
	v_mfma_f32_16x16x32_bf16 v[124:127], v[132:135], v[192:195], v[124:127]
	v_mfma_f32_16x16x32_bf16 v[120:123], v[140:143], v[192:195], v[120:123]
	v_mfma_f32_16x16x32_bf16 v[112:115], v[132:135], v[200:203], v[112:115]
	v_mfma_f32_16x16x32_bf16 v[104:107], v[140:143], v[200:203], v[104:107]
	v_mfma_f32_16x16x32_bf16 v[92:95], v[132:135], v[222:225], v[92:95]
	v_mfma_f32_16x16x32_bf16 v[88:91], v[140:143], v[222:225], v[88:91]
	v_mfma_f32_16x16x32_bf16 v[76:79], v[132:135], v[230:233], v[76:79]
	v_mfma_f32_16x16x32_bf16 v[72:75], v[140:143], v[230:233], v[72:75]
	s_setprio 0
	s_setprio 1
	v_mfma_f32_16x16x32_bf16 v[116:119], v[164:167], v[188:191], v[116:119]
	v_mfma_f32_16x16x32_bf16 v[108:111], v[180:183], v[188:191], v[108:111]
	v_mfma_f32_16x16x32_bf16 v[100:103], v[164:167], v[196:199], v[100:103]
	v_mfma_f32_16x16x32_bf16 v[96:99], v[180:183], v[196:199], v[96:99]
	v_mfma_f32_16x16x32_bf16 v[84:87], v[164:167], v[218:221], v[84:87]
	v_mfma_f32_16x16x32_bf16 v[80:83], v[180:183], v[218:221], v[80:83]
	v_mfma_f32_16x16x32_bf16 v[68:71], v[164:167], v[226:229], v[68:71]
	v_mfma_f32_16x16x32_bf16 v[64:67], v[180:183], v[226:229], v[64:67]
	v_mfma_f32_16x16x32_bf16 v[116:119], v[168:171], v[192:195], v[116:119]
	v_mfma_f32_16x16x32_bf16 v[108:111], v[184:187], v[192:195], v[108:111]
	v_mfma_f32_16x16x32_bf16 v[100:103], v[168:171], v[200:203], v[100:103]
	v_mfma_f32_16x16x32_bf16 v[96:99], v[184:187], v[200:203], v[96:99]
	v_mfma_f32_16x16x32_bf16 v[84:87], v[168:171], v[222:225], v[84:87]
	v_mfma_f32_16x16x32_bf16 v[80:83], v[184:187], v[222:225], v[80:83]
	v_mfma_f32_16x16x32_bf16 v[68:71], v[168:171], v[230:233], v[68:71]
	v_mfma_f32_16x16x32_bf16 v[64:67], v[184:187], v[230:233], v[64:67]
	s_setprio 0
	s_barrier
; __device__ __forceinline__ float bflo(unsigned w) { return __uint_as_float(w << 16); }
; __device__ __forceinline__ float bfhi(unsigned w) { return __uint_as_float(w & 0xffff0000u); }
; #define PG8_STAGE(bufoff, gbase, voff) do { _Pragma("unroll") for (int _i = 0; _i < 2; ++_i) \
;         __builtin_amdgcn_global_load_lds((const unsigned*)((const char*)(gbase) + (voff)[_i]), (LAS unsigned*)(lds + (bufoff) + ldsw + _i * 8192), 16, 0, 0); } while (0)
; #define PG8_LDA(dst, b, h) do { _Pragma("unroll") for (int m = 0; m < 4; ++m) _Pragma("unroll") for (int k = 0; k < 2; ++k) dst[m][k] = *(const LAS bf16x8*)(lds + PG8_SA(b, h) + aoff + m * 2048 + k * 1024); } while (0)
; #define PG8_WAIT_V(n) asm volatile("s_waitcnt vmcnt(" #n ")" ::: "memory")
; template <class Epi, class Sched, bool ALIGN_EPI = false, bool SP2 = false>
; __device__ __forceinline__ void gemm_phase(LAS unsigned char* lds, const Gemm g, const Sched& S, const Epi& E) {
;     ...
;             PG8_LDA(At, 1, 1); PG8_STAGE(PG8_SB(1, 0), b3, voffB); PG8_STAGE(PG8_SB(1, 1), b3 + hstep, voffB); PG8_STAGE(PG8_SA(1, 0), a3, voffA);
;             PG8_WAIT_V(8); PG8_WAIT_L(0); PG8_BAR; PG8_MMA(1, 0, At, B0); PG8_MMA(1, 1, At, B1); PG8_BAR; PG8_SCHED;
; template <bool RD32>
; __device__ __forceinline__ void res_rows(const float* __restrict__ xold32, const bf16_t* __restrict__ xoldb, bf16_t* __restrict__ xb, float* __restrict__ ssq, const f32x4 (&acc)[2][2][4][2], int row0, int col0, int slot) {
;     ...
;     auto ld = [&](size_t o, f32x4& a, f32x4& b) { if (RD32) { a = *(const f32x4*)(xold32 + o); b = *(const f32x4*)(xold32 + o + 4); }
;         else { const u32x4 w = *(const u32x4*)(xoldb + o); a = (f32x4){bflo(w.x), bfhi(w.x), bflo(w.y), bfhi(w.y)}; b = (f32x4){bflo(w.z), bfhi(w.z), bflo(w.w), bfhi(w.w)}; } };
; #pragma unroll
;     for (int bj = 0; bj < 2; ++bj) ld((size_t)row0 * D + col0 + bj * HALF, xo[0][bj][0], xo[0][bj][1]);
; #pragma unroll
;     for (int idx = 0; idx < 8; ++idx) {
;         const int ai = idx >> 2, m = idx & 3; const int r = row0 + ai * HALF + m * 16; const size_t off = (size_t)r * D + col0;
;         if (idx < 7) { const int ai2 = (idx + 1) >> 2, m2 = (idx + 1) & 3; const size_t off2 = (size_t)(row0 + ai2 * HALF + m2 * 16) * D + col0;
; #pragma unroll
;             for (int bj = 0; bj < 2; ++bj) ld(off2 + bj * HALF, xo[(idx + 1) & 1][bj][0], xo[(idx + 1) & 1][bj][1]); }
	s_add_i32 s14, s16, s6
	v_lshl_add_u64 v[172:173], v[172:173], 0, s[30:31]
	s_mov_b32 m0, s14
	ds_read_b128 v[188:191], v178 offset:49152
	ds_read_b128 v[192:195], v178 offset:50176
	ds_read_b128 v[196:199], v178 offset:51200
	ds_read_b128 v[200:203], v178 offset:52224
	ds_read_b128 v[218:221], v178 offset:53248
	ds_read_b128 v[222:225], v178 offset:54272
	ds_read_b128 v[226:229], v178 offset:55296
	ds_read_b128 v[230:233], v178 offset:56320
	global_load_lds_dwordx4 v[172:173], off
	s_add_i32 m0, s14, 0x2000
	s_add_u32 s14, s46, 0x100080
	v_lshl_add_u64 v[172:173], v[204:205], 0, s[30:31]
	s_addc_u32 s15, s47, 0
	s_add_i32 s16, s17, s6
	global_load_lds_dwordx4 v[172:173], off
	v_lshl_add_u64 v[172:173], s[14:15], 0, v[152:153]
	s_mov_b32 m0, s16
	s_nop 0
	global_load_lds_dwordx4 v[172:173], off
	v_lshl_add_u64 v[172:173], s[14:15], 0, v[144:145]
	s_add_i32 m0, s16, 0x2000
	s_nop 0
	global_load_lds_dwordx4 v[172:173], off
	v_lshl_add_u64 v[172:173], v[234:235], 0, s[30:31]
	s_mov_b32 m0, s12
	s_nop 0
	global_load_lds_dwordx4 v[172:173], off
	v_lshl_add_u64 v[172:173], v[236:237], 0, s[30:31]
	s_mov_b32 m0, s13
	s_nop 0
	global_load_lds_dwordx4 v[172:173], off
	s_waitcnt vmcnt(8)
	s_waitcnt lgkmcnt(0)
	s_barrier
	s_setprio 1
	s_waitcnt lgkmcnt(0)
	v_mfma_f32_16x16x32_bf16 v[60:63], v[128:131], v[188:191], v[60:63]
	v_mfma_f32_16x16x32_bf16 v[56:59], v[136:139], v[188:191], v[56:59]
	v_mfma_f32_16x16x32_bf16 v[44:47], v[128:131], v[196:199], v[44:47]
	v_mfma_f32_16x16x32_bf16 v[40:43], v[136:139], v[196:199], v[40:43]
	v_mfma_f32_16x16x32_bf16 v[28:31], v[128:131], v[218:221], v[28:31]
	v_mfma_f32_16x16x32_bf16 v[24:27], v[136:139], v[218:221], v[24:27]
	v_mfma_f32_16x16x32_bf16 v[12:15], v[128:131], v[226:229], v[12:15]
	v_mfma_f32_16x16x32_bf16 v[8:11], v[136:139], v[226:229], v[8:11]
	v_mfma_f32_16x16x32_bf16 v[60:63], v[132:135], v[192:195], v[60:63]
	v_mfma_f32_16x16x32_bf16 v[56:59], v[140:143], v[192:195], v[56:59]
	v_mfma_f32_16x16x32_bf16 v[44:47], v[132:135], v[200:203], v[44:47]
	v_mfma_f32_16x16x32_bf16 v[40:43], v[140:143], v[200:203], v[40:43]
	v_mfma_f32_16x16x32_bf16 v[28:31], v[132:135], v[222:225], v[28:31]
	v_mfma_f32_16x16x32_bf16 v[24:27], v[140:143], v[222:225], v[24:27]
	v_mfma_f32_16x16x32_bf16 v[12:15], v[132:135], v[230:233], v[12:15]
	v_mfma_f32_16x16x32_bf16 v[8:11], v[140:143], v[230:233], v[8:11]
	s_setprio 0
	s_setprio 1
	v_mfma_f32_16x16x32_bf16 v[52:55], v[164:167], v[188:191], v[52:55]
	v_mfma_f32_16x16x32_bf16 v[48:51], v[180:183], v[188:191], v[48:51]
	v_mfma_f32_16x16x32_bf16 v[36:39], v[164:167], v[196:199], v[36:39]
	v_mfma_f32_16x16x32_bf16 v[32:35], v[180:183], v[196:199], v[32:35]
	v_mfma_f32_16x16x32_bf16 v[20:23], v[164:167], v[218:221], v[20:23]
	v_mfma_f32_16x16x32_bf16 v[16:19], v[180:183], v[218:221], v[16:19]
	v_mfma_f32_16x16x32_bf16 v[4:7], v[164:167], v[226:229], v[4:7]
	v_mfma_f32_16x16x32_bf16 v[0:3], v[180:183], v[226:229], v[0:3]
	v_mfma_f32_16x16x32_bf16 v[52:55], v[168:171], v[192:195], v[52:55]
	v_mfma_f32_16x16x32_bf16 v[48:51], v[184:187], v[192:195], v[48:51]
	v_mfma_f32_16x16x32_bf16 v[36:39], v[168:171], v[200:203], v[36:39]
	v_mfma_f32_16x16x32_bf16 v[32:35], v[184:187], v[200:203], v[32:35]
	v_mfma_f32_16x16x32_bf16 v[20:23], v[168:171], v[222:225], v[20:23]
	v_mfma_f32_16x16x32_bf16 v[16:19], v[184:187], v[222:225], v[16:19]
	v_mfma_f32_16x16x32_bf16 v[4:7], v[168:171], v[230:233], v[4:7]
	v_mfma_f32_16x16x32_bf16 v[0:3], v[184:187], v[230:233], v[0:3]
	s_setprio 0
	s_barrier
	s_add_i32 s71, s71, 2
	s_add_u32 s42, s42, 0x100
	s_addc_u32 s43, s43, 0
	s_add_u32 s64, s64, 0x100
	s_addc_u32 s65, s65, 0
	s_cmp_gt_u32 s71, 61
	s_cbranch_scc0 .LBB0_612
	s_and_b64 vcc, exec, s[26:27]
	s_cbranch_vccz .LBB0_615
	s_barrier
.LBB0_615:
	s_mov_b32 s101, 1
	v_lshl_add_u32 v164, s51, 8, v174
	v_lshl_or_b32 v128, s50, 8, v176
	v_ashrrev_i32_e32 v165, 31, v164
	v_ashrrev_i32_e32 v129, 31, v128
	v_lshlrev_b64 v[166:167], 11, v[164:165]
	v_lshl_add_u64 v[130:131], s[58:59], 0, v[166:167]
	v_lshlrev_b64 v[128:129], 1, v[128:129]
	v_lshl_add_u64 v[130:131], v[130:131], 0, v[128:129]
	global_load_dwordx4 v[136:139], v[130:131], off
	global_load_dwordx4 v[140:143], v[130:131], off offset:256
	v_or_b32_e32 v130, 16, v164
	v_ashrrev_i32_e32 v131, 31, v130
	v_lshl_add_u64 v[168:169], s[58:59], 0, v[128:129]
	v_lshlrev_b64 v[128:129], 11, v[130:131]
	v_lshl_add_u64 v[170:171], v[168:169], 0, v[128:129]
	global_load_dwordx4 v[128:131], v[170:171], off
	global_load_dwordx4 v[132:135], v[170:171], off offset:256
	v_and_b32_e32 v172, 64, v209
	v_xor_b32_e32 v173, 16, v209
	v_add_u32_e32 v194, 64, v172
	v_or_b32_e32 v172, 32, v164
	v_or_b32_e32 v182, 48, v164
	v_cmp_lt_i32_e32 vcc, v173, v194
	v_ashrrev_i32_e32 v183, 31, v182
	v_lshlrev_b64 v[182:183], 11, v[182:183]
	v_cndmask_b32_e32 v180, v209, v173, vcc
	v_ashrrev_i32_e32 v173, 31, v172
	v_lshlrev_b64 v[172:173], 11, v[172:173]
	v_lshl_add_u64 v[166:167], v[168:169], 0, v[166:167]
	v_lshl_add_u64 v[172:173], v[168:169], 0, v[172:173]
	v_lshl_add_u64 v[168:169], v[168:169], 0, v[182:183]
	v_lshlrev_b32_e32 v180, 2, v180
	s_mov_b32 s14, 0x40000
	v_xor_b32_e32 v181, 32, v209
	s_lshl_b32 s29, s50, 2
	v_or_b32_e32 v179, s29, v177
	s_waitcnt vmcnt(0)
; __device__ __forceinline__ unsigned cvt_pk_bf16(float lo, float hi) { unsigned r; asm volatile("v_cvt_pk_bf16_f32 %0, %1, %2" : "=v"(r) : "v"(lo), "v"(hi)); return r; }
; template <bool RD32>
; __device__ __forceinline__ void res_rows(const float* __restrict__ xold32, const bf16_t* __restrict__ xoldb, bf16_t* __restrict__ xb, float* __restrict__ ssq, const f32x4 (&acc)[2][2][4][2], int row0, int col0, int slot) {
;     ...
;     for (int idx = 0; idx < 8; ++idx) {
;         const int ai = idx >> 2, m = idx & 3; const int r = row0 + ai * HALF + m * 16; const size_t off = (size_t)r * D + col0;
;         if (idx < 7) { const int ai2 = (idx + 1) >> 2, m2 = (idx + 1) & 3; const size_t off2 = (size_t)(row0 + ai2 * HALF + m2 * 16) * D + col0;
; #pragma unroll
;             for (int bj = 0; bj < 2; ++bj) ld(off2 + bj * HALF, xo[(idx + 1) & 1][bj][0], xo[(idx + 1) & 1][bj][1]); }
;         float ss = 0.f;
; #pragma unroll
;         for (int bj = 0; bj < 2; ++bj) { const f32x4 x0 = xo[idx & 1][bj][0] + acc[ai][bj][m][0], x1 = xo[idx & 1][bj][1] + acc[ai][bj][m][1];
;             u32x4 w; w.x = cvt_pk_bf16(x0[0], x0[1]); w.y = cvt_pk_bf16(x0[2], x0[3]); w.z = cvt_pk_bf16(x1[0], x1[1]); w.w = cvt_pk_bf16(x1[2], x1[3]);
;             *(u32x4*)(xb + off + bj * HALF) = w;
;             ss += ((x0[0] * x0[0] + x0[1] * x0[1]) + (x0[2] * x0[2] + x0[3] * x0[3])) + ((x1[0] * x1[0] + x1[1] * x1[1]) + (x1[2] * x1[2] + x1[3] * x1[3])); }
;         ss += __shfl_xor(ss, 16); ss += __shfl_xor(ss, 32);
;         ssv[idx] = ss;
;     }
	v_lshlrev_b32_e32 v182, 16, v136
	v_and_b32_e32 v183, 0xffff0000, v136
	v_lshlrev_b32_e32 v136, 16, v137
	v_and_b32_e32 v137, 0xffff0000, v137
	v_lshlrev_b32_e32 v184, 16, v138
	v_and_b32_e32 v185, 0xffff0000, v138
	v_lshlrev_b32_e32 v138, 16, v139
	v_and_b32_e32 v139, 0xffff0000, v139
	v_lshlrev_b32_e32 v188, 16, v142
	v_and_b32_e32 v189, 0xffff0000, v142
	v_lshlrev_b32_e32 v142, 16, v143
	v_and_b32_e32 v143, 0xffff0000, v143
	v_lshlrev_b32_e32 v186, 16, v140
	v_and_b32_e32 v187, 0xffff0000, v140
	v_lshlrev_b32_e32 v140, 16, v141
	v_and_b32_e32 v141, 0xffff0000, v141
	v_pk_add_f32 v[126:127], v[126:127], v[136:137]
	v_pk_add_f32 v[124:125], v[124:125], v[182:183]
	v_pk_add_f32 v[136:137], v[122:123], v[138:139]
	v_pk_add_f32 v[138:139], v[120:121], v[184:185]
	v_pk_add_f32 v[142:143], v[110:111], v[142:143]
	v_pk_add_f32 v[184:185], v[108:109], v[188:189]
	v_cvt_pk_bf16_f32 v108, v124, v125
	v_cvt_pk_bf16_f32 v109, v126, v127
	v_cvt_pk_bf16_f32 v110, v138, v139
	v_cvt_pk_bf16_f32 v111, v136, v137
	v_pk_add_f32 v[140:141], v[118:119], v[140:141]
	v_pk_add_f32 v[182:183], v[116:117], v[186:187]
	global_store_dwordx4 v[166:167], v[108:111], off
	v_lshlrev_b32_e32 v190, 16, v128
	v_and_b32_e32 v191, 0xffff0000, v128
	v_cvt_pk_bf16_f32 v108, v182, v183
	v_cvt_pk_bf16_f32 v109, v140, v141
	v_cvt_pk_bf16_f32 v110, v184, v185
	v_cvt_pk_bf16_f32 v111, v142, v143
	global_load_dwordx4 v[116:119], v[172:173], off
	global_load_dwordx4 v[120:123], v[172:173], off offset:256
	v_lshlrev_b32_e32 v128, 16, v129
	v_and_b32_e32 v129, 0xffff0000, v129
	v_lshlrev_b32_e32 v186, 16, v130
	v_and_b32_e32 v187, 0xffff0000, v130
	v_lshlrev_b32_e32 v130, 16, v131
	v_and_b32_e32 v131, 0xffff0000, v131
	v_lshlrev_b32_e32 v188, 16, v132
	v_and_b32_e32 v189, 0xffff0000, v132
	v_lshlrev_b32_e32 v192, 16, v134
	v_and_b32_e32 v193, 0xffff0000, v134
	v_lshlrev_b32_e32 v134, 16, v135
	v_and_b32_e32 v135, 0xffff0000, v135
	v_lshlrev_b32_e32 v132, 16, v133
	v_and_b32_e32 v133, 0xffff0000, v133
	v_pk_add_f32 v[114:115], v[114:115], v[128:129]
	v_pk_add_f32 v[112:113], v[112:113], v[190:191]
	v_pk_add_f32 v[128:129], v[106:107], v[130:131]
	v_pk_add_f32 v[130:131], v[104:105], v[186:187]
	v_pk_add_f32 v[186:187], v[100:101], v[188:189]
	v_pk_add_f32 v[134:135], v[98:99], v[134:135]
	v_pk_add_f32 v[188:189], v[96:97], v[192:193]
	global_store_dwordx4 v[166:167], v[108:111], off offset:256
	v_cvt_pk_bf16_f32 v96, v112, v113
	v_cvt_pk_bf16_f32 v97, v114, v115
	v_cvt_pk_bf16_f32 v98, v130, v131
	v_cvt_pk_bf16_f32 v99, v128, v129
	v_pk_add_f32 v[132:133], v[102:103], v[132:133]
	global_store_dwordx4 v[170:171], v[96:99], off
	v_mul_f32_e32 v125, v125, v125
	v_mul_f32_e32 v127, v127, v127
	v_cvt_pk_bf16_f32 v96, v186, v187
	v_cvt_pk_bf16_f32 v97, v132, v133
	v_cvt_pk_bf16_f32 v98, v188, v189
	v_cvt_pk_bf16_f32 v99, v134, v135
	global_load_dwordx4 v[100:103], v[168:169], off
	global_load_dwordx4 v[104:107], v[168:169], off offset:256
	v_mul_f32_e32 v139, v139, v139
	v_mul_f32_e32 v137, v137, v137
	v_mul_f32_e32 v183, v183, v183
	v_mul_f32_e32 v141, v141, v141
	v_mul_f32_e32 v185, v185, v185
	v_mul_f32_e32 v143, v143, v143
	v_fmac_f32_e32 v125, v124, v124
	v_fmac_f32_e32 v127, v126, v126
	v_fmac_f32_e32 v139, v138, v138
	v_fmac_f32_e32 v137, v136, v136
	v_fmac_f32_e32 v183, v182, v182
	v_fmac_f32_e32 v141, v140, v140
	v_fmac_f32_e32 v185, v184, v184
	v_fmac_f32_e32 v143, v142, v142
	v_add_f32_e32 v108, v125, v127
	v_add_f32_e32 v109, v139, v137
	v_add_f32_e32 v110, v183, v141
	v_add_f32_e32 v111, v185, v143
	v_add_f32_e32 v108, v108, v109
	v_add_f32_e32 v109, v110, v111
	v_mul_f32_e32 v190, v113, v113
	v_mul_f32_e32 v191, v115, v115
	v_mul_f32_e32 v192, v131, v131
	v_mul_f32_e32 v193, v129, v129
	v_add_f32_e32 v108, v108, v109
	v_fmac_f32_e32 v190, v112, v112
	v_fmac_f32_e32 v191, v114, v114
	v_fmac_f32_e32 v192, v130, v130
	v_fmac_f32_e32 v193, v128, v128
	ds_bpermute_b32 v109, v180, v108
	v_add_f32_e32 v112, v190, v191
	v_add_f32_e32 v110, v192, v193
	v_add_f32_e32 v127, v112, v110
	v_mul_f32_e32 v195, v187, v187
	v_mul_f32_e32 v196, v133, v133
	v_mul_f32_e32 v197, v189, v189
	v_fmac_f32_e32 v195, v186, v186
	v_fmac_f32_e32 v196, v132, v132
	v_fmac_f32_e32 v197, v188, v188
	v_add_f32_e32 v126, v195, v196
	global_store_dwordx4 v[170:171], v[96:99], off offset:256
	s_waitcnt vmcnt(6)
	v_lshlrev_b32_e32 v110, 16, v118
	v_and_b32_e32 v111, 0xffff0000, v118
	v_lshlrev_b32_e32 v112, 16, v119
	v_and_b32_e32 v113, 0xffff0000, v119
	s_waitcnt vmcnt(5)
	v_lshlrev_b32_e32 v118, 16, v122
	v_and_b32_e32 v119, 0xffff0000, v122
	v_pk_add_f32 v[118:119], v[80:81], v[118:119]
	v_mul_f32_e32 v80, v135, v135
	v_fmac_f32_e32 v80, v134, v134
	s_waitcnt lgkmcnt(0)
	v_add_f32_e32 v96, v108, v109
	v_lshlrev_b32_e32 v98, 16, v116
	v_and_b32_e32 v99, 0xffff0000, v116
	v_lshlrev_b32_e32 v108, 16, v117
	v_and_b32_e32 v109, 0xffff0000, v117
	v_lshlrev_b32_e32 v114, 16, v120
	v_and_b32_e32 v115, 0xffff0000, v120
	v_lshlrev_b32_e32 v116, 16, v121
	v_and_b32_e32 v117, 0xffff0000, v121
	v_lshlrev_b32_e32 v120, 16, v123
	v_and_b32_e32 v121, 0xffff0000, v123
	v_add_f32_e32 v80, v197, v80
	v_pk_add_f32 v[120:121], v[82:83], v[120:121]
	v_add_co_u32_e32 v82, vcc, s14, v166
	v_add_f32_e32 v80, v126, v80
	s_mov_b64 s[14:15], 0x40000
	v_pk_add_f32 v[122:123], v[94:95], v[108:109]
	v_pk_add_f32 v[98:99], v[92:93], v[98:99]
	v_pk_add_f32 v[90:91], v[90:91], v[112:113]
	v_pk_add_f32 v[88:89], v[88:89], v[110:111]
	v_cvt_pk_bf16_f32 v92, v98, v99
	v_cvt_pk_bf16_f32 v93, v122, v123
	v_pk_add_f32 v[124:125], v[84:85], v[114:115]
	v_cvt_pk_bf16_f32 v94, v88, v89
	v_cvt_pk_bf16_f32 v95, v90, v91
	v_addc_co_u32_e32 v83, vcc, 0, v167, vcc
	v_add_f32_e32 v84, v127, v80
	v_lshl_add_u64 v[80:81], v[166:167], 0, s[14:15]
	global_store_dwordx4 v[172:173], v[92:95], off
	v_pk_add_f32 v[116:117], v[86:87], v[116:117]
	v_mul_f32_e32 v97, v99, v99
	v_cvt_pk_bf16_f32 v92, v124, v125
	v_cvt_pk_bf16_f32 v93, v116, v117
	v_cvt_pk_bf16_f32 v94, v118, v119
	v_cvt_pk_bf16_f32 v95, v120, v121
	global_load_dwordx4 v[108:111], v[82:83], off
	global_load_dwordx4 v[112:115], v[80:81], off offset:256
	s_waitcnt vmcnt(4)
; __device__ __forceinline__ unsigned cvt_pk_bf16(float lo, float hi) { unsigned r; asm volatile("v_cvt_pk_bf16_f32 %0, %1, %2" : "=v"(r) : "v"(lo), "v"(hi)); return r; }
; template <bool RD32>
; __device__ __forceinline__ void res_rows(const float* __restrict__ xold32, const bf16_t* __restrict__ xoldb, bf16_t* __restrict__ xb, float* __restrict__ ssq, const f32x4 (&acc)[2][2][4][2], int row0, int col0, int slot) {
;     ...
;     for (int idx = 0; idx < 8; ++idx) {
;         const int ai = idx >> 2, m = idx & 3; const int r = row0 + ai * HALF + m * 16; const size_t off = (size_t)r * D + col0;
;         if (idx < 7) { const int ai2 = (idx + 1) >> 2, m2 = (idx + 1) & 3; const size_t off2 = (size_t)(row0 + ai2 * HALF + m2 * 16) * D + col0;
; #pragma unroll
;             for (int bj = 0; bj < 2; ++bj) ld(off2 + bj * HALF, xo[(idx + 1) & 1][bj][0], xo[(idx + 1) & 1][bj][1]); }
;         float ss = 0.f;
; #pragma unroll
;         for (int bj = 0; bj < 2; ++bj) { const f32x4 x0 = xo[idx & 1][bj][0] + acc[ai][bj][m][0], x1 = xo[idx & 1][bj][1] + acc[ai][bj][m][1];
;             u32x4 w; w.x = cvt_pk_bf16(x0[0], x0[1]); w.y = cvt_pk_bf16(x0[2], x0[3]); w.z = cvt_pk_bf16(x1[0], x1[1]); w.w = cvt_pk_bf16(x1[2], x1[3]);
;             *(u32x4*)(xb + off + bj * HALF) = w;
;             ss += ((x0[0] * x0[0] + x0[1] * x0[1]) + (x0[2] * x0[2] + x0[3] * x0[3])) + ((x1[0] * x1[0] + x1[1] * x1[1]) + (x1[2] * x1[2] + x1[3] * x1[3])); }
;         ss += __shfl_xor(ss, 16); ss += __shfl_xor(ss, 32);
;         ssv[idx] = ss;
;     }
	v_lshlrev_b32_e32 v132, 16, v106
	v_and_b32_e32 v133, 0xffff0000, v106
	v_fmac_f32_e32 v97, v98, v98
	v_mul_f32_e32 v98, v123, v123
	v_fmac_f32_e32 v98, v122, v122
	v_mul_f32_e32 v89, v89, v89
	v_pk_add_f32 v[122:123], v[64:65], v[132:133]
	v_mul_f32_e32 v64, v91, v91
	v_cmp_lt_i32_e32 vcc, v181, v194
	v_lshlrev_b32_e32 v106, 16, v107
	v_and_b32_e32 v107, 0xffff0000, v107
	s_mov_b32 s14, 0x48000
	v_fmac_f32_e32 v89, v88, v88
	v_fmac_f32_e32 v64, v90, v90
	v_cndmask_b32_e32 v85, v209, v181, vcc
	v_lshlrev_b32_e32 v126, 16, v100
	v_and_b32_e32 v127, 0xffff0000, v100
	v_lshlrev_b32_e32 v100, 16, v101
	v_and_b32_e32 v101, 0xffff0000, v101
	v_lshlrev_b32_e32 v128, 16, v102
	v_and_b32_e32 v129, 0xffff0000, v102
	v_lshlrev_b32_e32 v102, 16, v103
	v_and_b32_e32 v103, 0xffff0000, v103
	v_add_f32_e32 v97, v97, v98
	v_pk_add_f32 v[106:107], v[66:67], v[106:107]
	v_add_co_u32_e32 v66, vcc, s14, v166
	v_add_f32_e32 v64, v89, v64
	s_mov_b64 s[14:15], 0x48000
	v_lshlrev_b32_e32 v130, 16, v104
	v_and_b32_e32 v131, 0xffff0000, v104
	v_lshlrev_b32_e32 v104, 16, v105
	v_and_b32_e32 v105, 0xffff0000, v105
	global_store_dwordx4 v[172:173], v[92:95], off offset:256
	v_pk_add_f32 v[98:99], v[74:75], v[102:103]
	v_addc_co_u32_e32 v67, vcc, 0, v167, vcc
	v_pk_add_f32 v[92:93], v[78:79], v[100:101]
	v_pk_add_f32 v[94:95], v[76:77], v[126:127]
	v_pk_add_f32 v[100:101], v[72:73], v[128:129]
	v_cvt_pk_bf16_f32 v72, v94, v95
	v_cvt_pk_bf16_f32 v73, v92, v93
	v_add_f32_e32 v88, v97, v64
	v_cvt_pk_bf16_f32 v74, v100, v101
	v_cvt_pk_bf16_f32 v75, v98, v99
	v_lshl_add_u64 v[64:65], v[166:167], 0, s[14:15]
	global_store_dwordx4 v[168:169], v[72:75], off
	v_pk_add_f32 v[102:103], v[70:71], v[104:105]
	v_pk_add_f32 v[104:105], v[68:69], v[130:131]
	v_mul_f32_e32 v89, v125, v125
	v_cvt_pk_bf16_f32 v68, v104, v105
	v_cvt_pk_bf16_f32 v69, v102, v103
	v_cvt_pk_bf16_f32 v70, v122, v123
	v_cvt_pk_bf16_f32 v71, v106, v107
	global_load_dwordx4 v[72:75], v[66:67], off
	global_load_dwordx4 v[76:79], v[64:65], off offset:256
	v_mul_f32_e32 v90, v117, v117
	v_fmac_f32_e32 v89, v124, v124
	v_fmac_f32_e32 v90, v116, v116
	v_add_f32_e32 v89, v89, v90
	v_mul_f32_e32 v90, v119, v119
	v_mul_f32_e32 v91, v121, v121
	v_mul_f32_e32 v95, v95, v95
	v_mul_f32_e32 v93, v93, v93
	v_fmac_f32_e32 v90, v118, v118
	v_fmac_f32_e32 v91, v120, v120
	v_fmac_f32_e32 v95, v94, v94
	v_fmac_f32_e32 v93, v92, v92
	v_add_f32_e32 v90, v90, v91
	v_add_f32_e32 v92, v95, v93
	v_mul_f32_e32 v93, v101, v101
	v_mul_f32_e32 v94, v99, v99
	v_add_f32_e32 v89, v89, v90
	v_fmac_f32_e32 v93, v100, v100
	v_fmac_f32_e32 v94, v98, v98
	global_store_dwordx4 v[168:169], v[68:71], off offset:256
	s_mov_b32 s14, 0x50000
	v_add_f32_e32 v97, v88, v89
	v_mul_f32_e32 v68, v105, v105
	s_waitcnt vmcnt(5)
	v_lshlrev_b32_e32 v118, 16, v114
	v_and_b32_e32 v119, 0xffff0000, v114
	v_lshlrev_b32_e32 v114, 16, v115
	v_and_b32_e32 v115, 0xffff0000, v115
	v_mul_f32_e32 v69, v103, v103
	v_lshlrev_b32_e32 v88, 16, v108
	v_and_b32_e32 v89, 0xffff0000, v108
	v_lshlrev_b32_e32 v90, 16, v109
	v_and_b32_e32 v91, 0xffff0000, v109
	v_lshlrev_b32_e32 v108, 16, v110
	v_and_b32_e32 v109, 0xffff0000, v110
	v_lshlrev_b32_e32 v110, 16, v111
	v_and_b32_e32 v111, 0xffff0000, v111
	v_add_f32_e32 v93, v93, v94
	v_fmac_f32_e32 v68, v104, v104
	v_fmac_f32_e32 v69, v102, v102
	v_pk_add_f32 v[94:95], v[50:51], v[114:115]
	v_add_co_u32_e32 v50, vcc, s14, v166
	v_lshlrev_b32_e32 v116, 16, v112
	v_and_b32_e32 v117, 0xffff0000, v112
	v_lshlrev_b32_e32 v112, 16, v113
	v_and_b32_e32 v113, 0xffff0000, v113
	v_add_f32_e32 v124, v68, v69
	v_pk_add_f32 v[62:63], v[62:63], v[90:91]
	v_pk_add_f32 v[60:61], v[60:61], v[88:89]
	v_pk_add_f32 v[58:59], v[58:59], v[110:111]
	v_pk_add_f32 v[56:57], v[56:57], v[108:109]
	v_cvt_pk_bf16_f32 v68, v60, v61
	v_cvt_pk_bf16_f32 v69, v62, v63
	v_addc_co_u32_e32 v51, vcc, 0, v167, vcc
	v_cvt_pk_bf16_f32 v70, v56, v57
	v_cvt_pk_bf16_f32 v71, v58, v59
	v_add_f32_e32 v121, v92, v93
	global_store_dwordx4 v[82:83], v[68:71], off
	v_pk_add_f32 v[82:83], v[54:55], v[112:113]
	v_pk_add_f32 v[92:93], v[52:53], v[116:117]
	v_pk_add_f32 v[98:99], v[48:49], v[118:119]
	v_cvt_pk_bf16_f32 v52, v92, v93
	v_cvt_pk_bf16_f32 v53, v82, v83
	s_mov_b64 s[14:15], 0x50000
	v_cvt_pk_bf16_f32 v54, v98, v99
	v_cvt_pk_bf16_f32 v55, v94, v95
	global_load_dwordx4 v[68:71], v[50:51], off
	v_lshl_add_u64 v[48:49], v[166:167], 0, s[14:15]
	global_load_dwordx4 v[88:91], v[48:49], off offset:256
	s_mov_b32 s14, 0x58000
	v_mul_f32_e32 v108, v107, v107
	v_fmac_f32_e32 v108, v106, v106
	global_store_dwordx4 v[80:81], v[52:55], off offset:256
	v_mul_f32_e32 v123, v123, v123
	v_fmac_f32_e32 v123, v122, v122
	ds_bpermute_b32 v86, v180, v84
	ds_bpermute_b32 v120, v180, v97
	s_waitcnt vmcnt(6)
	v_lshlrev_b32_e32 v100, 16, v72
	s_waitcnt vmcnt(5)
; __device__ __forceinline__ unsigned cvt_pk_bf16(float lo, float hi) { unsigned r; asm volatile("v_cvt_pk_bf16_f32 %0, %1, %2" : "=v"(r) : "v"(lo), "v"(hi)); return r; }
; template <bool RD32>
; __device__ __forceinline__ void res_rows(const float* __restrict__ xold32, const bf16_t* __restrict__ xoldb, bf16_t* __restrict__ xb, float* __restrict__ ssq, const f32x4 (&acc)[2][2][4][2], int row0, int col0, int slot) {
;     ...
;     for (int idx = 0; idx < 8; ++idx) {
;         const int ai = idx >> 2, m = idx & 3; const int r = row0 + ai * HALF + m * 16; const size_t off = (size_t)r * D + col0;
;         if (idx < 7) { const int ai2 = (idx + 1) >> 2, m2 = (idx + 1) & 3; const size_t off2 = (size_t)(row0 + ai2 * HALF + m2 * 16) * D + col0;
; #pragma unroll
;             for (int bj = 0; bj < 2; ++bj) ld(off2 + bj * HALF, xo[(idx + 1) & 1][bj][0], xo[(idx + 1) & 1][bj][1]); }
;         float ss = 0.f;
; #pragma unroll
;         for (int bj = 0; bj < 2; ++bj) { const f32x4 x0 = xo[idx & 1][bj][0] + acc[ai][bj][m][0], x1 = xo[idx & 1][bj][1] + acc[ai][bj][m][1];
;             u32x4 w; w.x = cvt_pk_bf16(x0[0], x0[1]); w.y = cvt_pk_bf16(x0[2], x0[3]); w.z = cvt_pk_bf16(x1[0], x1[1]); w.w = cvt_pk_bf16(x1[2], x1[3]);
;             *(u32x4*)(xb + off + bj * HALF) = w;
;             ss += ((x0[0] * x0[0] + x0[1] * x0[1]) + (x0[2] * x0[2] + x0[3] * x0[3])) + ((x1[0] * x1[0] + x1[1] * x1[1]) + (x1[2] * x1[2] + x1[3] * x1[3])); }
;         ss += __shfl_xor(ss, 16); ss += __shfl_xor(ss, 32);
;         ssv[idx] = ss;
;     }
	v_lshlrev_b32_e32 v104, 16, v76
	v_and_b32_e32 v105, 0xffff0000, v76
	v_and_b32_e32 v101, 0xffff0000, v72
	v_lshlrev_b32_e32 v72, 16, v73
	v_and_b32_e32 v73, 0xffff0000, v73
	v_lshlrev_b32_e32 v102, 16, v74
	v_and_b32_e32 v103, 0xffff0000, v74
	v_lshlrev_b32_e32 v74, 16, v75
	v_and_b32_e32 v75, 0xffff0000, v75
	v_pk_add_f32 v[36:37], v[36:37], v[104:105]
	v_add_co_u32_e32 v104, vcc, s14, v166
	v_lshlrev_b32_e32 v76, 16, v77
	v_and_b32_e32 v77, 0xffff0000, v77
	v_lshlrev_b32_e32 v106, 16, v78
	v_and_b32_e32 v107, 0xffff0000, v78
	v_lshlrev_b32_e32 v78, 16, v79
	v_and_b32_e32 v79, 0xffff0000, v79
	v_pk_add_f32 v[46:47], v[46:47], v[72:73]
	v_pk_add_f32 v[80:81], v[44:45], v[100:101]
	v_pk_add_f32 v[100:101], v[42:43], v[74:75]
	v_pk_add_f32 v[102:103], v[40:41], v[102:103]
	v_cvt_pk_bf16_f32 v40, v80, v81
	v_cvt_pk_bf16_f32 v41, v46, v47
	v_addc_co_u32_e32 v105, vcc, 0, v167, vcc
	v_cvt_pk_bf16_f32 v42, v102, v103
	v_cvt_pk_bf16_f32 v43, v100, v101
	global_store_dwordx4 v[66:67], v[40:43], off
	v_pk_add_f32 v[66:67], v[38:39], v[76:77]
	v_pk_add_f32 v[76:77], v[34:35], v[78:79]
	v_pk_add_f32 v[78:79], v[32:33], v[106:107]
	v_cvt_pk_bf16_f32 v42, v36, v37
	v_cvt_pk_bf16_f32 v43, v66, v67
	v_add_f32_e32 v32, v123, v108
	v_cvt_pk_bf16_f32 v44, v78, v79
	v_cvt_pk_bf16_f32 v45, v76, v77
	global_load_dwordx4 v[52:55], v[104:105], off
	v_add_f32_e32 v32, v124, v32
	s_mov_b64 s[14:15], 0x58000
	v_add_f32_e32 v34, v121, v32
	v_lshl_add_u64 v[32:33], v[166:167], 0, s[14:15]
	global_load_dwordx4 v[72:75], v[32:33], off offset:256
	v_mul_f32_e32 v38, v61, v61
	v_mul_f32_e32 v39, v63, v63
	v_mul_f32_e32 v81, v81, v81
	v_mul_f32_e32 v47, v47, v47
	v_fmac_f32_e32 v38, v60, v60
	v_fmac_f32_e32 v39, v62, v62
	v_fmac_f32_e32 v81, v80, v80
	v_fmac_f32_e32 v47, v46, v46
	v_add_f32_e32 v38, v38, v39
	v_mul_f32_e32 v39, v57, v57
	v_mul_f32_e32 v40, v59, v59
	v_add_f32_e32 v46, v81, v47
	v_mul_f32_e32 v47, v103, v103
	v_mul_f32_e32 v80, v101, v101
	v_mul_f32_e32 v37, v37, v37
	v_fmac_f32_e32 v39, v56, v56
	v_fmac_f32_e32 v40, v58, v58
	v_fmac_f32_e32 v47, v102, v102
	v_fmac_f32_e32 v80, v100, v100
	v_fmac_f32_e32 v37, v36, v36
	v_mul_f32_e32 v36, v67, v67
	v_add_f32_e32 v47, v47, v80
	v_fmac_f32_e32 v36, v66, v66
	global_store_dwordx4 v[64:65], v[42:45], off offset:256
	v_add_f32_e32 v46, v46, v47
	s_waitcnt vmcnt(6)
	v_lshlrev_b32_e32 v56, 16, v68
	v_and_b32_e32 v57, 0xffff0000, v68
	v_lshlrev_b32_e32 v58, 16, v69
	v_and_b32_e32 v59, 0xffff0000, v69
	v_lshlrev_b32_e32 v60, 16, v70
	v_and_b32_e32 v61, 0xffff0000, v70
	v_lshlrev_b32_e32 v62, 16, v71
	v_and_b32_e32 v63, 0xffff0000, v71
	v_pk_add_f32 v[30:31], v[30:31], v[58:59]
	v_pk_add_f32 v[28:29], v[28:29], v[56:57]
	v_pk_add_f32 v[58:59], v[24:25], v[60:61]
	v_cvt_pk_bf16_f32 v24, v28, v29
	v_cvt_pk_bf16_f32 v25, v30, v31
	v_add_f32_e32 v36, v37, v36
	v_mul_f32_e32 v37, v79, v79
	v_mul_f32_e32 v47, v77, v77
	v_pk_add_f32 v[56:57], v[26:27], v[62:63]
	v_cvt_pk_bf16_f32 v26, v58, v59
	v_fmac_f32_e32 v37, v78, v78
	v_cvt_pk_bf16_f32 v27, v56, v57
	global_store_dwordx4 v[50:51], v[24:27], off
	v_fmac_f32_e32 v47, v76, v76
	v_add_f32_e32 v37, v37, v47
	v_mul_f32_e32 v24, v29, v29
	v_mul_f32_e32 v25, v31, v31
	v_fmac_f32_e32 v24, v28, v28
	v_fmac_f32_e32 v25, v30, v30
	v_add_f32_e32 v24, v24, v25
	v_mul_f32_e32 v25, v59, v59
	v_mul_f32_e32 v26, v57, v57
	v_add_f32_e32 v39, v39, v40
	v_mul_f32_e32 v40, v83, v83
	s_waitcnt vmcnt(6)
	v_lshlrev_b32_e32 v68, 16, v88
	v_and_b32_e32 v69, 0xffff0000, v88
	v_add_f32_e32 v36, v36, v37
	v_fmac_f32_e32 v25, v58, v58
	v_fmac_f32_e32 v26, v56, v56
	v_fmac_f32_e32 v40, v82, v82
	v_lshlrev_b32_e32 v70, 16, v89
	v_and_b32_e32 v71, 0xffff0000, v89
	v_lshlrev_b32_e32 v82, 16, v90
	v_add_f32_e32 v36, v46, v36
	v_and_b32_e32 v83, 0xffff0000, v90
	v_lshlrev_b32_e32 v46, 16, v91
	v_and_b32_e32 v47, 0xffff0000, v91
	v_add_f32_e32 v25, v25, v26
	v_pk_add_f32 v[20:21], v[20:21], v[68:69]
	v_add_f32_e32 v26, v24, v25
	v_pk_add_f32 v[22:23], v[22:23], v[70:71]
	v_pk_add_f32 v[24:25], v[18:19], v[46:47]
	v_pk_add_f32 v[18:19], v[16:17], v[82:83]
	v_mul_f32_e32 v17, v21, v21
	v_cvt_pk_bf16_f32 v16, v20, v21
	v_fmac_f32_e32 v17, v20, v20
	v_mul_f32_e32 v20, v23, v23
	v_fmac_f32_e32 v20, v22, v22
	v_add_f32_e32 v17, v17, v20
	v_mul_f32_e32 v20, v19, v19
	v_mul_f32_e32 v21, v25, v25
	v_fmac_f32_e32 v20, v18, v18
	v_fmac_f32_e32 v21, v24, v24
	v_add_f32_e32 v20, v20, v21
	v_add_f32_e32 v17, v17, v20
	v_add_f32_e32 v20, v26, v17
	ds_bpermute_b32 v21, v180, v20
	s_waitcnt vmcnt(3)
; __device__ __forceinline__ unsigned cvt_pk_bf16(float lo, float hi) { unsigned r; asm volatile("v_cvt_pk_bf16_f32 %0, %1, %2" : "=v"(r) : "v"(lo), "v"(hi)); return r; }
; template <bool RD32>
; __device__ __forceinline__ void res_rows(const float* __restrict__ xold32, const bf16_t* __restrict__ xoldb, bf16_t* __restrict__ xb, float* __restrict__ ssq, const f32x4 (&acc)[2][2][4][2], int row0, int col0, int slot) {
;     ...
;         for (int bj = 0; bj < 2; ++bj) { const f32x4 x0 = xo[idx & 1][bj][0] + acc[ai][bj][m][0], x1 = xo[idx & 1][bj][1] + acc[ai][bj][m][1];
;             u32x4 w; w.x = cvt_pk_bf16(x0[0], x0[1]); w.y = cvt_pk_bf16(x0[2], x0[3]); w.z = cvt_pk_bf16(x1[0], x1[1]); w.w = cvt_pk_bf16(x1[2], x1[3]);
;             *(u32x4*)(xb + off + bj * HALF) = w;
;             ss += ((x0[0] * x0[0] + x0[1] * x0[1]) + (x0[2] * x0[2] + x0[3] * x0[3])) + ((x1[0] * x1[0] + x1[1] * x1[1]) + (x1[2] * x1[2] + x1[3] * x1[3])); }
;         ss += __shfl_xor(ss, 16); ss += __shfl_xor(ss, 32);
;         ssv[idx] = ss;
;     }
;     const int fq = slot >> 6;
; #pragma unroll
;     for (int j = 0; j < 2; ++j) { const float v = fq == 0 ? ssv[j] : fq == 1 ? ssv[2 + j] : fq == 2 ? ssv[4 + j] : ssv[6 + j]; const int idx = 2 * fq + j;
;         ssq[(size_t)(row0 + (idx >> 2) * HALF + (idx & 3) * 16) * 16 + (slot & 15)] = v; }
	v_lshlrev_b32_e32 v42, 16, v52
	v_and_b32_e32 v43, 0xffff0000, v52
	v_lshlrev_b32_e32 v44, 16, v53
	v_and_b32_e32 v45, 0xffff0000, v53
	v_lshlrev_b32_e32 v52, 16, v54
	v_and_b32_e32 v53, 0xffff0000, v54
	v_lshlrev_b32_e32 v54, 16, v55
	v_and_b32_e32 v55, 0xffff0000, v55
	v_cvt_pk_bf16_f32 v17, v22, v23
	v_cvt_pk_bf16_f32 v18, v18, v19
	v_cvt_pk_bf16_f32 v19, v24, v25
	global_store_dwordx4 v[48:49], v[16:19], off offset:256
	v_pk_add_f32 v[14:15], v[14:15], v[44:45]
	v_pk_add_f32 v[12:13], v[12:13], v[42:43]
	s_waitcnt lgkmcnt(0)
	v_add_f32_e32 v16, v20, v21
	v_pk_add_f32 v[20:21], v[8:9], v[52:53]
	v_cvt_pk_bf16_f32 v8, v12, v13
	v_cvt_pk_bf16_f32 v9, v14, v15
	v_pk_add_f32 v[18:19], v[10:11], v[54:55]
	v_cvt_pk_bf16_f32 v10, v20, v21
	s_waitcnt vmcnt(3)
	v_lshlrev_b32_e32 v64, 16, v72
	v_cvt_pk_bf16_f32 v11, v18, v19
	global_store_dwordx4 v[104:105], v[8:11], off
	v_and_b32_e32 v65, 0xffff0000, v72
	v_lshlrev_b32_e32 v66, 16, v73
	v_mul_f32_e32 v8, v13, v13
	v_mul_f32_e32 v9, v15, v15
	v_fmac_f32_e32 v8, v12, v12
	v_fmac_f32_e32 v9, v14, v14
	v_add_f32_e32 v8, v8, v9
	v_mul_f32_e32 v9, v21, v21
	v_mul_f32_e32 v10, v19, v19
	v_fmac_f32_e32 v9, v20, v20
	v_fmac_f32_e32 v10, v18, v18
	v_and_b32_e32 v67, 0xffff0000, v73
	v_lshlrev_b32_e32 v72, 16, v74
	v_and_b32_e32 v73, 0xffff0000, v74
	v_lshlrev_b32_e32 v74, 16, v75
	v_and_b32_e32 v75, 0xffff0000, v75
	v_add_f32_e32 v9, v9, v10
	v_pk_add_f32 v[4:5], v[4:5], v[64:65]
	v_add_f32_e32 v10, v8, v9
	v_pk_add_f32 v[6:7], v[6:7], v[66:67]
	v_pk_add_f32 v[8:9], v[2:3], v[74:75]
	v_pk_add_f32 v[2:3], v[0:1], v[72:73]
	v_mul_f32_e32 v1, v5, v5
	v_add_f32_e32 v38, v38, v39
	v_mul_f32_e32 v39, v93, v93
	v_cvt_pk_bf16_f32 v0, v4, v5
	v_fmac_f32_e32 v1, v4, v4
	v_mul_f32_e32 v4, v7, v7
	v_fmac_f32_e32 v39, v92, v92
	v_fmac_f32_e32 v4, v6, v6
	v_add_f32_e32 v39, v39, v40
	v_mul_f32_e32 v40, v99, v99
	v_mul_f32_e32 v41, v95, v95
	v_add_f32_e32 v1, v1, v4
	v_mul_f32_e32 v4, v3, v3
	v_mul_f32_e32 v5, v9, v9
	v_fmac_f32_e32 v40, v98, v98
	v_fmac_f32_e32 v41, v94, v94
	v_fmac_f32_e32 v4, v2, v2
	v_fmac_f32_e32 v5, v8, v8
	v_add_f32_e32 v40, v40, v41
	v_add_f32_e32 v4, v4, v5
	v_add_f32_e32 v39, v39, v40
	v_add_f32_e32 v1, v1, v4
	v_add_f32_e32 v40, v38, v39
	v_add_f32_e32 v4, v10, v1
	ds_bpermute_b32 v35, v180, v34
	ds_bpermute_b32 v41, v180, v40
	ds_bpermute_b32 v37, v180, v36
	ds_bpermute_b32 v5, v180, v4
	v_cvt_pk_bf16_f32 v1, v6, v7
	v_cvt_pk_bf16_f32 v2, v2, v3
	v_lshlrev_b32_e32 v87, 2, v85
	v_add_f32_e32 v84, v84, v86
	v_add_f32_e32 v38, v97, v120
	s_waitcnt lgkmcnt(3)
	v_add_f32_e32 v34, v34, v35
	s_waitcnt lgkmcnt(2)
	v_add_f32_e32 v40, v40, v41
	s_waitcnt lgkmcnt(1)
	v_add_f32_e32 v36, v36, v37
	v_cvt_pk_bf16_f32 v3, v8, v9
	global_store_dwordx4 v[32:33], v[0:3], off offset:256
	ds_bpermute_b32 v85, v87, v96
	ds_bpermute_b32 v86, v87, v84
	s_waitcnt lgkmcnt(2)
	v_add_f32_e32 v2, v4, v5
	ds_bpermute_b32 v39, v87, v38
	ds_bpermute_b32 v35, v87, v34
	ds_bpermute_b32 v41, v87, v40
	ds_bpermute_b32 v37, v87, v36
	ds_bpermute_b32 v17, v87, v16
	ds_bpermute_b32 v3, v87, v2
	s_and_b32 s14, s29, 12
	s_or_b32 s14, s14, s11
	s_lshl_b32 s14, s14, 2
	v_bitop3_b32 v0, s29, v216, v177 bitop3:0xc8
	s_add_u32 s46, s18, s14
	v_cmp_lt_u32_e32 vcc, 63, v179
	v_add_u32_e32 v0, v164, v0
	s_addc_u32 s47, s19, 0
	s_and_saveexec_b64 s[14:15], vcc
	s_xor_b64 s[48:49], exec, s[14:15]
	s_cbranch_execz .LBB0_626
	v_ashrrev_i32_e32 v4, 6, v179
	v_cmp_lt_i32_e32 vcc, 1, v4
	s_mov_b64 s[42:43], 0
	s_and_saveexec_b64 s[14:15], vcc
	s_xor_b64 s[50:51], exec, s[14:15]
	s_cbranch_execnz .LBB0_631
	s_or_saveexec_b64 s[50:51], s[50:51]
	v_cmp_ne_u32_e32 vcc, 1, v4
	s_xor_b64 exec, exec, s[50:51]
	s_cbranch_execnz .LBB0_634

; __global__ void __launch_bounds__(512, 2) fwd_megakernel(Params p) {
;     extern __shared__ __attribute__((aligned(16))) unsigned char lds[];
	.amdhsa_kernel _Z14fwd_megakernel6Params
		.amdhsa_group_segment_fixed_size 0
		.amdhsa_private_segment_fixed_size 0
		.amdhsa_kernarg_size 400
		.amdhsa_user_sgpr_count 2
		.amdhsa_user_sgpr_dispatch_ptr 0
		.amdhsa_user_sgpr_queue_ptr 0
		.amdhsa_user_sgpr_kernarg_segment_ptr 1
		.amdhsa_user_sgpr_dispatch_id 0
		.amdhsa_user_sgpr_kernarg_preload_length 0
		.amdhsa_user_sgpr_kernarg_preload_offset 0
		.amdhsa_user_sgpr_private_segment_size 0
		.amdhsa_uses_dynamic_stack 0
		.amdhsa_enable_private_segment 0
		.amdhsa_system_sgpr_workgroup_id_x 1
		.amdhsa_system_sgpr_workgroup_id_y 0
		.amdhsa_system_sgpr_workgroup_id_z 0
		.amdhsa_system_sgpr_workgroup_info 0
		.amdhsa_system_vgpr_workitem_id 2
		.amdhsa_next_free_vgpr 249
		.amdhsa_next_free_sgpr 102
		.amdhsa_accum_offset 252
		.amdhsa_reserve_vcc 1
		.amdhsa_float_round_mode_32 0
		.amdhsa_float_round_mode_16_64 0
		.amdhsa_float_denorm_mode_32 3
		.amdhsa_float_denorm_mode_16_64 3
		.amdhsa_dx10_clamp 1
		.amdhsa_ieee_mode 1
		.amdhsa_fp16_overflow 0
		.amdhsa_tg_split 0
		.amdhsa_exception_fp_ieee_invalid_op 0
		.amdhsa_exception_fp_denorm_src 0
		.amdhsa_exception_fp_ieee_div_zero 0
		.amdhsa_exception_fp_ieee_overflow 0
		.amdhsa_exception_fp_ieee_underflow 0
		.amdhsa_exception_fp_ieee_inexact 0
		.amdhsa_exception_int_div_zero 0
	.end_amdhsa_kernel

; __global__ void __launch_bounds__(512, 2) fwd_megakernel(Params p) {
;     extern __shared__ __attribute__((aligned(16))) unsigned char lds[];
amdhsa.kernels:
  - .agpr_count:     0
    .args:
      - .offset:         0
        .size:           144
        .value_kind:     by_value
      - .offset:         144
        .size:           4
        .value_kind:     hidden_block_count_x
      - .offset:         148
        .size:           4
        .value_kind:     hidden_block_count_y
      - .offset:         152
        .size:           4
        .value_kind:     hidden_block_count_z
      - .offset:         156
        .size:           2
        .value_kind:     hidden_group_size_x
      - .offset:         158
        .size:           2
        .value_kind:     hidden_group_size_y
      - .offset:         160
        .size:           2
        .value_kind:     hidden_group_size_z
      - .offset:         162
        .size:           2
        .value_kind:     hidden_remainder_x
      - .offset:         164
        .size:           2
        .value_kind:     hidden_remainder_y
      - .offset:         166
        .size:           2
        .value_kind:     hidden_remainder_z
      - .offset:         184
        .size:           8
        .value_kind:     hidden_global_offset_x
      - .offset:         192
        .size:           8
        .value_kind:     hidden_global_offset_y
      - .offset:         200
        .size:           8
        .value_kind:     hidden_global_offset_z
      - .offset:         208
        .size:           2
        .value_kind:     hidden_grid_dims
      - .offset:         232
        .size:           8
        .value_kind:     hidden_multigrid_sync_arg
      - .offset:         264
        .size:           4
        .value_kind:     hidden_dynamic_lds_size
    .group_segment_fixed_size: 0
    .kernarg_segment_align: 8
    .kernarg_segment_size: 400
    .language:       OpenCL C
    .language_version:
      - 2
      - 0
    .max_flat_workgroup_size: 512
    .name:           _Z14fwd_megakernel6Params
    .private_segment_fixed_size: 0
    .sgpr_count:     108
    .sgpr_spill_count: 188
    .symbol:         _Z14fwd_megakernel6Params.kd
    .uniform_work_group_size: 1
    .uses_dynamic_stack: false
    .vgpr_count:     249
    .vgpr_spill_count: 0
    .wavefront_size: 64
